# nt cache policy on the residual-stream loads of the out/down epilogues (read once, overwritten in place right after)
# baseline (speedup 1.0000x reference)
; __device__ __forceinline__ unsigned pk2(float lo, float hi) { return pg8::cvt_pk_bf16(lo, hi); }
;     __device__ __forceinline__ void operator()(const f32x4 (&acc)[2][2][4][2], const pg8::Unit& u, int wr, int wc, int fr, int fq) const {
;         const int Rt = rowbase + u.pm * 256; const bool islat = Rt < TL; const int mrow = islat ? (Rt >> 13) : 8;
;         const float* gp = gate + (size_t)mrow * MODW; const float* gsp = gs + (size_t)mrow * DM;
;         f32x4 gv[2][2], sv[2][2];
; #pragma unroll
;         for (int bj = 0; bj < 2; ++bj) { const int c = u.pn * 256 + bj * 128 + wc * 32 + 8 * fq;
;             gv[bj][0] = *(const f32x4*)(gp + c); gv[bj][1] = *(const f32x4*)(gp + c + 4); sv[bj][0] = *(const f32x4*)(gsp + c); sv[bj][1] = *(const f32x4*)(gsp + c + 4); }
; #pragma unroll
;         for (int ai = 0; ai < 2; ++ai)
; #pragma unroll
;             for (int m = 0; m < 4; ++m) {
;                 const int R = rowbase + u.pm * 256 + ai * 128 + wr * 64 + m * 16 + fr;
;                 const float* src = islat ? rin_l + (size_t)R * DM : rin_c + (size_t)(R - TL) * DM;
;                 float* dst = islat ? rout_l + (size_t)R * DM : rout_c + (size_t)(R - TL) * DM;
;                 float ss = 0.f;
; #pragma unroll
;                 for (int bj = 0; bj < 2; ++bj) { const int c = u.pn * 256 + bj * 128 + wc * 32 + 8 * fq;
;                     const f32x4 xa = *(const f32x4*)(src + c) + gv[bj][0] * acc[ai][bj][m][0];
;                     const f32x4 xb = *(const f32x4*)(src + c + 4) + gv[bj][1] * acc[ai][bj][m][1];
;                     *(f32x4*)(dst + c) = xa; *(f32x4*)(dst + c + 4) = xb;
;                     ss += (xa[0] * xa[0] + xa[1] * xa[1]) + (xa[2] * xa[2] + xa[3] * xa[3]) + (xb[0] * xb[0] + xb[1] * xb[1]) + (xb[2] * xb[2] + xb[3] * xb[3]);
;                     const f32x4 ya = xa * sv[bj][0], yb = xb * sv[bj][1];
;                     u32x4 w; w.x = pk2(ya[0], ya[1]); w.y = pk2(ya[2], ya[3]); w.z = pk2(yb[0], yb[1]); w.w = pk2(yb[2], yb[3]);
;                     *(u32x4*)(Hn + (size_t)R * DM + c) = w; }
;                 ss += __shfl_xor(ss, 16); ss += __shfl_xor(ss, 32);
;                 if (fq == 0) stat[(size_t)R * 16 + u.pn * 4 + wc] = ss;
;             }
.LBB0_922:
	s_lshl_b32 s24, s24, 2
	s_ashr_i32 s25, s24, 31
	v_cndmask_b32_e64 v202, v194, v190, s[42:43]
	s_and_b64 s[8:9], s[42:43], exec
	v_ashrrev_i32_e32 v203, 31, v202
	s_cselect_b32 s69, s19, s49
	s_cselect_b32 s68, s18, s48
	v_lshlrev_b64 v[202:203], 12, v[202:203]
	v_lshl_add_u64 v[202:203], s[68:69], 0, v[202:203]
	v_lshl_add_u64 v[212:213], v[202:203], 0, v[188:189]
	s_mov_b32 s100, 0xaaaaaaaa
	s_mov_b32 s101, 0xaaaaaaaa
	v_mov_b32_e32 v222, 0x1000
	v_mov_b32_e32 v223, 16
	v_cndmask_b32_e64 v242, v222, v223, s[100:101]
	v_mov_b32_e32 v243, 0
	v_lshl_add_u64 v[226:227], v[212:213], 0, v[242:243]
	global_load_dwordx4 v[214:217], v[226:227], off offset:-4096 nt
	global_load_dwordx4 v[218:221], v[226:227], off nt
	v_lshlrev_b64 v[210:211], 11, v[190:191]
	v_and_b32_e32 v200, 64, v228
	v_xor_b32_e32 v195, 16, v228
	v_add_u32_e32 v201, 64, v200
	v_cmp_lt_i32_e32 vcc, v195, v201
	s_waitcnt vmcnt(0)
	v_cndmask_b32_e64 v222, v218, v214, s[100:101]
	v_cndmask_b32_e64 v223, v219, v215, s[100:101]
	v_cndmask_b32_e64 v224, v220, v216, s[100:101]
	v_cndmask_b32_e64 v225, v221, v217, s[100:101]
	v_mov_b32_dpp v238, v222 quad_perm:[1,0,3,2] row_mask:0xf bank_mask:0xf
	v_mov_b32_dpp v239, v223 quad_perm:[1,0,3,2] row_mask:0xf bank_mask:0xf
	v_mov_b32_dpp v240, v224 quad_perm:[1,0,3,2] row_mask:0xf bank_mask:0xf
	v_mov_b32_dpp v241, v225 quad_perm:[1,0,3,2] row_mask:0xf bank_mask:0xf
	v_cndmask_b32_e64 v206, v214, v238, s[100:101]
	v_cndmask_b32_e64 v202, v238, v218, s[100:101]
	v_cndmask_b32_e64 v207, v215, v239, s[100:101]
	v_cndmask_b32_e64 v203, v239, v219, s[100:101]
	v_cndmask_b32_e64 v208, v216, v240, s[100:101]
	v_cndmask_b32_e64 v204, v240, v220, s[100:101]
	v_cndmask_b32_e64 v209, v217, v241, s[100:101]
	v_cndmask_b32_e64 v205, v241, v221, s[100:101]
	v_pk_fma_f32 v[204:205], v[156:157], v[88:89], v[204:205]
	v_pk_fma_f32 v[160:161], v[160:161], v[96:97], v[208:209]
	v_pk_fma_f32 v[158:159], v[158:159], v[94:95], v[206:207]
	v_mul_f32_e32 v157, v161, v161
	v_mul_f32_e32 v156, v159, v159
	v_pk_fma_f32 v[202:203], v[154:155], v[86:87], v[202:203]
	v_fmac_f32_e32 v156, v158, v158
	v_fmac_f32_e32 v157, v160, v160
	v_add_f32_e32 v156, v156, v157
	v_mul_f32_e32 v157, v203, v203
	v_fmac_f32_e32 v157, v202, v202
	v_add_f32_e32 v156, v156, v157
	v_mul_f32_e32 v157, v205, v205
	v_lshl_add_u64 v[154:155], v[192:193], 0, v[188:189]
	v_fmac_f32_e32 v157, v204, v204
	v_cndmask_b32_e64 v222, v202, v158, s[100:101]
	v_cndmask_b32_e64 v223, v203, v159, s[100:101]
	v_cndmask_b32_e64 v224, v204, v160, s[100:101]
	v_cndmask_b32_e64 v225, v205, v161, s[100:101]
	v_mov_b32_dpp v238, v222 quad_perm:[1,0,3,2] row_mask:0xf bank_mask:0xf
	v_mov_b32_dpp v239, v223 quad_perm:[1,0,3,2] row_mask:0xf bank_mask:0xf
	v_mov_b32_dpp v240, v224 quad_perm:[1,0,3,2] row_mask:0xf bank_mask:0xf
	v_mov_b32_dpp v241, v225 quad_perm:[1,0,3,2] row_mask:0xf bank_mask:0xf
	v_cndmask_b32_e64 v214, v158, v238, s[100:101]
	v_cndmask_b32_e64 v218, v238, v202, s[100:101]
	v_cndmask_b32_e64 v215, v159, v239, s[100:101]
	v_cndmask_b32_e64 v219, v239, v203, s[100:101]
	v_cndmask_b32_e64 v216, v160, v240, s[100:101]
	v_cndmask_b32_e64 v220, v240, v204, s[100:101]
	v_cndmask_b32_e64 v217, v161, v241, s[100:101]
	v_cndmask_b32_e64 v221, v241, v205, s[100:101]
	v_lshl_add_u64 v[226:227], v[154:155], 0, v[242:243]
	global_store_dwordx4 v[226:227], v[214:217], off offset:-4096
	global_store_dwordx4 v[226:227], v[218:221], off
	v_add_f32_e32 v194, v157, v156
	v_pk_mul_f32 v[160:161], v[92:93], v[160:161]
	v_pk_mul_f32 v[156:157], v[90:91], v[158:159]
	v_pk_mul_f32 v[192:193], v[84:85], v[204:205]
	v_pk_mul_f32 v[158:159], v[82:83], v[202:203]
	v_cvt_pk_bf16_f32 v156, v156, v157
	v_cvt_pk_bf16_f32 v157, v160, v161
	v_lshl_add_u64 v[160:161], s[60:61], 0, v[210:211]
	v_cvt_pk_bf16_f32 v158, v158, v159
	v_cvt_pk_bf16_f32 v159, v192, v193
	v_lshl_add_u64 v[160:161], v[186:187], 1, v[160:161]
	global_store_dwordx4 v[160:161], v[156:159], off
	v_lshl_add_u64 v[226:227], v[212:213], 0, v[242:243]
	global_load_dwordx4 v[214:217], v[226:227], off offset:-3584 nt
	global_load_dwordx4 v[218:221], v[226:227], off offset:512 nt
	s_nop 0
	v_cndmask_b32_e32 v195, v228, v195, vcc
	v_lshlrev_b32_e32 v200, 2, v195
	v_xor_b32_e32 v195, 32, v228
	v_cmp_lt_i32_e32 vcc, v195, v201
	s_waitcnt vmcnt(0)
; __device__ __forceinline__ unsigned pk2(float lo, float hi) { return pg8::cvt_pk_bf16(lo, hi); }
;     __device__ __forceinline__ void operator()(const f32x4 (&acc)[2][2][4][2], const pg8::Unit& u, int wr, int wc, int fr, int fq) const {
;     ...
;                 for (int bj = 0; bj < 2; ++bj) { const int c = u.pn * 256 + bj * 128 + wc * 32 + 8 * fq;
;                     const f32x4 xa = *(const f32x4*)(src + c) + gv[bj][0] * acc[ai][bj][m][0];
;                     const f32x4 xb = *(const f32x4*)(src + c + 4) + gv[bj][1] * acc[ai][bj][m][1];
;                     *(f32x4*)(dst + c) = xa; *(f32x4*)(dst + c + 4) = xb;
;                     ss += (xa[0] * xa[0] + xa[1] * xa[1]) + (xa[2] * xa[2] + xa[3] * xa[3]) + (xb[0] * xb[0] + xb[1] * xb[1]) + (xb[2] * xb[2] + xb[3] * xb[3]);
;                     const f32x4 ya = xa * sv[bj][0], yb = xb * sv[bj][1];
;                     u32x4 w; w.x = pk2(ya[0], ya[1]); w.y = pk2(ya[2], ya[3]); w.z = pk2(yb[0], yb[1]); w.w = pk2(yb[2], yb[3]);
;                     *(u32x4*)(Hn + (size_t)R * DM + c) = w; }
;                 ss += __shfl_xor(ss, 16); ss += __shfl_xor(ss, 32);
;                 if (fq == 0) stat[(size_t)R * 16 + u.pn * 4 + wc] = ss;
;             }
	v_cndmask_b32_e64 v222, v218, v214, s[100:101]
	v_cndmask_b32_e64 v223, v219, v215, s[100:101]
	v_cndmask_b32_e64 v224, v220, v216, s[100:101]
	v_cndmask_b32_e64 v225, v221, v217, s[100:101]
	v_mov_b32_dpp v238, v222 quad_perm:[1,0,3,2] row_mask:0xf bank_mask:0xf
	v_mov_b32_dpp v239, v223 quad_perm:[1,0,3,2] row_mask:0xf bank_mask:0xf
	v_mov_b32_dpp v240, v224 quad_perm:[1,0,3,2] row_mask:0xf bank_mask:0xf
	v_mov_b32_dpp v241, v225 quad_perm:[1,0,3,2] row_mask:0xf bank_mask:0xf
	v_cndmask_b32_e64 v202, v214, v238, s[100:101]
	v_cndmask_b32_e64 v156, v238, v218, s[100:101]
	v_cndmask_b32_e64 v203, v215, v239, s[100:101]
	v_cndmask_b32_e64 v157, v239, v219, s[100:101]
	v_cndmask_b32_e64 v204, v216, v240, s[100:101]
	v_cndmask_b32_e64 v158, v240, v220, s[100:101]
	v_cndmask_b32_e64 v205, v217, v241, s[100:101]
	v_cndmask_b32_e64 v159, v241, v221, s[100:101]
	v_pk_fma_f32 v[148:149], v[148:149], v[76:77], v[158:159]
	s_waitcnt vmcnt(0)
	v_pk_fma_f32 v[152:153], v[152:153], v[80:81], v[204:205]
	v_pk_fma_f32 v[150:151], v[150:151], v[78:79], v[202:203]
	v_pk_fma_f32 v[146:147], v[146:147], v[74:75], v[156:157]
	v_cndmask_b32_e64 v222, v146, v150, s[100:101]
	v_cndmask_b32_e64 v223, v147, v151, s[100:101]
	v_cndmask_b32_e64 v224, v148, v152, s[100:101]
	v_cndmask_b32_e64 v225, v149, v153, s[100:101]
	v_mov_b32_dpp v238, v222 quad_perm:[1,0,3,2] row_mask:0xf bank_mask:0xf
	v_mov_b32_dpp v239, v223 quad_perm:[1,0,3,2] row_mask:0xf bank_mask:0xf
	v_mov_b32_dpp v240, v224 quad_perm:[1,0,3,2] row_mask:0xf bank_mask:0xf
	v_mov_b32_dpp v241, v225 quad_perm:[1,0,3,2] row_mask:0xf bank_mask:0xf
	v_cndmask_b32_e64 v214, v150, v238, s[100:101]
	v_cndmask_b32_e64 v218, v238, v146, s[100:101]
	v_cndmask_b32_e64 v215, v151, v239, s[100:101]
	v_cndmask_b32_e64 v219, v239, v147, s[100:101]
	v_cndmask_b32_e64 v216, v152, v240, s[100:101]
	v_cndmask_b32_e64 v220, v240, v148, s[100:101]
	v_cndmask_b32_e64 v217, v153, v241, s[100:101]
	v_cndmask_b32_e64 v221, v241, v149, s[100:101]
	v_lshl_add_u64 v[226:227], v[154:155], 0, v[242:243]
	global_store_dwordx4 v[226:227], v[214:217], off offset:-3584
	global_store_dwordx4 v[226:227], v[218:221], off offset:512
	v_mul_f32_e32 v154, v151, v151
	v_mul_f32_e32 v155, v153, v153
	v_fmac_f32_e32 v154, v150, v150
	v_fmac_f32_e32 v155, v152, v152
	v_add_f32_e32 v154, v154, v155
	v_mul_f32_e32 v155, v147, v147
	v_fmac_f32_e32 v155, v146, v146
	v_add_f32_e32 v154, v154, v155
	v_mul_f32_e32 v155, v149, v149
	v_fmac_f32_e32 v155, v148, v148
	v_add_f32_e32 v154, v155, v154
	v_add_f32_e32 v156, v194, v154
	v_pk_mul_f32 v[152:153], v[64:65], v[152:153]
	v_pk_mul_f32 v[150:151], v[62:63], v[150:151]
	v_pk_mul_f32 v[154:155], v[60:61], v[148:149]
	v_pk_mul_f32 v[148:149], v[58:59], v[146:147]
	v_cvt_pk_bf16_f32 v146, v150, v151
	v_cvt_pk_bf16_f32 v147, v152, v153
	v_cvt_pk_bf16_f32 v148, v148, v149
	v_cvt_pk_bf16_f32 v149, v154, v155
	global_store_dwordx4 v[160:161], v[146:149], off offset:256
	ds_bpermute_b32 v146, v200, v156
	v_cndmask_b32_e32 v195, v228, v195, vcc
	v_lshlrev_b32_e32 v195, 2, v195
	s_waitcnt lgkmcnt(0)
	v_add_f32_e32 v146, v156, v146
	ds_bpermute_b32 v147, v195, v146
	s_and_saveexec_b64 s[34:35], s[38:39]
	s_cbranch_execz .LBB0_924
	v_lshlrev_b64 v[148:149], 6, v[190:191]
	v_lshl_add_u64 v[148:149], s[62:63], 0, v[148:149]
	v_lshl_add_u64 v[148:149], s[24:25], 2, v[148:149]
	s_lshl_b32 s0, s47, 2
	v_lshl_add_u64 v[148:149], v[148:149], 0, s[0:1]
	s_waitcnt lgkmcnt(0)
	v_add_f32_e32 v146, v146, v147
	global_store_dword v[148:149], v146, off

; __device__ __forceinline__ unsigned pk2(float lo, float hi) { return pg8::cvt_pk_bf16(lo, hi); }
;     __device__ __forceinline__ void operator()(const f32x4 (&acc)[2][2][4][2], const pg8::Unit& u, int wr, int wc, int fr, int fq) const {
;     ...
;             for (int m = 0; m < 4; ++m) {
;                 const int R = rowbase + u.pm * 256 + ai * 128 + wr * 64 + m * 16 + fr;
;                 const float* src = islat ? rin_l + (size_t)R * DM : rin_c + (size_t)(R - TL) * DM;
;                 float* dst = islat ? rout_l + (size_t)R * DM : rout_c + (size_t)(R - TL) * DM;
;                 float ss = 0.f;
; #pragma unroll
;                 for (int bj = 0; bj < 2; ++bj) { const int c = u.pn * 256 + bj * 128 + wc * 32 + 8 * fq;
;                     const f32x4 xa = *(const f32x4*)(src + c) + gv[bj][0] * acc[ai][bj][m][0];
;                     const f32x4 xb = *(const f32x4*)(src + c + 4) + gv[bj][1] * acc[ai][bj][m][1];
;                     *(f32x4*)(dst + c) = xa; *(f32x4*)(dst + c + 4) = xb;
;                     ss += (xa[0] * xa[0] + xa[1] * xa[1]) + (xa[2] * xa[2] + xa[3] * xa[3]) + (xb[0] * xb[0] + xb[1] * xb[1]) + (xb[2] * xb[2] + xb[3] * xb[3]);
;                     const f32x4 ya = xa * sv[bj][0], yb = xb * sv[bj][1];
;                     u32x4 w; w.x = pk2(ya[0], ya[1]); w.y = pk2(ya[2], ya[3]); w.z = pk2(yb[0], yb[1]); w.w = pk2(yb[2], yb[3]);
;                     *(u32x4*)(Hn + (size_t)R * DM + c) = w; }
;                 ss += __shfl_xor(ss, 16); ss += __shfl_xor(ss, 32);
;                 if (fq == 0) stat[(size_t)R * 16 + u.pn * 4 + wc] = ss;
;             }
.LBB0_928:
	v_cndmask_b32_e64 v150, v150, v146, s[42:43]
	v_ashrrev_i32_e32 v151, 31, v150
	v_lshlrev_b64 v[150:151], 12, v[150:151]
	v_lshl_add_u64 v[150:151], s[68:69], 0, v[150:151]
	v_lshl_add_u64 v[158:159], v[150:151], 0, v[188:189]
	v_lshl_add_u64 v[226:227], v[158:159], 0, v[242:243]
	global_load_dwordx4 v[214:217], v[226:227], off offset:-4096 nt
	global_load_dwordx4 v[218:221], v[226:227], off nt
	v_lshlrev_b64 v[160:161], 11, v[146:147]
	v_lshl_add_u64 v[192:193], v[148:149], 0, v[188:189]
	v_lshl_add_u64 v[148:149], s[60:61], 0, v[160:161]
	v_lshl_add_u64 v[160:161], v[186:187], 1, v[148:149]
	s_waitcnt vmcnt(0)
	v_cndmask_b32_e64 v222, v218, v214, s[100:101]
	v_cndmask_b32_e64 v223, v219, v215, s[100:101]
	v_cndmask_b32_e64 v224, v220, v216, s[100:101]
	v_cndmask_b32_e64 v225, v221, v217, s[100:101]
	v_mov_b32_dpp v238, v222 quad_perm:[1,0,3,2] row_mask:0xf bank_mask:0xf
	v_mov_b32_dpp v239, v223 quad_perm:[1,0,3,2] row_mask:0xf bank_mask:0xf
	v_mov_b32_dpp v240, v224 quad_perm:[1,0,3,2] row_mask:0xf bank_mask:0xf
	v_mov_b32_dpp v241, v225 quad_perm:[1,0,3,2] row_mask:0xf bank_mask:0xf
	v_cndmask_b32_e64 v150, v214, v238, s[100:101]
	v_cndmask_b32_e64 v154, v238, v218, s[100:101]
	v_cndmask_b32_e64 v151, v215, v239, s[100:101]
	v_cndmask_b32_e64 v155, v239, v219, s[100:101]
	v_cndmask_b32_e64 v152, v216, v240, s[100:101]
	v_cndmask_b32_e64 v156, v240, v220, s[100:101]
	v_cndmask_b32_e64 v153, v217, v241, s[100:101]
	v_cndmask_b32_e64 v157, v241, v221, s[100:101]
	v_pk_fma_f32 v[144:145], v[144:145], v[96:97], v[152:153]
	v_pk_fma_f32 v[142:143], v[142:143], v[94:95], v[150:151]
	s_waitcnt vmcnt(0)
	v_pk_fma_f32 v[140:141], v[140:141], v[88:89], v[156:157]
	v_pk_fma_f32 v[138:139], v[138:139], v[86:87], v[154:155]
	v_pk_mul_f32 v[150:151], v[92:93], v[144:145]
	v_pk_mul_f32 v[148:149], v[90:91], v[142:143]
	v_pk_mul_f32 v[152:153], v[84:85], v[140:141]
	v_pk_mul_f32 v[154:155], v[82:83], v[138:139]
	v_cvt_pk_bf16_f32 v148, v148, v149
	v_cvt_pk_bf16_f32 v149, v150, v151
	v_cvt_pk_bf16_f32 v150, v154, v155
	v_cvt_pk_bf16_f32 v151, v152, v153
	v_cndmask_b32_e64 v222, v138, v142, s[100:101]
	v_cndmask_b32_e64 v223, v139, v143, s[100:101]
	v_cndmask_b32_e64 v224, v140, v144, s[100:101]
	v_cndmask_b32_e64 v225, v141, v145, s[100:101]
	v_mov_b32_dpp v238, v222 quad_perm:[1,0,3,2] row_mask:0xf bank_mask:0xf
	v_mov_b32_dpp v239, v223 quad_perm:[1,0,3,2] row_mask:0xf bank_mask:0xf
	v_mov_b32_dpp v240, v224 quad_perm:[1,0,3,2] row_mask:0xf bank_mask:0xf
	v_mov_b32_dpp v241, v225 quad_perm:[1,0,3,2] row_mask:0xf bank_mask:0xf
	v_cndmask_b32_e64 v214, v142, v238, s[100:101]
	v_cndmask_b32_e64 v218, v238, v138, s[100:101]
	v_cndmask_b32_e64 v215, v143, v239, s[100:101]
	v_cndmask_b32_e64 v219, v239, v139, s[100:101]
	v_cndmask_b32_e64 v216, v144, v240, s[100:101]
	v_cndmask_b32_e64 v220, v240, v140, s[100:101]
	v_cndmask_b32_e64 v217, v145, v241, s[100:101]
	v_cndmask_b32_e64 v221, v241, v141, s[100:101]
	v_lshl_add_u64 v[226:227], v[192:193], 0, v[242:243]
	global_store_dwordx4 v[226:227], v[214:217], off offset:-4096
	global_store_dwordx4 v[226:227], v[218:221], off
	global_store_dwordx4 v[160:161], v[148:151], off
	v_lshl_add_u64 v[226:227], v[158:159], 0, v[242:243]
	global_load_dwordx4 v[214:217], v[226:227], off offset:-3584 nt
	global_load_dwordx4 v[218:221], v[226:227], off offset:512 nt
	s_nop 0
	v_mul_f32_e32 v143, v143, v143
	v_mul_f32_e32 v145, v145, v145
	v_mul_f32_e32 v139, v139, v139
	v_fmac_f32_e32 v143, v142, v142
	v_fmac_f32_e32 v145, v144, v144
	v_mul_f32_e32 v141, v141, v141
	v_fmac_f32_e32 v139, v138, v138
	v_add_f32_e32 v138, v143, v145
	v_fmac_f32_e32 v141, v140, v140
	v_add_f32_e32 v138, v138, v139
	v_add_f32_e32 v138, v141, v138
	s_waitcnt vmcnt(0)
	v_cndmask_b32_e64 v222, v218, v214, s[100:101]
	v_cndmask_b32_e64 v223, v219, v215, s[100:101]
	v_cndmask_b32_e64 v224, v220, v216, s[100:101]
	v_cndmask_b32_e64 v225, v221, v217, s[100:101]
	v_mov_b32_dpp v238, v222 quad_perm:[1,0,3,2] row_mask:0xf bank_mask:0xf
	v_mov_b32_dpp v239, v223 quad_perm:[1,0,3,2] row_mask:0xf bank_mask:0xf
	v_mov_b32_dpp v240, v224 quad_perm:[1,0,3,2] row_mask:0xf bank_mask:0xf
	v_mov_b32_dpp v241, v225 quad_perm:[1,0,3,2] row_mask:0xf bank_mask:0xf
	v_cndmask_b32_e64 v148, v214, v238, s[100:101]
	v_cndmask_b32_e64 v152, v238, v218, s[100:101]
	v_cndmask_b32_e64 v149, v215, v239, s[100:101]
	v_cndmask_b32_e64 v153, v239, v219, s[100:101]
	v_cndmask_b32_e64 v150, v216, v240, s[100:101]
	v_cndmask_b32_e64 v154, v240, v220, s[100:101]
	v_cndmask_b32_e64 v151, v217, v241, s[100:101]
	v_cndmask_b32_e64 v155, v241, v221, s[100:101]
	v_pk_fma_f32 v[136:137], v[136:137], v[80:81], v[150:151]
	v_pk_fma_f32 v[134:135], v[134:135], v[78:79], v[148:149]
	s_waitcnt vmcnt(0)
	v_pk_fma_f32 v[130:131], v[130:131], v[74:75], v[152:153]
	v_mul_f32_e32 v139, v135, v135
	v_mul_f32_e32 v140, v137, v137
	v_pk_fma_f32 v[132:133], v[132:133], v[76:77], v[154:155]
	v_mul_f32_e32 v141, v131, v131
	v_fmac_f32_e32 v139, v134, v134
	v_fmac_f32_e32 v140, v136, v136
	v_mul_f32_e32 v142, v133, v133
	v_fmac_f32_e32 v141, v130, v130
	v_add_f32_e32 v139, v139, v140
	v_fmac_f32_e32 v142, v132, v132
	v_add_f32_e32 v139, v139, v141
	v_add_f32_e32 v139, v142, v139
	v_add_f32_e32 v142, v138, v139
	ds_bpermute_b32 v143, v200, v142
	v_cndmask_b32_e64 v222, v130, v134, s[100:101]
	v_cndmask_b32_e64 v223, v131, v135, s[100:101]
	v_cndmask_b32_e64 v224, v132, v136, s[100:101]
	v_cndmask_b32_e64 v225, v133, v137, s[100:101]
	v_mov_b32_dpp v238, v222 quad_perm:[1,0,3,2] row_mask:0xf bank_mask:0xf
	v_mov_b32_dpp v239, v223 quad_perm:[1,0,3,2] row_mask:0xf bank_mask:0xf
	v_mov_b32_dpp v240, v224 quad_perm:[1,0,3,2] row_mask:0xf bank_mask:0xf
	v_mov_b32_dpp v241, v225 quad_perm:[1,0,3,2] row_mask:0xf bank_mask:0xf
	v_cndmask_b32_e64 v214, v134, v238, s[100:101]
	v_cndmask_b32_e64 v218, v238, v130, s[100:101]
	v_cndmask_b32_e64 v215, v135, v239, s[100:101]
	v_cndmask_b32_e64 v219, v239, v131, s[100:101]
	v_cndmask_b32_e64 v216, v136, v240, s[100:101]
	v_cndmask_b32_e64 v220, v240, v132, s[100:101]
	v_cndmask_b32_e64 v217, v137, v241, s[100:101]
	v_cndmask_b32_e64 v221, v241, v133, s[100:101]
	v_lshl_add_u64 v[226:227], v[192:193], 0, v[242:243]
	global_store_dwordx4 v[226:227], v[214:217], off offset:-3584
	global_store_dwordx4 v[226:227], v[218:221], off offset:512
	v_pk_mul_f32 v[140:141], v[58:59], v[130:131]
	v_pk_mul_f32 v[136:137], v[64:65], v[136:137]
	v_pk_mul_f32 v[134:135], v[62:63], v[134:135]
	s_waitcnt lgkmcnt(0)
	v_add_f32_e32 v130, v142, v143
	ds_bpermute_b32 v131, v195, v130
	v_pk_mul_f32 v[138:139], v[60:61], v[132:133]
	v_cvt_pk_bf16_f32 v132, v134, v135
	v_cvt_pk_bf16_f32 v133, v136, v137
	v_cvt_pk_bf16_f32 v134, v140, v141
	v_cvt_pk_bf16_f32 v135, v138, v139
	global_store_dwordx4 v[160:161], v[132:135], off offset:256
	s_and_saveexec_b64 s[34:35], s[38:39]
	s_cbranch_execz .LBB0_930
;     __device__ __forceinline__ void operator()(const f32x4 (&acc)[2][2][4][2], const pg8::Unit& u, int wr, int wc, int fr, int fq) const {
;     ...
;                 ss += __shfl_xor(ss, 16); ss += __shfl_xor(ss, 32);
;                 if (fq == 0) stat[(size_t)R * 16 + u.pn * 4 + wc] = ss;
	v_lshlrev_b64 v[132:133], 6, v[146:147]
	v_lshl_add_u64 v[132:133], s[62:63], 0, v[132:133]
	v_lshl_add_u64 v[132:133], s[24:25], 2, v[132:133]
	s_lshl_b32 s0, s47, 2
	v_lshl_add_u64 v[132:133], v[132:133], 0, s[0:1]
	s_waitcnt lgkmcnt(0)
	v_add_f32_e32 v130, v130, v131
	global_store_dword v[132:133], v130, off

; __device__ __forceinline__ unsigned pk2(float lo, float hi) { return pg8::cvt_pk_bf16(lo, hi); }
;     __device__ __forceinline__ void operator()(const f32x4 (&acc)[2][2][4][2], const pg8::Unit& u, int wr, int wc, int fr, int fq) const {
;     ...
;             for (int m = 0; m < 4; ++m) {
;                 const int R = rowbase + u.pm * 256 + ai * 128 + wr * 64 + m * 16 + fr;
;                 const float* src = islat ? rin_l + (size_t)R * DM : rin_c + (size_t)(R - TL) * DM;
;                 float* dst = islat ? rout_l + (size_t)R * DM : rout_c + (size_t)(R - TL) * DM;
;                 float ss = 0.f;
; #pragma unroll
;                 for (int bj = 0; bj < 2; ++bj) { const int c = u.pn * 256 + bj * 128 + wc * 32 + 8 * fq;
;                     const f32x4 xa = *(const f32x4*)(src + c) + gv[bj][0] * acc[ai][bj][m][0];
;                     const f32x4 xb = *(const f32x4*)(src + c + 4) + gv[bj][1] * acc[ai][bj][m][1];
;                     *(f32x4*)(dst + c) = xa; *(f32x4*)(dst + c + 4) = xb;
;                     ss += (xa[0] * xa[0] + xa[1] * xa[1]) + (xa[2] * xa[2] + xa[3] * xa[3]) + (xb[0] * xb[0] + xb[1] * xb[1]) + (xb[2] * xb[2] + xb[3] * xb[3]);
;                     const f32x4 ya = xa * sv[bj][0], yb = xb * sv[bj][1];
;                     u32x4 w; w.x = pk2(ya[0], ya[1]); w.y = pk2(ya[2], ya[3]); w.z = pk2(yb[0], yb[1]); w.w = pk2(yb[2], yb[3]);
;                     *(u32x4*)(Hn + (size_t)R * DM + c) = w; }
;                 ss += __shfl_xor(ss, 16); ss += __shfl_xor(ss, 32);
;                 if (fq == 0) stat[(size_t)R * 16 + u.pn * 4 + wc] = ss;
;             }
.LBB0_934:
	v_cndmask_b32_e64 v134, v134, v130, s[42:43]
	v_ashrrev_i32_e32 v135, 31, v134
	v_lshlrev_b64 v[134:135], 12, v[134:135]
	v_lshl_add_u64 v[134:135], s[68:69], 0, v[134:135]
	v_lshl_add_u64 v[142:143], v[134:135], 0, v[188:189]
	v_lshl_add_u64 v[226:227], v[142:143], 0, v[242:243]
	global_load_dwordx4 v[214:217], v[226:227], off offset:-4096 nt
	global_load_dwordx4 v[218:221], v[226:227], off nt
	v_lshlrev_b64 v[144:145], 11, v[130:131]
	v_lshl_add_u64 v[146:147], v[132:133], 0, v[188:189]
	v_lshl_add_u64 v[132:133], s[60:61], 0, v[144:145]
	v_lshl_add_u64 v[144:145], v[186:187], 1, v[132:133]
	s_waitcnt vmcnt(0)
	v_cndmask_b32_e64 v222, v218, v214, s[100:101]
	v_cndmask_b32_e64 v223, v219, v215, s[100:101]
	v_cndmask_b32_e64 v224, v220, v216, s[100:101]
	v_cndmask_b32_e64 v225, v221, v217, s[100:101]
	v_mov_b32_dpp v238, v222 quad_perm:[1,0,3,2] row_mask:0xf bank_mask:0xf
	v_mov_b32_dpp v239, v223 quad_perm:[1,0,3,2] row_mask:0xf bank_mask:0xf
	v_mov_b32_dpp v240, v224 quad_perm:[1,0,3,2] row_mask:0xf bank_mask:0xf
	v_mov_b32_dpp v241, v225 quad_perm:[1,0,3,2] row_mask:0xf bank_mask:0xf
	v_cndmask_b32_e64 v134, v214, v238, s[100:101]
	v_cndmask_b32_e64 v138, v238, v218, s[100:101]
	v_cndmask_b32_e64 v135, v215, v239, s[100:101]
	v_cndmask_b32_e64 v139, v239, v219, s[100:101]
	v_cndmask_b32_e64 v136, v216, v240, s[100:101]
	v_cndmask_b32_e64 v140, v240, v220, s[100:101]
	v_cndmask_b32_e64 v137, v217, v241, s[100:101]
	v_cndmask_b32_e64 v141, v241, v221, s[100:101]
	v_pk_fma_f32 v[128:129], v[128:129], v[96:97], v[136:137]
	v_pk_fma_f32 v[126:127], v[126:127], v[94:95], v[134:135]
	s_waitcnt vmcnt(0)
	v_pk_fma_f32 v[124:125], v[124:125], v[88:89], v[140:141]
	v_pk_fma_f32 v[122:123], v[122:123], v[86:87], v[138:139]
	v_pk_mul_f32 v[134:135], v[92:93], v[128:129]
	v_pk_mul_f32 v[132:133], v[90:91], v[126:127]
	v_pk_mul_f32 v[136:137], v[84:85], v[124:125]
	v_pk_mul_f32 v[138:139], v[82:83], v[122:123]
	v_cvt_pk_bf16_f32 v132, v132, v133
	v_cvt_pk_bf16_f32 v133, v134, v135
	v_cvt_pk_bf16_f32 v134, v138, v139
	v_cvt_pk_bf16_f32 v135, v136, v137
	v_cndmask_b32_e64 v222, v122, v126, s[100:101]
	v_cndmask_b32_e64 v223, v123, v127, s[100:101]
	v_cndmask_b32_e64 v224, v124, v128, s[100:101]
	v_cndmask_b32_e64 v225, v125, v129, s[100:101]
	v_mov_b32_dpp v238, v222 quad_perm:[1,0,3,2] row_mask:0xf bank_mask:0xf
	v_mov_b32_dpp v239, v223 quad_perm:[1,0,3,2] row_mask:0xf bank_mask:0xf
	v_mov_b32_dpp v240, v224 quad_perm:[1,0,3,2] row_mask:0xf bank_mask:0xf
	v_mov_b32_dpp v241, v225 quad_perm:[1,0,3,2] row_mask:0xf bank_mask:0xf
	v_cndmask_b32_e64 v214, v126, v238, s[100:101]
	v_cndmask_b32_e64 v218, v238, v122, s[100:101]
	v_cndmask_b32_e64 v215, v127, v239, s[100:101]
	v_cndmask_b32_e64 v219, v239, v123, s[100:101]
	v_cndmask_b32_e64 v216, v128, v240, s[100:101]
	v_cndmask_b32_e64 v220, v240, v124, s[100:101]
	v_cndmask_b32_e64 v217, v129, v241, s[100:101]
	v_cndmask_b32_e64 v221, v241, v125, s[100:101]
	v_lshl_add_u64 v[226:227], v[146:147], 0, v[242:243]
	global_store_dwordx4 v[226:227], v[214:217], off offset:-4096
	global_store_dwordx4 v[226:227], v[218:221], off
	global_store_dwordx4 v[144:145], v[132:135], off
	v_lshl_add_u64 v[226:227], v[142:143], 0, v[242:243]
	global_load_dwordx4 v[214:217], v[226:227], off offset:-3584 nt
	global_load_dwordx4 v[218:221], v[226:227], off offset:512 nt
	s_nop 0
	v_mul_f32_e32 v127, v127, v127
	v_mul_f32_e32 v129, v129, v129
	v_mul_f32_e32 v123, v123, v123
	v_fmac_f32_e32 v127, v126, v126
	v_fmac_f32_e32 v129, v128, v128
	v_mul_f32_e32 v125, v125, v125
	v_fmac_f32_e32 v123, v122, v122
	v_add_f32_e32 v122, v127, v129
	v_fmac_f32_e32 v125, v124, v124
	v_add_f32_e32 v122, v122, v123
	v_add_f32_e32 v122, v125, v122
	s_waitcnt vmcnt(0)
	v_cndmask_b32_e64 v222, v218, v214, s[100:101]
	v_cndmask_b32_e64 v223, v219, v215, s[100:101]
	v_cndmask_b32_e64 v224, v220, v216, s[100:101]
	v_cndmask_b32_e64 v225, v221, v217, s[100:101]
	v_mov_b32_dpp v238, v222 quad_perm:[1,0,3,2] row_mask:0xf bank_mask:0xf
	v_mov_b32_dpp v239, v223 quad_perm:[1,0,3,2] row_mask:0xf bank_mask:0xf
	v_mov_b32_dpp v240, v224 quad_perm:[1,0,3,2] row_mask:0xf bank_mask:0xf
	v_mov_b32_dpp v241, v225 quad_perm:[1,0,3,2] row_mask:0xf bank_mask:0xf
	v_cndmask_b32_e64 v132, v214, v238, s[100:101]
	v_cndmask_b32_e64 v136, v238, v218, s[100:101]
	v_cndmask_b32_e64 v133, v215, v239, s[100:101]
	v_cndmask_b32_e64 v137, v239, v219, s[100:101]
	v_cndmask_b32_e64 v134, v216, v240, s[100:101]
	v_cndmask_b32_e64 v138, v240, v220, s[100:101]
	v_cndmask_b32_e64 v135, v217, v241, s[100:101]
	v_cndmask_b32_e64 v139, v241, v221, s[100:101]
	v_pk_fma_f32 v[120:121], v[120:121], v[80:81], v[134:135]
	v_pk_fma_f32 v[118:119], v[118:119], v[78:79], v[132:133]
	s_waitcnt vmcnt(0)
	v_pk_fma_f32 v[114:115], v[114:115], v[74:75], v[136:137]
	v_mul_f32_e32 v123, v119, v119
	v_mul_f32_e32 v124, v121, v121
	v_pk_fma_f32 v[116:117], v[116:117], v[76:77], v[138:139]
	v_mul_f32_e32 v125, v115, v115
	v_fmac_f32_e32 v123, v118, v118
	v_fmac_f32_e32 v124, v120, v120
	v_mul_f32_e32 v126, v117, v117
	v_fmac_f32_e32 v125, v114, v114
	v_add_f32_e32 v123, v123, v124
	v_fmac_f32_e32 v126, v116, v116
	v_add_f32_e32 v123, v123, v125
	v_add_f32_e32 v123, v126, v123
	v_add_f32_e32 v126, v122, v123
	ds_bpermute_b32 v127, v200, v126
	v_cndmask_b32_e64 v222, v114, v118, s[100:101]
	v_cndmask_b32_e64 v223, v115, v119, s[100:101]
	v_cndmask_b32_e64 v224, v116, v120, s[100:101]
	v_cndmask_b32_e64 v225, v117, v121, s[100:101]
	v_mov_b32_dpp v238, v222 quad_perm:[1,0,3,2] row_mask:0xf bank_mask:0xf
	v_mov_b32_dpp v239, v223 quad_perm:[1,0,3,2] row_mask:0xf bank_mask:0xf
	v_mov_b32_dpp v240, v224 quad_perm:[1,0,3,2] row_mask:0xf bank_mask:0xf
	v_mov_b32_dpp v241, v225 quad_perm:[1,0,3,2] row_mask:0xf bank_mask:0xf
	v_cndmask_b32_e64 v214, v118, v238, s[100:101]
	v_cndmask_b32_e64 v218, v238, v114, s[100:101]
	v_cndmask_b32_e64 v215, v119, v239, s[100:101]
	v_cndmask_b32_e64 v219, v239, v115, s[100:101]
	v_cndmask_b32_e64 v216, v120, v240, s[100:101]
	v_cndmask_b32_e64 v220, v240, v116, s[100:101]
	v_cndmask_b32_e64 v217, v121, v241, s[100:101]
	v_cndmask_b32_e64 v221, v241, v117, s[100:101]
	v_lshl_add_u64 v[226:227], v[146:147], 0, v[242:243]
	global_store_dwordx4 v[226:227], v[214:217], off offset:-3584
	global_store_dwordx4 v[226:227], v[218:221], off offset:512
	v_pk_mul_f32 v[124:125], v[58:59], v[114:115]
	v_pk_mul_f32 v[120:121], v[64:65], v[120:121]
	v_pk_mul_f32 v[118:119], v[62:63], v[118:119]
	s_waitcnt lgkmcnt(0)
	v_add_f32_e32 v114, v126, v127
	ds_bpermute_b32 v115, v195, v114
	v_pk_mul_f32 v[122:123], v[60:61], v[116:117]
	v_cvt_pk_bf16_f32 v116, v118, v119
	v_cvt_pk_bf16_f32 v117, v120, v121
	v_cvt_pk_bf16_f32 v118, v124, v125
	v_cvt_pk_bf16_f32 v119, v122, v123
	global_store_dwordx4 v[144:145], v[116:119], off offset:256
	s_and_saveexec_b64 s[34:35], s[38:39]
	s_cbranch_execz .LBB0_936
;     __device__ __forceinline__ void operator()(const f32x4 (&acc)[2][2][4][2], const pg8::Unit& u, int wr, int wc, int fr, int fq) const {
;     ...
;                 ss += __shfl_xor(ss, 16); ss += __shfl_xor(ss, 32);
;                 if (fq == 0) stat[(size_t)R * 16 + u.pn * 4 + wc] = ss;
	v_lshlrev_b64 v[116:117], 6, v[130:131]
	v_lshl_add_u64 v[116:117], s[62:63], 0, v[116:117]
	v_lshl_add_u64 v[116:117], s[24:25], 2, v[116:117]
	s_lshl_b32 s0, s47, 2
	v_lshl_add_u64 v[116:117], v[116:117], 0, s[0:1]
	s_waitcnt lgkmcnt(0)
	v_add_f32_e32 v114, v114, v115
	global_store_dword v[116:117], v114, off

; __device__ __forceinline__ unsigned pk2(float lo, float hi) { return pg8::cvt_pk_bf16(lo, hi); }
;     __device__ __forceinline__ void operator()(const f32x4 (&acc)[2][2][4][2], const pg8::Unit& u, int wr, int wc, int fr, int fq) const {
;     ...
;             for (int m = 0; m < 4; ++m) {
;                 const int R = rowbase + u.pm * 256 + ai * 128 + wr * 64 + m * 16 + fr;
;                 const float* src = islat ? rin_l + (size_t)R * DM : rin_c + (size_t)(R - TL) * DM;
;                 float* dst = islat ? rout_l + (size_t)R * DM : rout_c + (size_t)(R - TL) * DM;
;                 float ss = 0.f;
; #pragma unroll
;                 for (int bj = 0; bj < 2; ++bj) { const int c = u.pn * 256 + bj * 128 + wc * 32 + 8 * fq;
;                     const f32x4 xa = *(const f32x4*)(src + c) + gv[bj][0] * acc[ai][bj][m][0];
;                     const f32x4 xb = *(const f32x4*)(src + c + 4) + gv[bj][1] * acc[ai][bj][m][1];
;                     *(f32x4*)(dst + c) = xa; *(f32x4*)(dst + c + 4) = xb;
;                     ss += (xa[0] * xa[0] + xa[1] * xa[1]) + (xa[2] * xa[2] + xa[3] * xa[3]) + (xb[0] * xb[0] + xb[1] * xb[1]) + (xb[2] * xb[2] + xb[3] * xb[3]);
;                     const f32x4 ya = xa * sv[bj][0], yb = xb * sv[bj][1];
;                     u32x4 w; w.x = pk2(ya[0], ya[1]); w.y = pk2(ya[2], ya[3]); w.z = pk2(yb[0], yb[1]); w.w = pk2(yb[2], yb[3]);
;                     *(u32x4*)(Hn + (size_t)R * DM + c) = w; }
;                 ss += __shfl_xor(ss, 16); ss += __shfl_xor(ss, 32);
;                 if (fq == 0) stat[(size_t)R * 16 + u.pn * 4 + wc] = ss;
;             }
.LBB0_940:
	v_cndmask_b32_e64 v118, v118, v114, s[42:43]
	v_ashrrev_i32_e32 v119, 31, v118
	v_lshlrev_b64 v[118:119], 12, v[118:119]
	v_lshl_add_u64 v[118:119], s[68:69], 0, v[118:119]
	v_lshl_add_u64 v[126:127], v[118:119], 0, v[188:189]
	v_lshl_add_u64 v[226:227], v[126:127], 0, v[242:243]
	global_load_dwordx4 v[214:217], v[226:227], off offset:-4096 nt
	global_load_dwordx4 v[218:221], v[226:227], off nt
	v_lshlrev_b64 v[128:129], 11, v[114:115]
	v_lshl_add_u64 v[130:131], v[116:117], 0, v[188:189]
	v_lshl_add_u64 v[116:117], s[60:61], 0, v[128:129]
	v_lshl_add_u64 v[128:129], v[186:187], 1, v[116:117]
	s_waitcnt vmcnt(0)
	v_cndmask_b32_e64 v222, v218, v214, s[100:101]
	v_cndmask_b32_e64 v223, v219, v215, s[100:101]
	v_cndmask_b32_e64 v224, v220, v216, s[100:101]
	v_cndmask_b32_e64 v225, v221, v217, s[100:101]
	v_mov_b32_dpp v238, v222 quad_perm:[1,0,3,2] row_mask:0xf bank_mask:0xf
	v_mov_b32_dpp v239, v223 quad_perm:[1,0,3,2] row_mask:0xf bank_mask:0xf
	v_mov_b32_dpp v240, v224 quad_perm:[1,0,3,2] row_mask:0xf bank_mask:0xf
	v_mov_b32_dpp v241, v225 quad_perm:[1,0,3,2] row_mask:0xf bank_mask:0xf
	v_cndmask_b32_e64 v118, v214, v238, s[100:101]
	v_cndmask_b32_e64 v122, v238, v218, s[100:101]
	v_cndmask_b32_e64 v119, v215, v239, s[100:101]
	v_cndmask_b32_e64 v123, v239, v219, s[100:101]
	v_cndmask_b32_e64 v120, v216, v240, s[100:101]
	v_cndmask_b32_e64 v124, v240, v220, s[100:101]
	v_cndmask_b32_e64 v121, v217, v241, s[100:101]
	v_cndmask_b32_e64 v125, v241, v221, s[100:101]
	v_pk_fma_f32 v[112:113], v[112:113], v[96:97], v[120:121]
	v_pk_fma_f32 v[110:111], v[110:111], v[94:95], v[118:119]
	s_waitcnt vmcnt(0)
	v_pk_fma_f32 v[108:109], v[108:109], v[88:89], v[124:125]
	v_pk_fma_f32 v[106:107], v[106:107], v[86:87], v[122:123]
	v_pk_mul_f32 v[118:119], v[92:93], v[112:113]
	v_pk_mul_f32 v[116:117], v[90:91], v[110:111]
	v_pk_mul_f32 v[120:121], v[84:85], v[108:109]
	v_pk_mul_f32 v[122:123], v[82:83], v[106:107]
	v_cvt_pk_bf16_f32 v116, v116, v117
	v_cvt_pk_bf16_f32 v117, v118, v119
	v_cvt_pk_bf16_f32 v118, v122, v123
	v_cvt_pk_bf16_f32 v119, v120, v121
	v_cndmask_b32_e64 v222, v106, v110, s[100:101]
	v_cndmask_b32_e64 v223, v107, v111, s[100:101]
	v_cndmask_b32_e64 v224, v108, v112, s[100:101]
	v_cndmask_b32_e64 v225, v109, v113, s[100:101]
	v_mov_b32_dpp v238, v222 quad_perm:[1,0,3,2] row_mask:0xf bank_mask:0xf
	v_mov_b32_dpp v239, v223 quad_perm:[1,0,3,2] row_mask:0xf bank_mask:0xf
	v_mov_b32_dpp v240, v224 quad_perm:[1,0,3,2] row_mask:0xf bank_mask:0xf
	v_mov_b32_dpp v241, v225 quad_perm:[1,0,3,2] row_mask:0xf bank_mask:0xf
	v_cndmask_b32_e64 v214, v110, v238, s[100:101]
	v_cndmask_b32_e64 v218, v238, v106, s[100:101]
	v_cndmask_b32_e64 v215, v111, v239, s[100:101]
	v_cndmask_b32_e64 v219, v239, v107, s[100:101]
	v_cndmask_b32_e64 v216, v112, v240, s[100:101]
	v_cndmask_b32_e64 v220, v240, v108, s[100:101]
	v_cndmask_b32_e64 v217, v113, v241, s[100:101]
	v_cndmask_b32_e64 v221, v241, v109, s[100:101]
	v_lshl_add_u64 v[226:227], v[130:131], 0, v[242:243]
	global_store_dwordx4 v[226:227], v[214:217], off offset:-4096
	global_store_dwordx4 v[226:227], v[218:221], off
	global_store_dwordx4 v[128:129], v[116:119], off
	v_lshl_add_u64 v[226:227], v[126:127], 0, v[242:243]
	global_load_dwordx4 v[214:217], v[226:227], off offset:-3584 nt
	global_load_dwordx4 v[218:221], v[226:227], off offset:512 nt
	s_nop 0
	v_mul_f32_e32 v111, v111, v111
	v_mul_f32_e32 v113, v113, v113
	v_mul_f32_e32 v107, v107, v107
	v_fmac_f32_e32 v111, v110, v110
	v_fmac_f32_e32 v113, v112, v112
	v_mul_f32_e32 v109, v109, v109
	v_fmac_f32_e32 v107, v106, v106
	v_add_f32_e32 v106, v111, v113
	v_fmac_f32_e32 v109, v108, v108
	v_add_f32_e32 v106, v106, v107
	v_add_f32_e32 v106, v109, v106
	s_waitcnt vmcnt(0)
	v_cndmask_b32_e64 v222, v218, v214, s[100:101]
	v_cndmask_b32_e64 v223, v219, v215, s[100:101]
	v_cndmask_b32_e64 v224, v220, v216, s[100:101]
	v_cndmask_b32_e64 v225, v221, v217, s[100:101]
	v_mov_b32_dpp v238, v222 quad_perm:[1,0,3,2] row_mask:0xf bank_mask:0xf
	v_mov_b32_dpp v239, v223 quad_perm:[1,0,3,2] row_mask:0xf bank_mask:0xf
	v_mov_b32_dpp v240, v224 quad_perm:[1,0,3,2] row_mask:0xf bank_mask:0xf
	v_mov_b32_dpp v241, v225 quad_perm:[1,0,3,2] row_mask:0xf bank_mask:0xf
	v_cndmask_b32_e64 v116, v214, v238, s[100:101]
	v_cndmask_b32_e64 v120, v238, v218, s[100:101]
	v_cndmask_b32_e64 v117, v215, v239, s[100:101]
	v_cndmask_b32_e64 v121, v239, v219, s[100:101]
	v_cndmask_b32_e64 v118, v216, v240, s[100:101]
	v_cndmask_b32_e64 v122, v240, v220, s[100:101]
	v_cndmask_b32_e64 v119, v217, v241, s[100:101]
	v_cndmask_b32_e64 v123, v241, v221, s[100:101]
	v_pk_fma_f32 v[104:105], v[104:105], v[80:81], v[118:119]
	v_pk_fma_f32 v[102:103], v[102:103], v[78:79], v[116:117]
	s_waitcnt vmcnt(0)
	v_pk_fma_f32 v[98:99], v[98:99], v[74:75], v[120:121]
	v_mul_f32_e32 v107, v103, v103
	v_mul_f32_e32 v108, v105, v105
	v_pk_fma_f32 v[100:101], v[100:101], v[76:77], v[122:123]
	v_mul_f32_e32 v109, v99, v99
	v_fmac_f32_e32 v107, v102, v102
	v_fmac_f32_e32 v108, v104, v104
	v_mul_f32_e32 v110, v101, v101
	v_fmac_f32_e32 v109, v98, v98
	v_add_f32_e32 v107, v107, v108
	v_fmac_f32_e32 v110, v100, v100
	v_add_f32_e32 v107, v107, v109
	v_add_f32_e32 v107, v110, v107
	v_add_f32_e32 v110, v106, v107
	ds_bpermute_b32 v111, v200, v110
	v_cndmask_b32_e64 v222, v98, v102, s[100:101]
	v_cndmask_b32_e64 v223, v99, v103, s[100:101]
	v_cndmask_b32_e64 v224, v100, v104, s[100:101]
	v_cndmask_b32_e64 v225, v101, v105, s[100:101]
	v_mov_b32_dpp v238, v222 quad_perm:[1,0,3,2] row_mask:0xf bank_mask:0xf
	v_mov_b32_dpp v239, v223 quad_perm:[1,0,3,2] row_mask:0xf bank_mask:0xf
	v_mov_b32_dpp v240, v224 quad_perm:[1,0,3,2] row_mask:0xf bank_mask:0xf
	v_mov_b32_dpp v241, v225 quad_perm:[1,0,3,2] row_mask:0xf bank_mask:0xf
	v_cndmask_b32_e64 v214, v102, v238, s[100:101]
	v_cndmask_b32_e64 v218, v238, v98, s[100:101]
	v_cndmask_b32_e64 v215, v103, v239, s[100:101]
	v_cndmask_b32_e64 v219, v239, v99, s[100:101]
	v_cndmask_b32_e64 v216, v104, v240, s[100:101]
	v_cndmask_b32_e64 v220, v240, v100, s[100:101]
	v_cndmask_b32_e64 v217, v105, v241, s[100:101]
	v_cndmask_b32_e64 v221, v241, v101, s[100:101]
	v_lshl_add_u64 v[226:227], v[130:131], 0, v[242:243]
	global_store_dwordx4 v[226:227], v[214:217], off offset:-3584
	global_store_dwordx4 v[226:227], v[218:221], off offset:512
	v_pk_mul_f32 v[108:109], v[58:59], v[98:99]
	v_pk_mul_f32 v[104:105], v[64:65], v[104:105]
	v_pk_mul_f32 v[102:103], v[62:63], v[102:103]
	s_waitcnt lgkmcnt(0)
	v_add_f32_e32 v98, v110, v111
	ds_bpermute_b32 v99, v195, v98
	v_pk_mul_f32 v[106:107], v[60:61], v[100:101]
	v_cvt_pk_bf16_f32 v100, v102, v103
	v_cvt_pk_bf16_f32 v101, v104, v105
	v_cvt_pk_bf16_f32 v102, v108, v109
	v_cvt_pk_bf16_f32 v103, v106, v107
	global_store_dwordx4 v[128:129], v[100:103], off offset:256
	s_and_saveexec_b64 s[34:35], s[38:39]
	s_cbranch_execz .LBB0_942
;     __device__ __forceinline__ void operator()(const f32x4 (&acc)[2][2][4][2], const pg8::Unit& u, int wr, int wc, int fr, int fq) const {
;     ...
;                 ss += __shfl_xor(ss, 16); ss += __shfl_xor(ss, 32);
;                 if (fq == 0) stat[(size_t)R * 16 + u.pn * 4 + wc] = ss;
	v_lshlrev_b64 v[100:101], 6, v[114:115]
	v_lshl_add_u64 v[100:101], s[62:63], 0, v[100:101]
	v_lshl_add_u64 v[100:101], s[24:25], 2, v[100:101]
	s_lshl_b32 s0, s47, 2
	v_lshl_add_u64 v[100:101], v[100:101], 0, s[0:1]
	s_waitcnt lgkmcnt(0)
	v_add_f32_e32 v98, v98, v99
	global_store_dword v[100:101], v98, off

; __device__ __forceinline__ unsigned pk2(float lo, float hi) { return pg8::cvt_pk_bf16(lo, hi); }
;     __device__ __forceinline__ void operator()(const f32x4 (&acc)[2][2][4][2], const pg8::Unit& u, int wr, int wc, int fr, int fq) const {
;     ...
;             for (int m = 0; m < 4; ++m) {
;                 const int R = rowbase + u.pm * 256 + ai * 128 + wr * 64 + m * 16 + fr;
;                 const float* src = islat ? rin_l + (size_t)R * DM : rin_c + (size_t)(R - TL) * DM;
;                 float* dst = islat ? rout_l + (size_t)R * DM : rout_c + (size_t)(R - TL) * DM;
;                 float ss = 0.f;
; #pragma unroll
;                 for (int bj = 0; bj < 2; ++bj) { const int c = u.pn * 256 + bj * 128 + wc * 32 + 8 * fq;
;                     const f32x4 xa = *(const f32x4*)(src + c) + gv[bj][0] * acc[ai][bj][m][0];
;                     const f32x4 xb = *(const f32x4*)(src + c + 4) + gv[bj][1] * acc[ai][bj][m][1];
;                     *(f32x4*)(dst + c) = xa; *(f32x4*)(dst + c + 4) = xb;
;                     ss += (xa[0] * xa[0] + xa[1] * xa[1]) + (xa[2] * xa[2] + xa[3] * xa[3]) + (xb[0] * xb[0] + xb[1] * xb[1]) + (xb[2] * xb[2] + xb[3] * xb[3]);
;                     const f32x4 ya = xa * sv[bj][0], yb = xb * sv[bj][1];
;                     u32x4 w; w.x = pk2(ya[0], ya[1]); w.y = pk2(ya[2], ya[3]); w.z = pk2(yb[0], yb[1]); w.w = pk2(yb[2], yb[3]);
;                     *(u32x4*)(Hn + (size_t)R * DM + c) = w; }
;                 ss += __shfl_xor(ss, 16); ss += __shfl_xor(ss, 32);
;                 if (fq == 0) stat[(size_t)R * 16 + u.pn * 4 + wc] = ss;
;             }
.LBB0_946:
	v_cndmask_b32_e64 v102, v102, v98, s[42:43]
	v_ashrrev_i32_e32 v103, 31, v102
	v_lshlrev_b64 v[102:103], 12, v[102:103]
	v_lshl_add_u64 v[102:103], s[68:69], 0, v[102:103]
	v_lshl_add_u64 v[110:111], v[102:103], 0, v[188:189]
	v_lshl_add_u64 v[226:227], v[110:111], 0, v[242:243]
	global_load_dwordx4 v[214:217], v[226:227], off offset:-4096 nt
	global_load_dwordx4 v[218:221], v[226:227], off nt
	v_lshlrev_b64 v[112:113], 11, v[98:99]
	v_lshl_add_u64 v[114:115], v[100:101], 0, v[188:189]
	v_lshl_add_u64 v[100:101], s[60:61], 0, v[112:113]
	v_lshl_add_u64 v[112:113], v[186:187], 1, v[100:101]
	s_waitcnt vmcnt(0)
	v_cndmask_b32_e64 v222, v218, v214, s[100:101]
	v_cndmask_b32_e64 v223, v219, v215, s[100:101]
	v_cndmask_b32_e64 v224, v220, v216, s[100:101]
	v_cndmask_b32_e64 v225, v221, v217, s[100:101]
	v_mov_b32_dpp v238, v222 quad_perm:[1,0,3,2] row_mask:0xf bank_mask:0xf
	v_mov_b32_dpp v239, v223 quad_perm:[1,0,3,2] row_mask:0xf bank_mask:0xf
	v_mov_b32_dpp v240, v224 quad_perm:[1,0,3,2] row_mask:0xf bank_mask:0xf
	v_mov_b32_dpp v241, v225 quad_perm:[1,0,3,2] row_mask:0xf bank_mask:0xf
	v_cndmask_b32_e64 v102, v214, v238, s[100:101]
	v_cndmask_b32_e64 v106, v238, v218, s[100:101]
	v_cndmask_b32_e64 v103, v215, v239, s[100:101]
	v_cndmask_b32_e64 v107, v239, v219, s[100:101]
	v_cndmask_b32_e64 v104, v216, v240, s[100:101]
	v_cndmask_b32_e64 v108, v240, v220, s[100:101]
	v_cndmask_b32_e64 v105, v217, v241, s[100:101]
	v_cndmask_b32_e64 v109, v241, v221, s[100:101]
	v_pk_fma_f32 v[72:73], v[72:73], v[96:97], v[104:105]
	v_pk_fma_f32 v[70:71], v[70:71], v[94:95], v[102:103]
	s_waitcnt vmcnt(0)
	v_pk_fma_f32 v[68:69], v[68:69], v[88:89], v[108:109]
	v_pk_fma_f32 v[66:67], v[66:67], v[86:87], v[106:107]
	v_pk_mul_f32 v[102:103], v[92:93], v[72:73]
	v_pk_mul_f32 v[100:101], v[90:91], v[70:71]
	v_pk_mul_f32 v[104:105], v[84:85], v[68:69]
	v_pk_mul_f32 v[106:107], v[82:83], v[66:67]
	v_cvt_pk_bf16_f32 v100, v100, v101
	v_cvt_pk_bf16_f32 v101, v102, v103
	v_cvt_pk_bf16_f32 v102, v106, v107
	v_cvt_pk_bf16_f32 v103, v104, v105
	v_cndmask_b32_e64 v222, v66, v70, s[100:101]
	v_cndmask_b32_e64 v223, v67, v71, s[100:101]
	v_cndmask_b32_e64 v224, v68, v72, s[100:101]
	v_cndmask_b32_e64 v225, v69, v73, s[100:101]
	v_mov_b32_dpp v238, v222 quad_perm:[1,0,3,2] row_mask:0xf bank_mask:0xf
	v_mov_b32_dpp v239, v223 quad_perm:[1,0,3,2] row_mask:0xf bank_mask:0xf
	v_mov_b32_dpp v240, v224 quad_perm:[1,0,3,2] row_mask:0xf bank_mask:0xf
	v_mov_b32_dpp v241, v225 quad_perm:[1,0,3,2] row_mask:0xf bank_mask:0xf
	v_cndmask_b32_e64 v214, v70, v238, s[100:101]
	v_cndmask_b32_e64 v218, v238, v66, s[100:101]
	v_cndmask_b32_e64 v215, v71, v239, s[100:101]
	v_cndmask_b32_e64 v219, v239, v67, s[100:101]
	v_cndmask_b32_e64 v216, v72, v240, s[100:101]
	v_cndmask_b32_e64 v220, v240, v68, s[100:101]
	v_cndmask_b32_e64 v217, v73, v241, s[100:101]
	v_cndmask_b32_e64 v221, v241, v69, s[100:101]
	v_lshl_add_u64 v[226:227], v[114:115], 0, v[242:243]
	global_store_dwordx4 v[226:227], v[214:217], off offset:-4096
	global_store_dwordx4 v[226:227], v[218:221], off
	global_store_dwordx4 v[112:113], v[100:103], off
	v_lshl_add_u64 v[226:227], v[110:111], 0, v[242:243]
	global_load_dwordx4 v[214:217], v[226:227], off offset:-3584 nt
	global_load_dwordx4 v[218:221], v[226:227], off offset:512 nt
	s_nop 0
	v_mul_f32_e32 v71, v71, v71
	v_mul_f32_e32 v73, v73, v73
	v_mul_f32_e32 v67, v67, v67
	v_fmac_f32_e32 v71, v70, v70
	v_fmac_f32_e32 v73, v72, v72
	v_mul_f32_e32 v69, v69, v69
	v_fmac_f32_e32 v67, v66, v66
	v_add_f32_e32 v66, v71, v73
	v_fmac_f32_e32 v69, v68, v68
	v_add_f32_e32 v66, v66, v67
	v_add_f32_e32 v66, v69, v66
	s_waitcnt vmcnt(0)
	v_cndmask_b32_e64 v222, v218, v214, s[100:101]
	v_cndmask_b32_e64 v223, v219, v215, s[100:101]
	v_cndmask_b32_e64 v224, v220, v216, s[100:101]
	v_cndmask_b32_e64 v225, v221, v217, s[100:101]
	v_mov_b32_dpp v238, v222 quad_perm:[1,0,3,2] row_mask:0xf bank_mask:0xf
	v_mov_b32_dpp v239, v223 quad_perm:[1,0,3,2] row_mask:0xf bank_mask:0xf
	v_mov_b32_dpp v240, v224 quad_perm:[1,0,3,2] row_mask:0xf bank_mask:0xf
	v_mov_b32_dpp v241, v225 quad_perm:[1,0,3,2] row_mask:0xf bank_mask:0xf
	v_cndmask_b32_e64 v100, v214, v238, s[100:101]
	v_cndmask_b32_e64 v104, v238, v218, s[100:101]
	v_cndmask_b32_e64 v101, v215, v239, s[100:101]
	v_cndmask_b32_e64 v105, v239, v219, s[100:101]
	v_cndmask_b32_e64 v102, v216, v240, s[100:101]
	v_cndmask_b32_e64 v106, v240, v220, s[100:101]
	v_cndmask_b32_e64 v103, v217, v241, s[100:101]
	v_cndmask_b32_e64 v107, v241, v221, s[100:101]
	v_pk_fma_f32 v[56:57], v[56:57], v[80:81], v[102:103]
	v_pk_fma_f32 v[54:55], v[54:55], v[78:79], v[100:101]
	s_waitcnt vmcnt(0)
	v_pk_fma_f32 v[50:51], v[50:51], v[74:75], v[104:105]
	v_mul_f32_e32 v67, v55, v55
	v_mul_f32_e32 v68, v57, v57
	v_pk_fma_f32 v[52:53], v[52:53], v[76:77], v[106:107]
	v_mul_f32_e32 v69, v51, v51
	v_fmac_f32_e32 v67, v54, v54
	v_fmac_f32_e32 v68, v56, v56
	v_mul_f32_e32 v70, v53, v53
	v_fmac_f32_e32 v69, v50, v50
	v_add_f32_e32 v67, v67, v68
	v_fmac_f32_e32 v70, v52, v52
	v_add_f32_e32 v67, v67, v69
	v_add_f32_e32 v67, v70, v67
	v_add_f32_e32 v70, v66, v67
	ds_bpermute_b32 v71, v200, v70
	v_cndmask_b32_e64 v222, v50, v54, s[100:101]
	v_cndmask_b32_e64 v223, v51, v55, s[100:101]
	v_cndmask_b32_e64 v224, v52, v56, s[100:101]
	v_cndmask_b32_e64 v225, v53, v57, s[100:101]
	v_mov_b32_dpp v238, v222 quad_perm:[1,0,3,2] row_mask:0xf bank_mask:0xf
	v_mov_b32_dpp v239, v223 quad_perm:[1,0,3,2] row_mask:0xf bank_mask:0xf
	v_mov_b32_dpp v240, v224 quad_perm:[1,0,3,2] row_mask:0xf bank_mask:0xf
	v_mov_b32_dpp v241, v225 quad_perm:[1,0,3,2] row_mask:0xf bank_mask:0xf
	v_cndmask_b32_e64 v214, v54, v238, s[100:101]
	v_cndmask_b32_e64 v218, v238, v50, s[100:101]
	v_cndmask_b32_e64 v215, v55, v239, s[100:101]
	v_cndmask_b32_e64 v219, v239, v51, s[100:101]
	v_cndmask_b32_e64 v216, v56, v240, s[100:101]
	v_cndmask_b32_e64 v220, v240, v52, s[100:101]
	v_cndmask_b32_e64 v217, v57, v241, s[100:101]
	v_cndmask_b32_e64 v221, v241, v53, s[100:101]
	v_lshl_add_u64 v[226:227], v[114:115], 0, v[242:243]
	global_store_dwordx4 v[226:227], v[214:217], off offset:-3584
	global_store_dwordx4 v[226:227], v[218:221], off offset:512
	v_pk_mul_f32 v[68:69], v[58:59], v[50:51]
	v_pk_mul_f32 v[56:57], v[64:65], v[56:57]
	v_pk_mul_f32 v[54:55], v[62:63], v[54:55]
	s_waitcnt lgkmcnt(0)
	v_add_f32_e32 v50, v70, v71
	ds_bpermute_b32 v51, v195, v50
	v_pk_mul_f32 v[66:67], v[60:61], v[52:53]
	v_cvt_pk_bf16_f32 v52, v54, v55
	v_cvt_pk_bf16_f32 v53, v56, v57
	v_cvt_pk_bf16_f32 v54, v68, v69
	v_cvt_pk_bf16_f32 v55, v66, v67
	global_store_dwordx4 v[112:113], v[52:55], off offset:256
	s_and_saveexec_b64 s[34:35], s[38:39]
	s_cbranch_execz .LBB0_948
	v_lshlrev_b64 v[52:53], 6, v[98:99]
	v_lshl_add_u64 v[52:53], s[62:63], 0, v[52:53]
	v_lshl_add_u64 v[52:53], s[24:25], 2, v[52:53]
	s_lshl_b32 s0, s47, 2
	v_lshl_add_u64 v[52:53], v[52:53], 0, s[0:1]
	s_waitcnt lgkmcnt(0)
	v_add_f32_e32 v50, v50, v51
	global_store_dword v[52:53], v50, off

; __device__ __forceinline__ unsigned pk2(float lo, float hi) { return pg8::cvt_pk_bf16(lo, hi); }
;     __device__ __forceinline__ void operator()(const f32x4 (&acc)[2][2][4][2], const pg8::Unit& u, int wr, int wc, int fr, int fq) const {
;     ...
;             for (int m = 0; m < 4; ++m) {
;                 const int R = rowbase + u.pm * 256 + ai * 128 + wr * 64 + m * 16 + fr;
;                 const float* src = islat ? rin_l + (size_t)R * DM : rin_c + (size_t)(R - TL) * DM;
;                 float* dst = islat ? rout_l + (size_t)R * DM : rout_c + (size_t)(R - TL) * DM;
;                 float ss = 0.f;
; #pragma unroll
;                 for (int bj = 0; bj < 2; ++bj) { const int c = u.pn * 256 + bj * 128 + wc * 32 + 8 * fq;
;                     const f32x4 xa = *(const f32x4*)(src + c) + gv[bj][0] * acc[ai][bj][m][0];
;                     const f32x4 xb = *(const f32x4*)(src + c + 4) + gv[bj][1] * acc[ai][bj][m][1];
;                     *(f32x4*)(dst + c) = xa; *(f32x4*)(dst + c + 4) = xb;
;                     ss += (xa[0] * xa[0] + xa[1] * xa[1]) + (xa[2] * xa[2] + xa[3] * xa[3]) + (xb[0] * xb[0] + xb[1] * xb[1]) + (xb[2] * xb[2] + xb[3] * xb[3]);
;                     const f32x4 ya = xa * sv[bj][0], yb = xb * sv[bj][1];
;                     u32x4 w; w.x = pk2(ya[0], ya[1]); w.y = pk2(ya[2], ya[3]); w.z = pk2(yb[0], yb[1]); w.w = pk2(yb[2], yb[3]);
;                     *(u32x4*)(Hn + (size_t)R * DM + c) = w; }
;                 ss += __shfl_xor(ss, 16); ss += __shfl_xor(ss, 32);
;                 if (fq == 0) stat[(size_t)R * 16 + u.pn * 4 + wc] = ss;
;             }
.LBB0_952:
	v_cndmask_b32_e64 v54, v54, v50, s[42:43]
	v_ashrrev_i32_e32 v55, 31, v54
	v_lshlrev_b64 v[54:55], 12, v[54:55]
	v_lshl_add_u64 v[54:55], s[68:69], 0, v[54:55]
	v_lshl_add_u64 v[70:71], v[54:55], 0, v[188:189]
	v_lshl_add_u64 v[226:227], v[70:71], 0, v[242:243]
	global_load_dwordx4 v[214:217], v[226:227], off offset:-4096 nt
	global_load_dwordx4 v[218:221], v[226:227], off nt
	v_lshlrev_b64 v[72:73], 11, v[50:51]
	v_lshl_add_u64 v[98:99], v[52:53], 0, v[188:189]
	v_lshl_add_u64 v[52:53], s[60:61], 0, v[72:73]
	v_lshl_add_u64 v[72:73], v[186:187], 1, v[52:53]
	s_waitcnt vmcnt(0)
	v_cndmask_b32_e64 v222, v218, v214, s[100:101]
	v_cndmask_b32_e64 v223, v219, v215, s[100:101]
	v_cndmask_b32_e64 v224, v220, v216, s[100:101]
	v_cndmask_b32_e64 v225, v221, v217, s[100:101]
	v_mov_b32_dpp v238, v222 quad_perm:[1,0,3,2] row_mask:0xf bank_mask:0xf
	v_mov_b32_dpp v239, v223 quad_perm:[1,0,3,2] row_mask:0xf bank_mask:0xf
	v_mov_b32_dpp v240, v224 quad_perm:[1,0,3,2] row_mask:0xf bank_mask:0xf
	v_mov_b32_dpp v241, v225 quad_perm:[1,0,3,2] row_mask:0xf bank_mask:0xf
	v_cndmask_b32_e64 v54, v214, v238, s[100:101]
	v_cndmask_b32_e64 v66, v238, v218, s[100:101]
	v_cndmask_b32_e64 v55, v215, v239, s[100:101]
	v_cndmask_b32_e64 v67, v239, v219, s[100:101]
	v_cndmask_b32_e64 v56, v216, v240, s[100:101]
	v_cndmask_b32_e64 v68, v240, v220, s[100:101]
	v_cndmask_b32_e64 v57, v217, v241, s[100:101]
	v_cndmask_b32_e64 v69, v241, v221, s[100:101]
	v_pk_fma_f32 v[48:49], v[48:49], v[96:97], v[56:57]
	v_pk_fma_f32 v[46:47], v[46:47], v[94:95], v[54:55]
	s_waitcnt vmcnt(0)
	v_pk_fma_f32 v[44:45], v[44:45], v[88:89], v[68:69]
	v_pk_fma_f32 v[42:43], v[42:43], v[86:87], v[66:67]
	v_pk_mul_f32 v[54:55], v[92:93], v[48:49]
	v_pk_mul_f32 v[52:53], v[90:91], v[46:47]
	v_pk_mul_f32 v[56:57], v[84:85], v[44:45]
	v_pk_mul_f32 v[66:67], v[82:83], v[42:43]
	v_cvt_pk_bf16_f32 v52, v52, v53
	v_cvt_pk_bf16_f32 v53, v54, v55
	v_cvt_pk_bf16_f32 v54, v66, v67
	v_cvt_pk_bf16_f32 v55, v56, v57
	v_cndmask_b32_e64 v222, v42, v46, s[100:101]
	v_cndmask_b32_e64 v223, v43, v47, s[100:101]
	v_cndmask_b32_e64 v224, v44, v48, s[100:101]
	v_cndmask_b32_e64 v225, v45, v49, s[100:101]
	v_mov_b32_dpp v238, v222 quad_perm:[1,0,3,2] row_mask:0xf bank_mask:0xf
	v_mov_b32_dpp v239, v223 quad_perm:[1,0,3,2] row_mask:0xf bank_mask:0xf
	v_mov_b32_dpp v240, v224 quad_perm:[1,0,3,2] row_mask:0xf bank_mask:0xf
	v_mov_b32_dpp v241, v225 quad_perm:[1,0,3,2] row_mask:0xf bank_mask:0xf
	v_cndmask_b32_e64 v214, v46, v238, s[100:101]
	v_cndmask_b32_e64 v218, v238, v42, s[100:101]
	v_cndmask_b32_e64 v215, v47, v239, s[100:101]
	v_cndmask_b32_e64 v219, v239, v43, s[100:101]
	v_cndmask_b32_e64 v216, v48, v240, s[100:101]
	v_cndmask_b32_e64 v220, v240, v44, s[100:101]
	v_cndmask_b32_e64 v217, v49, v241, s[100:101]
	v_cndmask_b32_e64 v221, v241, v45, s[100:101]
	v_lshl_add_u64 v[226:227], v[98:99], 0, v[242:243]
	global_store_dwordx4 v[226:227], v[214:217], off offset:-4096
	global_store_dwordx4 v[226:227], v[218:221], off
	global_store_dwordx4 v[72:73], v[52:55], off
	v_lshl_add_u64 v[226:227], v[70:71], 0, v[242:243]
	global_load_dwordx4 v[214:217], v[226:227], off offset:-3584 nt
	global_load_dwordx4 v[218:221], v[226:227], off offset:512 nt
	s_nop 0
	v_mul_f32_e32 v47, v47, v47
	v_mul_f32_e32 v49, v49, v49
	v_mul_f32_e32 v43, v43, v43
	v_fmac_f32_e32 v47, v46, v46
	v_fmac_f32_e32 v49, v48, v48
	v_mul_f32_e32 v45, v45, v45
	v_fmac_f32_e32 v43, v42, v42
	v_add_f32_e32 v42, v47, v49
	v_fmac_f32_e32 v45, v44, v44
	v_add_f32_e32 v42, v42, v43
	v_add_f32_e32 v42, v45, v42
	s_waitcnt vmcnt(0)
	v_cndmask_b32_e64 v222, v218, v214, s[100:101]
	v_cndmask_b32_e64 v223, v219, v215, s[100:101]
	v_cndmask_b32_e64 v224, v220, v216, s[100:101]
	v_cndmask_b32_e64 v225, v221, v217, s[100:101]
	v_mov_b32_dpp v238, v222 quad_perm:[1,0,3,2] row_mask:0xf bank_mask:0xf
	v_mov_b32_dpp v239, v223 quad_perm:[1,0,3,2] row_mask:0xf bank_mask:0xf
	v_mov_b32_dpp v240, v224 quad_perm:[1,0,3,2] row_mask:0xf bank_mask:0xf
	v_mov_b32_dpp v241, v225 quad_perm:[1,0,3,2] row_mask:0xf bank_mask:0xf
	v_cndmask_b32_e64 v52, v214, v238, s[100:101]
	v_cndmask_b32_e64 v66, v238, v218, s[100:101]
	v_cndmask_b32_e64 v53, v215, v239, s[100:101]
	v_cndmask_b32_e64 v67, v239, v219, s[100:101]
	v_cndmask_b32_e64 v54, v216, v240, s[100:101]
	v_cndmask_b32_e64 v68, v240, v220, s[100:101]
	v_cndmask_b32_e64 v55, v217, v241, s[100:101]
	v_cndmask_b32_e64 v69, v241, v221, s[100:101]
	v_pk_fma_f32 v[40:41], v[40:41], v[80:81], v[54:55]
	v_pk_fma_f32 v[38:39], v[38:39], v[78:79], v[52:53]
	s_waitcnt vmcnt(0)
	v_pk_fma_f32 v[34:35], v[34:35], v[74:75], v[66:67]
	v_mul_f32_e32 v43, v39, v39
	v_mul_f32_e32 v44, v41, v41
	v_pk_fma_f32 v[36:37], v[36:37], v[76:77], v[68:69]
	v_mul_f32_e32 v45, v35, v35
	v_fmac_f32_e32 v43, v38, v38
	v_fmac_f32_e32 v44, v40, v40
	v_mul_f32_e32 v46, v37, v37
	v_fmac_f32_e32 v45, v34, v34
	v_add_f32_e32 v43, v43, v44
	v_fmac_f32_e32 v46, v36, v36
	v_add_f32_e32 v43, v43, v45
	v_add_f32_e32 v43, v46, v43
	v_add_f32_e32 v46, v42, v43
	ds_bpermute_b32 v47, v200, v46
	v_cndmask_b32_e64 v222, v34, v38, s[100:101]
	v_cndmask_b32_e64 v223, v35, v39, s[100:101]
	v_cndmask_b32_e64 v224, v36, v40, s[100:101]
	v_cndmask_b32_e64 v225, v37, v41, s[100:101]
	v_mov_b32_dpp v238, v222 quad_perm:[1,0,3,2] row_mask:0xf bank_mask:0xf
	v_mov_b32_dpp v239, v223 quad_perm:[1,0,3,2] row_mask:0xf bank_mask:0xf
	v_mov_b32_dpp v240, v224 quad_perm:[1,0,3,2] row_mask:0xf bank_mask:0xf
	v_mov_b32_dpp v241, v225 quad_perm:[1,0,3,2] row_mask:0xf bank_mask:0xf
	v_cndmask_b32_e64 v214, v38, v238, s[100:101]
	v_cndmask_b32_e64 v218, v238, v34, s[100:101]
	v_cndmask_b32_e64 v215, v39, v239, s[100:101]
	v_cndmask_b32_e64 v219, v239, v35, s[100:101]
	v_cndmask_b32_e64 v216, v40, v240, s[100:101]
	v_cndmask_b32_e64 v220, v240, v36, s[100:101]
	v_cndmask_b32_e64 v217, v41, v241, s[100:101]
	v_cndmask_b32_e64 v221, v241, v37, s[100:101]
	v_lshl_add_u64 v[226:227], v[98:99], 0, v[242:243]
	global_store_dwordx4 v[226:227], v[214:217], off offset:-3584
	global_store_dwordx4 v[226:227], v[218:221], off offset:512
	v_pk_mul_f32 v[44:45], v[58:59], v[34:35]
	v_pk_mul_f32 v[40:41], v[64:65], v[40:41]
	v_pk_mul_f32 v[38:39], v[62:63], v[38:39]
	s_waitcnt lgkmcnt(0)
	v_add_f32_e32 v34, v46, v47
	ds_bpermute_b32 v35, v195, v34
	v_pk_mul_f32 v[42:43], v[60:61], v[36:37]
	v_cvt_pk_bf16_f32 v36, v38, v39
	v_cvt_pk_bf16_f32 v37, v40, v41
	v_cvt_pk_bf16_f32 v38, v44, v45
	v_cvt_pk_bf16_f32 v39, v42, v43
	global_store_dwordx4 v[72:73], v[36:39], off offset:256
	s_and_saveexec_b64 s[34:35], s[38:39]
	s_cbranch_execz .LBB0_954
	v_lshlrev_b64 v[36:37], 6, v[50:51]
	v_lshl_add_u64 v[36:37], s[62:63], 0, v[36:37]
	v_lshl_add_u64 v[36:37], s[24:25], 2, v[36:37]
	s_lshl_b32 s0, s47, 2
	v_lshl_add_u64 v[36:37], v[36:37], 0, s[0:1]
	s_waitcnt lgkmcnt(0)
	v_add_f32_e32 v34, v34, v35
	global_store_dword v[36:37], v34, off

; __device__ __forceinline__ unsigned pk2(float lo, float hi) { return pg8::cvt_pk_bf16(lo, hi); }
;     __device__ __forceinline__ void operator()(const f32x4 (&acc)[2][2][4][2], const pg8::Unit& u, int wr, int wc, int fr, int fq) const {
;     ...
;                 const int R = rowbase + u.pm * 256 + ai * 128 + wr * 64 + m * 16 + fr;
;                 const float* src = islat ? rin_l + (size_t)R * DM : rin_c + (size_t)(R - TL) * DM;
;                 float* dst = islat ? rout_l + (size_t)R * DM : rout_c + (size_t)(R - TL) * DM;
;                 float ss = 0.f;
; #pragma unroll
;                 for (int bj = 0; bj < 2; ++bj) { const int c = u.pn * 256 + bj * 128 + wc * 32 + 8 * fq;
;                     const f32x4 xa = *(const f32x4*)(src + c) + gv[bj][0] * acc[ai][bj][m][0];
;                     const f32x4 xb = *(const f32x4*)(src + c + 4) + gv[bj][1] * acc[ai][bj][m][1];
;                     *(f32x4*)(dst + c) = xa; *(f32x4*)(dst + c + 4) = xb;
;                     ss += (xa[0] * xa[0] + xa[1] * xa[1]) + (xa[2] * xa[2] + xa[3] * xa[3]) + (xb[0] * xb[0] + xb[1] * xb[1]) + (xb[2] * xb[2] + xb[3] * xb[3]);
;                     const f32x4 ya = xa * sv[bj][0], yb = xb * sv[bj][1];
;                     u32x4 w; w.x = pk2(ya[0], ya[1]); w.y = pk2(ya[2], ya[3]); w.z = pk2(yb[0], yb[1]); w.w = pk2(yb[2], yb[3]);
;                     *(u32x4*)(Hn + (size_t)R * DM + c) = w; }
;                 ss += __shfl_xor(ss, 16); ss += __shfl_xor(ss, 32);
;                 if (fq == 0) stat[(size_t)R * 16 + u.pn * 4 + wc] = ss;
.LBB0_958:
	v_cndmask_b32_e64 v38, v38, v34, s[42:43]
	v_ashrrev_i32_e32 v39, 31, v38
	v_lshlrev_b64 v[38:39], 12, v[38:39]
	v_lshl_add_u64 v[38:39], s[68:69], 0, v[38:39]
	v_lshl_add_u64 v[46:47], v[38:39], 0, v[188:189]
	v_lshl_add_u64 v[226:227], v[46:47], 0, v[242:243]
	global_load_dwordx4 v[214:217], v[226:227], off offset:-4096 nt
	global_load_dwordx4 v[218:221], v[226:227], off nt
	v_lshlrev_b64 v[48:49], 11, v[34:35]
	v_lshl_add_u64 v[50:51], v[36:37], 0, v[188:189]
	v_lshl_add_u64 v[36:37], s[60:61], 0, v[48:49]
	v_lshl_add_u64 v[48:49], v[186:187], 1, v[36:37]
	s_waitcnt vmcnt(0)
	v_cndmask_b32_e64 v222, v218, v214, s[100:101]
	v_cndmask_b32_e64 v223, v219, v215, s[100:101]
	v_cndmask_b32_e64 v224, v220, v216, s[100:101]
	v_cndmask_b32_e64 v225, v221, v217, s[100:101]
	v_mov_b32_dpp v238, v222 quad_perm:[1,0,3,2] row_mask:0xf bank_mask:0xf
	v_mov_b32_dpp v239, v223 quad_perm:[1,0,3,2] row_mask:0xf bank_mask:0xf
	v_mov_b32_dpp v240, v224 quad_perm:[1,0,3,2] row_mask:0xf bank_mask:0xf
	v_mov_b32_dpp v241, v225 quad_perm:[1,0,3,2] row_mask:0xf bank_mask:0xf
	v_cndmask_b32_e64 v38, v214, v238, s[100:101]
	v_cndmask_b32_e64 v42, v238, v218, s[100:101]
	v_cndmask_b32_e64 v39, v215, v239, s[100:101]
	v_cndmask_b32_e64 v43, v239, v219, s[100:101]
	v_cndmask_b32_e64 v40, v216, v240, s[100:101]
	v_cndmask_b32_e64 v44, v240, v220, s[100:101]
	v_cndmask_b32_e64 v41, v217, v241, s[100:101]
	v_cndmask_b32_e64 v45, v241, v221, s[100:101]
	v_pk_fma_f32 v[32:33], v[32:33], v[96:97], v[40:41]
	v_pk_fma_f32 v[30:31], v[30:31], v[94:95], v[38:39]
	s_waitcnt vmcnt(0)
	v_pk_fma_f32 v[28:29], v[28:29], v[88:89], v[44:45]
	v_pk_fma_f32 v[26:27], v[26:27], v[86:87], v[42:43]
	v_pk_mul_f32 v[38:39], v[92:93], v[32:33]
	v_pk_mul_f32 v[36:37], v[90:91], v[30:31]
	v_pk_mul_f32 v[40:41], v[84:85], v[28:29]
	v_pk_mul_f32 v[42:43], v[82:83], v[26:27]
	v_cvt_pk_bf16_f32 v36, v36, v37
	v_cvt_pk_bf16_f32 v37, v38, v39
	v_cvt_pk_bf16_f32 v38, v42, v43
	v_cvt_pk_bf16_f32 v39, v40, v41
	v_cndmask_b32_e64 v222, v26, v30, s[100:101]
	v_cndmask_b32_e64 v223, v27, v31, s[100:101]
	v_cndmask_b32_e64 v224, v28, v32, s[100:101]
	v_cndmask_b32_e64 v225, v29, v33, s[100:101]
	v_mov_b32_dpp v238, v222 quad_perm:[1,0,3,2] row_mask:0xf bank_mask:0xf
	v_mov_b32_dpp v239, v223 quad_perm:[1,0,3,2] row_mask:0xf bank_mask:0xf
	v_mov_b32_dpp v240, v224 quad_perm:[1,0,3,2] row_mask:0xf bank_mask:0xf
	v_mov_b32_dpp v241, v225 quad_perm:[1,0,3,2] row_mask:0xf bank_mask:0xf
	v_cndmask_b32_e64 v214, v30, v238, s[100:101]
	v_cndmask_b32_e64 v218, v238, v26, s[100:101]
	v_cndmask_b32_e64 v215, v31, v239, s[100:101]
	v_cndmask_b32_e64 v219, v239, v27, s[100:101]
	v_cndmask_b32_e64 v216, v32, v240, s[100:101]
	v_cndmask_b32_e64 v220, v240, v28, s[100:101]
	v_cndmask_b32_e64 v217, v33, v241, s[100:101]
	v_cndmask_b32_e64 v221, v241, v29, s[100:101]
	v_lshl_add_u64 v[226:227], v[50:51], 0, v[242:243]
	global_store_dwordx4 v[226:227], v[214:217], off offset:-4096
	global_store_dwordx4 v[226:227], v[218:221], off
	global_store_dwordx4 v[48:49], v[36:39], off
	v_lshl_add_u64 v[226:227], v[46:47], 0, v[242:243]
	global_load_dwordx4 v[214:217], v[226:227], off offset:-3584 nt
	global_load_dwordx4 v[218:221], v[226:227], off offset:512 nt
	s_nop 0
	v_mul_f32_e32 v31, v31, v31
	v_mul_f32_e32 v33, v33, v33
	v_mul_f32_e32 v27, v27, v27
	v_fmac_f32_e32 v31, v30, v30
	v_fmac_f32_e32 v33, v32, v32
	v_mul_f32_e32 v29, v29, v29
	v_fmac_f32_e32 v27, v26, v26
	v_add_f32_e32 v26, v31, v33
	v_fmac_f32_e32 v29, v28, v28
	v_add_f32_e32 v26, v26, v27
	v_add_f32_e32 v26, v29, v26
	s_waitcnt vmcnt(0)
	v_cndmask_b32_e64 v222, v218, v214, s[100:101]
	v_cndmask_b32_e64 v223, v219, v215, s[100:101]
	v_cndmask_b32_e64 v224, v220, v216, s[100:101]
	v_cndmask_b32_e64 v225, v221, v217, s[100:101]
	v_mov_b32_dpp v238, v222 quad_perm:[1,0,3,2] row_mask:0xf bank_mask:0xf
	v_mov_b32_dpp v239, v223 quad_perm:[1,0,3,2] row_mask:0xf bank_mask:0xf
	v_mov_b32_dpp v240, v224 quad_perm:[1,0,3,2] row_mask:0xf bank_mask:0xf
	v_mov_b32_dpp v241, v225 quad_perm:[1,0,3,2] row_mask:0xf bank_mask:0xf
	v_cndmask_b32_e64 v36, v214, v238, s[100:101]
	v_cndmask_b32_e64 v40, v238, v218, s[100:101]
	v_cndmask_b32_e64 v37, v215, v239, s[100:101]
	v_cndmask_b32_e64 v41, v239, v219, s[100:101]
	v_cndmask_b32_e64 v38, v216, v240, s[100:101]
	v_cndmask_b32_e64 v42, v240, v220, s[100:101]
	v_cndmask_b32_e64 v39, v217, v241, s[100:101]
	v_cndmask_b32_e64 v43, v241, v221, s[100:101]
	v_pk_fma_f32 v[24:25], v[24:25], v[80:81], v[38:39]
	v_pk_fma_f32 v[22:23], v[22:23], v[78:79], v[36:37]
	s_waitcnt vmcnt(0)
	v_pk_fma_f32 v[18:19], v[18:19], v[74:75], v[40:41]
	v_mul_f32_e32 v27, v23, v23
	v_mul_f32_e32 v28, v25, v25
	v_pk_fma_f32 v[20:21], v[20:21], v[76:77], v[42:43]
	v_mul_f32_e32 v29, v19, v19
	v_fmac_f32_e32 v27, v22, v22
	v_fmac_f32_e32 v28, v24, v24
	v_mul_f32_e32 v30, v21, v21
	v_fmac_f32_e32 v29, v18, v18
	v_add_f32_e32 v27, v27, v28
	v_fmac_f32_e32 v30, v20, v20
	v_add_f32_e32 v27, v27, v29
	v_add_f32_e32 v27, v30, v27
	v_add_f32_e32 v30, v26, v27
	ds_bpermute_b32 v31, v200, v30
	v_cndmask_b32_e64 v222, v18, v22, s[100:101]
	v_cndmask_b32_e64 v223, v19, v23, s[100:101]
	v_cndmask_b32_e64 v224, v20, v24, s[100:101]
	v_cndmask_b32_e64 v225, v21, v25, s[100:101]
	v_mov_b32_dpp v238, v222 quad_perm:[1,0,3,2] row_mask:0xf bank_mask:0xf
	v_mov_b32_dpp v239, v223 quad_perm:[1,0,3,2] row_mask:0xf bank_mask:0xf
	v_mov_b32_dpp v240, v224 quad_perm:[1,0,3,2] row_mask:0xf bank_mask:0xf
	v_mov_b32_dpp v241, v225 quad_perm:[1,0,3,2] row_mask:0xf bank_mask:0xf
	v_cndmask_b32_e64 v214, v22, v238, s[100:101]
	v_cndmask_b32_e64 v218, v238, v18, s[100:101]
	v_cndmask_b32_e64 v215, v23, v239, s[100:101]
	v_cndmask_b32_e64 v219, v239, v19, s[100:101]
	v_cndmask_b32_e64 v216, v24, v240, s[100:101]
	v_cndmask_b32_e64 v220, v240, v20, s[100:101]
	v_cndmask_b32_e64 v217, v25, v241, s[100:101]
	v_cndmask_b32_e64 v221, v241, v21, s[100:101]
	v_lshl_add_u64 v[226:227], v[50:51], 0, v[242:243]
	global_store_dwordx4 v[226:227], v[214:217], off offset:-3584
	global_store_dwordx4 v[226:227], v[218:221], off offset:512
	v_pk_mul_f32 v[28:29], v[58:59], v[18:19]
	v_pk_mul_f32 v[24:25], v[64:65], v[24:25]
	v_pk_mul_f32 v[22:23], v[62:63], v[22:23]
	s_waitcnt lgkmcnt(0)
	v_add_f32_e32 v18, v30, v31
	ds_bpermute_b32 v19, v195, v18
	v_pk_mul_f32 v[26:27], v[60:61], v[20:21]
	v_cvt_pk_bf16_f32 v20, v22, v23
	v_cvt_pk_bf16_f32 v21, v24, v25
	v_cvt_pk_bf16_f32 v22, v28, v29
	v_cvt_pk_bf16_f32 v23, v26, v27
	global_store_dwordx4 v[48:49], v[20:23], off offset:256
	s_and_saveexec_b64 s[34:35], s[38:39]
	s_cbranch_execz .LBB0_960
	v_lshlrev_b64 v[20:21], 6, v[34:35]
	v_lshl_add_u64 v[20:21], s[62:63], 0, v[20:21]
	v_lshl_add_u64 v[20:21], s[24:25], 2, v[20:21]
	s_lshl_b32 s0, s47, 2
	v_lshl_add_u64 v[20:21], v[20:21], 0, s[0:1]
	s_waitcnt lgkmcnt(0)
	v_add_f32_e32 v18, v18, v19
	global_store_dword v[20:21], v18, off

; __device__ __forceinline__ unsigned pk2(float lo, float hi) { return pg8::cvt_pk_bf16(lo, hi); }
;     __device__ __forceinline__ void operator()(const f32x4 (&acc)[2][2][4][2], const pg8::Unit& u, int wr, int wc, int fr, int fq) const {
;     ...
;                 const int R = rowbase + u.pm * 256 + ai * 128 + wr * 64 + m * 16 + fr;
;                 const float* src = islat ? rin_l + (size_t)R * DM : rin_c + (size_t)(R - TL) * DM;
;                 float* dst = islat ? rout_l + (size_t)R * DM : rout_c + (size_t)(R - TL) * DM;
;                 float ss = 0.f;
; #pragma unroll
;                 for (int bj = 0; bj < 2; ++bj) { const int c = u.pn * 256 + bj * 128 + wc * 32 + 8 * fq;
;                     const f32x4 xa = *(const f32x4*)(src + c) + gv[bj][0] * acc[ai][bj][m][0];
;                     const f32x4 xb = *(const f32x4*)(src + c + 4) + gv[bj][1] * acc[ai][bj][m][1];
;                     *(f32x4*)(dst + c) = xa; *(f32x4*)(dst + c + 4) = xb;
;                     ss += (xa[0] * xa[0] + xa[1] * xa[1]) + (xa[2] * xa[2] + xa[3] * xa[3]) + (xb[0] * xb[0] + xb[1] * xb[1]) + (xb[2] * xb[2] + xb[3] * xb[3]);
;                     const f32x4 ya = xa * sv[bj][0], yb = xb * sv[bj][1];
;                     u32x4 w; w.x = pk2(ya[0], ya[1]); w.y = pk2(ya[2], ya[3]); w.z = pk2(yb[0], yb[1]); w.w = pk2(yb[2], yb[3]);
;                     *(u32x4*)(Hn + (size_t)R * DM + c) = w; }
;                 ss += __shfl_xor(ss, 16); ss += __shfl_xor(ss, 32);
;                 if (fq == 0) stat[(size_t)R * 16 + u.pn * 4 + wc] = ss;
.LBB0_964:
	v_cndmask_b32_e64 v22, v22, v18, s[42:43]
	v_ashrrev_i32_e32 v23, 31, v22
	v_lshlrev_b64 v[22:23], 12, v[22:23]
	v_lshl_add_u64 v[22:23], s[68:69], 0, v[22:23]
	v_lshl_add_u64 v[30:31], v[22:23], 0, v[188:189]
	v_lshl_add_u64 v[226:227], v[30:31], 0, v[242:243]
	global_load_dwordx4 v[214:217], v[226:227], off offset:-4096 nt
	global_load_dwordx4 v[218:221], v[226:227], off nt
	v_lshlrev_b64 v[32:33], 11, v[18:19]
	v_lshl_add_u64 v[34:35], v[20:21], 0, v[188:189]
	v_lshl_add_u64 v[20:21], s[60:61], 0, v[32:33]
	v_lshl_add_u64 v[32:33], v[186:187], 1, v[20:21]
	s_waitcnt vmcnt(0)
	v_cndmask_b32_e64 v222, v218, v214, s[100:101]
	v_cndmask_b32_e64 v223, v219, v215, s[100:101]
	v_cndmask_b32_e64 v224, v220, v216, s[100:101]
	v_cndmask_b32_e64 v225, v221, v217, s[100:101]
	v_mov_b32_dpp v238, v222 quad_perm:[1,0,3,2] row_mask:0xf bank_mask:0xf
	v_mov_b32_dpp v239, v223 quad_perm:[1,0,3,2] row_mask:0xf bank_mask:0xf
	v_mov_b32_dpp v240, v224 quad_perm:[1,0,3,2] row_mask:0xf bank_mask:0xf
	v_mov_b32_dpp v241, v225 quad_perm:[1,0,3,2] row_mask:0xf bank_mask:0xf
	v_cndmask_b32_e64 v22, v214, v238, s[100:101]
	v_cndmask_b32_e64 v26, v238, v218, s[100:101]
	v_cndmask_b32_e64 v23, v215, v239, s[100:101]
	v_cndmask_b32_e64 v27, v239, v219, s[100:101]
	v_cndmask_b32_e64 v24, v216, v240, s[100:101]
	v_cndmask_b32_e64 v28, v240, v220, s[100:101]
	v_cndmask_b32_e64 v25, v217, v241, s[100:101]
	v_cndmask_b32_e64 v29, v241, v221, s[100:101]
	v_pk_fma_f32 v[16:17], v[16:17], v[96:97], v[24:25]
	v_pk_fma_f32 v[14:15], v[14:15], v[94:95], v[22:23]
	s_waitcnt vmcnt(0)
	v_pk_fma_f32 v[12:13], v[12:13], v[88:89], v[28:29]
	v_pk_fma_f32 v[10:11], v[10:11], v[86:87], v[26:27]
	v_pk_mul_f32 v[22:23], v[92:93], v[16:17]
	v_pk_mul_f32 v[20:21], v[90:91], v[14:15]
	v_pk_mul_f32 v[24:25], v[84:85], v[12:13]
	v_pk_mul_f32 v[26:27], v[82:83], v[10:11]
	v_cvt_pk_bf16_f32 v20, v20, v21
	v_cvt_pk_bf16_f32 v21, v22, v23
	v_cvt_pk_bf16_f32 v22, v26, v27
	v_cvt_pk_bf16_f32 v23, v24, v25
	v_cndmask_b32_e64 v222, v10, v14, s[100:101]
	v_cndmask_b32_e64 v223, v11, v15, s[100:101]
	v_cndmask_b32_e64 v224, v12, v16, s[100:101]
	v_cndmask_b32_e64 v225, v13, v17, s[100:101]
	v_mov_b32_dpp v238, v222 quad_perm:[1,0,3,2] row_mask:0xf bank_mask:0xf
	v_mov_b32_dpp v239, v223 quad_perm:[1,0,3,2] row_mask:0xf bank_mask:0xf
	v_mov_b32_dpp v240, v224 quad_perm:[1,0,3,2] row_mask:0xf bank_mask:0xf
	v_mov_b32_dpp v241, v225 quad_perm:[1,0,3,2] row_mask:0xf bank_mask:0xf
	v_cndmask_b32_e64 v214, v14, v238, s[100:101]
	v_cndmask_b32_e64 v218, v238, v10, s[100:101]
	v_cndmask_b32_e64 v215, v15, v239, s[100:101]
	v_cndmask_b32_e64 v219, v239, v11, s[100:101]
	v_cndmask_b32_e64 v216, v16, v240, s[100:101]
	v_cndmask_b32_e64 v220, v240, v12, s[100:101]
	v_cndmask_b32_e64 v217, v17, v241, s[100:101]
	v_cndmask_b32_e64 v221, v241, v13, s[100:101]
	v_lshl_add_u64 v[226:227], v[34:35], 0, v[242:243]
	global_store_dwordx4 v[226:227], v[214:217], off offset:-4096
	global_store_dwordx4 v[226:227], v[218:221], off
	global_store_dwordx4 v[32:33], v[20:23], off
	v_lshl_add_u64 v[226:227], v[30:31], 0, v[242:243]
	global_load_dwordx4 v[214:217], v[226:227], off offset:-3584 nt
	global_load_dwordx4 v[218:221], v[226:227], off offset:512 nt
	s_nop 0
	v_mul_f32_e32 v15, v15, v15
	v_mul_f32_e32 v17, v17, v17
	v_mul_f32_e32 v11, v11, v11
	v_fmac_f32_e32 v15, v14, v14
	v_fmac_f32_e32 v17, v16, v16
	v_mul_f32_e32 v13, v13, v13
	v_fmac_f32_e32 v11, v10, v10
	v_add_f32_e32 v10, v15, v17
	v_fmac_f32_e32 v13, v12, v12
	v_add_f32_e32 v10, v10, v11
	v_add_f32_e32 v10, v13, v10
	s_waitcnt vmcnt(0)
	v_cndmask_b32_e64 v222, v218, v214, s[100:101]
	v_cndmask_b32_e64 v223, v219, v215, s[100:101]
	v_cndmask_b32_e64 v224, v220, v216, s[100:101]
	v_cndmask_b32_e64 v225, v221, v217, s[100:101]
	v_mov_b32_dpp v238, v222 quad_perm:[1,0,3,2] row_mask:0xf bank_mask:0xf
	v_mov_b32_dpp v239, v223 quad_perm:[1,0,3,2] row_mask:0xf bank_mask:0xf
	v_mov_b32_dpp v240, v224 quad_perm:[1,0,3,2] row_mask:0xf bank_mask:0xf
	v_mov_b32_dpp v241, v225 quad_perm:[1,0,3,2] row_mask:0xf bank_mask:0xf
	v_cndmask_b32_e64 v20, v214, v238, s[100:101]
	v_cndmask_b32_e64 v24, v238, v218, s[100:101]
	v_cndmask_b32_e64 v21, v215, v239, s[100:101]
	v_cndmask_b32_e64 v25, v239, v219, s[100:101]
	v_cndmask_b32_e64 v22, v216, v240, s[100:101]
	v_cndmask_b32_e64 v26, v240, v220, s[100:101]
	v_cndmask_b32_e64 v23, v217, v241, s[100:101]
	v_cndmask_b32_e64 v27, v241, v221, s[100:101]
	v_pk_fma_f32 v[8:9], v[8:9], v[80:81], v[22:23]
	v_pk_fma_f32 v[6:7], v[6:7], v[78:79], v[20:21]
	s_waitcnt vmcnt(0)
	v_pk_fma_f32 v[2:3], v[2:3], v[74:75], v[24:25]
	v_mul_f32_e32 v11, v7, v7
	v_mul_f32_e32 v12, v9, v9
	v_pk_fma_f32 v[4:5], v[4:5], v[76:77], v[26:27]
	v_mul_f32_e32 v13, v3, v3
	v_fmac_f32_e32 v11, v6, v6
	v_fmac_f32_e32 v12, v8, v8
	v_mul_f32_e32 v14, v5, v5
	v_fmac_f32_e32 v13, v2, v2
	v_add_f32_e32 v11, v11, v12
	v_fmac_f32_e32 v14, v4, v4
	v_add_f32_e32 v11, v11, v13
	v_add_f32_e32 v11, v14, v11
	v_add_f32_e32 v14, v10, v11
	ds_bpermute_b32 v15, v200, v14
	v_cndmask_b32_e64 v222, v2, v6, s[100:101]
	v_cndmask_b32_e64 v223, v3, v7, s[100:101]
	v_cndmask_b32_e64 v224, v4, v8, s[100:101]
	v_cndmask_b32_e64 v225, v5, v9, s[100:101]
	v_mov_b32_dpp v238, v222 quad_perm:[1,0,3,2] row_mask:0xf bank_mask:0xf
	v_mov_b32_dpp v239, v223 quad_perm:[1,0,3,2] row_mask:0xf bank_mask:0xf
	v_mov_b32_dpp v240, v224 quad_perm:[1,0,3,2] row_mask:0xf bank_mask:0xf
	v_mov_b32_dpp v241, v225 quad_perm:[1,0,3,2] row_mask:0xf bank_mask:0xf
	v_cndmask_b32_e64 v214, v6, v238, s[100:101]
	v_cndmask_b32_e64 v218, v238, v2, s[100:101]
	v_cndmask_b32_e64 v215, v7, v239, s[100:101]
	v_cndmask_b32_e64 v219, v239, v3, s[100:101]
	v_cndmask_b32_e64 v216, v8, v240, s[100:101]
	v_cndmask_b32_e64 v220, v240, v4, s[100:101]
	v_cndmask_b32_e64 v217, v9, v241, s[100:101]
	v_cndmask_b32_e64 v221, v241, v5, s[100:101]
	v_lshl_add_u64 v[226:227], v[34:35], 0, v[242:243]
	global_store_dwordx4 v[226:227], v[214:217], off offset:-3584
	global_store_dwordx4 v[226:227], v[218:221], off offset:512
	v_pk_mul_f32 v[12:13], v[58:59], v[2:3]
	v_pk_mul_f32 v[8:9], v[64:65], v[8:9]
	v_pk_mul_f32 v[6:7], v[62:63], v[6:7]
	s_waitcnt lgkmcnt(0)
	v_add_f32_e32 v2, v14, v15
	ds_bpermute_b32 v3, v195, v2
	v_pk_mul_f32 v[10:11], v[60:61], v[4:5]
	v_cvt_pk_bf16_f32 v4, v6, v7
	v_cvt_pk_bf16_f32 v5, v8, v9
	v_cvt_pk_bf16_f32 v6, v12, v13
	v_cvt_pk_bf16_f32 v7, v10, v11
	global_store_dwordx4 v[32:33], v[4:7], off offset:256
	s_and_saveexec_b64 s[34:35], s[38:39]
	s_cbranch_execz .LBB0_966
	v_lshlrev_b64 v[4:5], 6, v[18:19]
	v_lshl_add_u64 v[4:5], s[62:63], 0, v[4:5]
	v_lshl_add_u64 v[4:5], s[24:25], 2, v[4:5]
	s_lshl_b32 s0, s47, 2
	v_lshl_add_u64 v[4:5], v[4:5], 0, s[0:1]
	s_waitcnt lgkmcnt(0)
	v_add_f32_e32 v2, v2, v3
	global_store_dword v[4:5], v2, off

; __device__ __forceinline__ unsigned pk2(float lo, float hi) { return pg8::cvt_pk_bf16(lo, hi); }
;     __device__ __forceinline__ void operator()(const f32x4 (&acc)[2][2][4][2], const pg8::Unit& u, int wr, int wc, int fr, int fq) const {
;     ...
;                 const int R = rowbase + u.pm * 256 + ai * 128 + wr * 64 + m * 16 + fr;
;                 const float* src = islat ? rin_l + (size_t)R * DM : rin_c + (size_t)(R - TL) * DM;
;                 float* dst = islat ? rout_l + (size_t)R * DM : rout_c + (size_t)(R - TL) * DM;
;                 float ss = 0.f;
; #pragma unroll
;                 for (int bj = 0; bj < 2; ++bj) { const int c = u.pn * 256 + bj * 128 + wc * 32 + 8 * fq;
;                     const f32x4 xa = *(const f32x4*)(src + c) + gv[bj][0] * acc[ai][bj][m][0];
;                     const f32x4 xb = *(const f32x4*)(src + c + 4) + gv[bj][1] * acc[ai][bj][m][1];
;                     *(f32x4*)(dst + c) = xa; *(f32x4*)(dst + c + 4) = xb;
;                     ss += (xa[0] * xa[0] + xa[1] * xa[1]) + (xa[2] * xa[2] + xa[3] * xa[3]) + (xb[0] * xb[0] + xb[1] * xb[1]) + (xb[2] * xb[2] + xb[3] * xb[3]);
;                     const f32x4 ya = xa * sv[bj][0], yb = xb * sv[bj][1];
;                     u32x4 w; w.x = pk2(ya[0], ya[1]); w.y = pk2(ya[2], ya[3]); w.z = pk2(yb[0], yb[1]); w.w = pk2(yb[2], yb[3]);
;                     *(u32x4*)(Hn + (size_t)R * DM + c) = w; }
;                 ss += __shfl_xor(ss, 16); ss += __shfl_xor(ss, 32);
;                 if (fq == 0) stat[(size_t)R * 16 + u.pn * 4 + wc] = ss;
.LBB0_1215:
	v_and_b32_e32 v200, 64, v228
	v_xor_b32_e32 v195, 16, v228
	v_add_u32_e32 v202, 64, v200
	v_cmp_lt_i32_e32 vcc, v195, v202
	s_lshl_b32 s24, s0, 2
	s_ashr_i32 s25, s24, 31
	v_cndmask_b32_e32 v195, v228, v195, vcc
	v_lshlrev_b32_e32 v200, 2, v195
	v_xor_b32_e32 v195, 32, v228
	v_cmp_lt_i32_e32 vcc, v195, v202
	v_cndmask_b32_e64 v202, v194, v190, s[42:43]
	s_and_b64 s[10:11], s[42:43], exec
	v_ashrrev_i32_e32 v203, 31, v202
	s_cselect_b32 s69, s49, s67
	s_cselect_b32 s68, s48, s66
	v_lshlrev_b64 v[202:203], 12, v[202:203]
	v_lshl_add_u64 v[202:203], s[68:69], 0, v[202:203]
	v_lshl_add_u64 v[212:213], v[202:203], 0, v[188:189]
	s_mov_b32 s100, 0xaaaaaaaa
	s_mov_b32 s101, 0xaaaaaaaa
	v_mov_b32_e32 v222, 0x1000
	v_mov_b32_e32 v223, 16
	v_cndmask_b32_e64 v242, v222, v223, s[100:101]
	v_mov_b32_e32 v243, 0
	v_lshl_add_u64 v[226:227], v[212:213], 0, v[242:243]
	global_load_dwordx4 v[214:217], v[226:227], off offset:-4096 nt
	global_load_dwordx4 v[218:221], v[226:227], off nt
	v_lshlrev_b64 v[210:211], 11, v[190:191]
	v_cndmask_b32_e32 v195, v228, v195, vcc
	v_lshlrev_b32_e32 v195, 2, v195
	s_waitcnt vmcnt(0)
	v_cndmask_b32_e64 v222, v218, v214, s[100:101]
	v_cndmask_b32_e64 v223, v219, v215, s[100:101]
	v_cndmask_b32_e64 v224, v220, v216, s[100:101]
	v_cndmask_b32_e64 v225, v221, v217, s[100:101]
	v_mov_b32_dpp v238, v222 quad_perm:[1,0,3,2] row_mask:0xf bank_mask:0xf
	v_mov_b32_dpp v239, v223 quad_perm:[1,0,3,2] row_mask:0xf bank_mask:0xf
	v_mov_b32_dpp v240, v224 quad_perm:[1,0,3,2] row_mask:0xf bank_mask:0xf
	v_mov_b32_dpp v241, v225 quad_perm:[1,0,3,2] row_mask:0xf bank_mask:0xf
	v_cndmask_b32_e64 v206, v214, v238, s[100:101]
	v_cndmask_b32_e64 v202, v238, v218, s[100:101]
	v_cndmask_b32_e64 v207, v215, v239, s[100:101]
	v_cndmask_b32_e64 v203, v239, v219, s[100:101]
	v_cndmask_b32_e64 v208, v216, v240, s[100:101]
	v_cndmask_b32_e64 v204, v240, v220, s[100:101]
	v_cndmask_b32_e64 v209, v217, v241, s[100:101]
	v_cndmask_b32_e64 v205, v241, v221, s[100:101]
	v_pk_fma_f32 v[204:205], v[156:157], v[88:89], v[204:205]
	v_pk_fma_f32 v[160:161], v[160:161], v[96:97], v[208:209]
	v_pk_fma_f32 v[158:159], v[158:159], v[94:95], v[206:207]
	v_mul_f32_e32 v157, v161, v161
	v_mul_f32_e32 v156, v159, v159
	v_pk_fma_f32 v[202:203], v[154:155], v[86:87], v[202:203]
	v_fmac_f32_e32 v156, v158, v158
	v_fmac_f32_e32 v157, v160, v160
	v_add_f32_e32 v156, v156, v157
	v_mul_f32_e32 v157, v203, v203
	v_fmac_f32_e32 v157, v202, v202
	v_add_f32_e32 v156, v156, v157
	v_mul_f32_e32 v157, v205, v205
	v_lshl_add_u64 v[154:155], v[192:193], 0, v[188:189]
	v_fmac_f32_e32 v157, v204, v204
	v_cndmask_b32_e64 v222, v202, v158, s[100:101]
	v_cndmask_b32_e64 v223, v203, v159, s[100:101]
	v_cndmask_b32_e64 v224, v204, v160, s[100:101]
	v_cndmask_b32_e64 v225, v205, v161, s[100:101]
	v_mov_b32_dpp v238, v222 quad_perm:[1,0,3,2] row_mask:0xf bank_mask:0xf
	v_mov_b32_dpp v239, v223 quad_perm:[1,0,3,2] row_mask:0xf bank_mask:0xf
	v_mov_b32_dpp v240, v224 quad_perm:[1,0,3,2] row_mask:0xf bank_mask:0xf
	v_mov_b32_dpp v241, v225 quad_perm:[1,0,3,2] row_mask:0xf bank_mask:0xf
	v_cndmask_b32_e64 v214, v158, v238, s[100:101]
	v_cndmask_b32_e64 v218, v238, v202, s[100:101]
	v_cndmask_b32_e64 v215, v159, v239, s[100:101]
	v_cndmask_b32_e64 v219, v239, v203, s[100:101]
	v_cndmask_b32_e64 v216, v160, v240, s[100:101]
	v_cndmask_b32_e64 v220, v240, v204, s[100:101]
	v_cndmask_b32_e64 v217, v161, v241, s[100:101]
	v_cndmask_b32_e64 v221, v241, v205, s[100:101]
	v_lshl_add_u64 v[226:227], v[154:155], 0, v[242:243]
	global_store_dwordx4 v[226:227], v[214:217], off offset:-4096
	global_store_dwordx4 v[226:227], v[218:221], off
	v_add_f32_e32 v194, v157, v156
	v_pk_mul_f32 v[160:161], v[92:93], v[160:161]
	v_pk_mul_f32 v[156:157], v[90:91], v[158:159]
	v_pk_mul_f32 v[192:193], v[84:85], v[204:205]
	v_pk_mul_f32 v[158:159], v[82:83], v[202:203]
	v_cvt_pk_bf16_f32 v156, v156, v157
	v_cvt_pk_bf16_f32 v157, v160, v161
	v_lshl_add_u64 v[160:161], s[60:61], 0, v[210:211]
	v_cvt_pk_bf16_f32 v158, v158, v159
	v_cvt_pk_bf16_f32 v159, v192, v193
	v_lshl_add_u64 v[160:161], v[186:187], 1, v[160:161]
	global_store_dwordx4 v[160:161], v[156:159], off
	v_lshl_add_u64 v[226:227], v[212:213], 0, v[242:243]
	global_load_dwordx4 v[214:217], v[226:227], off offset:-3584 nt
	global_load_dwordx4 v[218:221], v[226:227], off offset:512 nt
	s_nop 0
	s_waitcnt vmcnt(0)
; __device__ __forceinline__ unsigned pk2(float lo, float hi) { return pg8::cvt_pk_bf16(lo, hi); }
;     __device__ __forceinline__ void operator()(const f32x4 (&acc)[2][2][4][2], const pg8::Unit& u, int wr, int wc, int fr, int fq) const {
;     ...
;                 for (int bj = 0; bj < 2; ++bj) { const int c = u.pn * 256 + bj * 128 + wc * 32 + 8 * fq;
;                     const f32x4 xa = *(const f32x4*)(src + c) + gv[bj][0] * acc[ai][bj][m][0];
;                     const f32x4 xb = *(const f32x4*)(src + c + 4) + gv[bj][1] * acc[ai][bj][m][1];
;                     *(f32x4*)(dst + c) = xa; *(f32x4*)(dst + c + 4) = xb;
;                     ss += (xa[0] * xa[0] + xa[1] * xa[1]) + (xa[2] * xa[2] + xa[3] * xa[3]) + (xb[0] * xb[0] + xb[1] * xb[1]) + (xb[2] * xb[2] + xb[3] * xb[3]);
;                     const f32x4 ya = xa * sv[bj][0], yb = xb * sv[bj][1];
;                     u32x4 w; w.x = pk2(ya[0], ya[1]); w.y = pk2(ya[2], ya[3]); w.z = pk2(yb[0], yb[1]); w.w = pk2(yb[2], yb[3]);
;                     *(u32x4*)(Hn + (size_t)R * DM + c) = w; }
;                 ss += __shfl_xor(ss, 16); ss += __shfl_xor(ss, 32);
;                 if (fq == 0) stat[(size_t)R * 16 + u.pn * 4 + wc] = ss;
	v_cndmask_b32_e64 v222, v218, v214, s[100:101]
	v_cndmask_b32_e64 v223, v219, v215, s[100:101]
	v_cndmask_b32_e64 v224, v220, v216, s[100:101]
	v_cndmask_b32_e64 v225, v221, v217, s[100:101]
	v_mov_b32_dpp v238, v222 quad_perm:[1,0,3,2] row_mask:0xf bank_mask:0xf
	v_mov_b32_dpp v239, v223 quad_perm:[1,0,3,2] row_mask:0xf bank_mask:0xf
	v_mov_b32_dpp v240, v224 quad_perm:[1,0,3,2] row_mask:0xf bank_mask:0xf
	v_mov_b32_dpp v241, v225 quad_perm:[1,0,3,2] row_mask:0xf bank_mask:0xf
	v_cndmask_b32_e64 v202, v214, v238, s[100:101]
	v_cndmask_b32_e64 v156, v238, v218, s[100:101]
	v_cndmask_b32_e64 v203, v215, v239, s[100:101]
	v_cndmask_b32_e64 v157, v239, v219, s[100:101]
	v_cndmask_b32_e64 v204, v216, v240, s[100:101]
	v_cndmask_b32_e64 v158, v240, v220, s[100:101]
	v_cndmask_b32_e64 v205, v217, v241, s[100:101]
	v_cndmask_b32_e64 v159, v241, v221, s[100:101]
	v_pk_fma_f32 v[148:149], v[148:149], v[76:77], v[158:159]
	s_waitcnt vmcnt(0)
	v_pk_fma_f32 v[152:153], v[152:153], v[80:81], v[204:205]
	v_pk_fma_f32 v[150:151], v[150:151], v[78:79], v[202:203]
	v_pk_fma_f32 v[146:147], v[146:147], v[74:75], v[156:157]
	v_cndmask_b32_e64 v222, v146, v150, s[100:101]
	v_cndmask_b32_e64 v223, v147, v151, s[100:101]
	v_cndmask_b32_e64 v224, v148, v152, s[100:101]
	v_cndmask_b32_e64 v225, v149, v153, s[100:101]
	v_mov_b32_dpp v238, v222 quad_perm:[1,0,3,2] row_mask:0xf bank_mask:0xf
	v_mov_b32_dpp v239, v223 quad_perm:[1,0,3,2] row_mask:0xf bank_mask:0xf
	v_mov_b32_dpp v240, v224 quad_perm:[1,0,3,2] row_mask:0xf bank_mask:0xf
	v_mov_b32_dpp v241, v225 quad_perm:[1,0,3,2] row_mask:0xf bank_mask:0xf
	v_cndmask_b32_e64 v214, v150, v238, s[100:101]
	v_cndmask_b32_e64 v218, v238, v146, s[100:101]
	v_cndmask_b32_e64 v215, v151, v239, s[100:101]
	v_cndmask_b32_e64 v219, v239, v147, s[100:101]
	v_cndmask_b32_e64 v216, v152, v240, s[100:101]
	v_cndmask_b32_e64 v220, v240, v148, s[100:101]
	v_cndmask_b32_e64 v217, v153, v241, s[100:101]
	v_cndmask_b32_e64 v221, v241, v149, s[100:101]
	v_lshl_add_u64 v[226:227], v[154:155], 0, v[242:243]
	global_store_dwordx4 v[226:227], v[214:217], off offset:-3584
	global_store_dwordx4 v[226:227], v[218:221], off offset:512
	v_mul_f32_e32 v154, v151, v151
	v_mul_f32_e32 v155, v153, v153
	v_fmac_f32_e32 v154, v150, v150
	v_fmac_f32_e32 v155, v152, v152
	v_add_f32_e32 v154, v154, v155
	v_mul_f32_e32 v155, v147, v147
	v_fmac_f32_e32 v155, v146, v146
	v_add_f32_e32 v154, v154, v155
	v_mul_f32_e32 v155, v149, v149
	v_fmac_f32_e32 v155, v148, v148
	v_add_f32_e32 v154, v155, v154
	v_add_f32_e32 v156, v194, v154
	v_pk_mul_f32 v[152:153], v[64:65], v[152:153]
	v_pk_mul_f32 v[150:151], v[62:63], v[150:151]
	v_pk_mul_f32 v[154:155], v[60:61], v[148:149]
	v_pk_mul_f32 v[148:149], v[58:59], v[146:147]
	v_cvt_pk_bf16_f32 v146, v150, v151
	v_cvt_pk_bf16_f32 v147, v152, v153
	v_cvt_pk_bf16_f32 v148, v148, v149
	v_cvt_pk_bf16_f32 v149, v154, v155
	global_store_dwordx4 v[160:161], v[146:149], off offset:256
	ds_bpermute_b32 v146, v200, v156
	s_waitcnt lgkmcnt(0)
	v_add_f32_e32 v146, v156, v146
	ds_bpermute_b32 v147, v195, v146
	s_and_saveexec_b64 s[34:35], s[38:39]
	s_cbranch_execz .LBB0_1217
	v_lshlrev_b64 v[148:149], 6, v[190:191]
	v_lshl_add_u64 v[148:149], s[62:63], 0, v[148:149]
	v_lshl_add_u64 v[148:149], s[24:25], 2, v[148:149]
	s_lshl_b32 s0, s56, 2
	v_lshl_add_u64 v[148:149], v[148:149], 0, s[0:1]
	s_waitcnt lgkmcnt(0)
	v_add_f32_e32 v146, v146, v147
	global_store_dword v[148:149], v146, off

; __device__ __forceinline__ unsigned pk2(float lo, float hi) { return pg8::cvt_pk_bf16(lo, hi); }
;     __device__ __forceinline__ void operator()(const f32x4 (&acc)[2][2][4][2], const pg8::Unit& u, int wr, int wc, int fr, int fq) const {
;     ...
;                 const int R = rowbase + u.pm * 256 + ai * 128 + wr * 64 + m * 16 + fr;
;                 const float* src = islat ? rin_l + (size_t)R * DM : rin_c + (size_t)(R - TL) * DM;
;                 float* dst = islat ? rout_l + (size_t)R * DM : rout_c + (size_t)(R - TL) * DM;
;                 float ss = 0.f;
; #pragma unroll
;                 for (int bj = 0; bj < 2; ++bj) { const int c = u.pn * 256 + bj * 128 + wc * 32 + 8 * fq;
;                     const f32x4 xa = *(const f32x4*)(src + c) + gv[bj][0] * acc[ai][bj][m][0];
;                     const f32x4 xb = *(const f32x4*)(src + c + 4) + gv[bj][1] * acc[ai][bj][m][1];
;                     *(f32x4*)(dst + c) = xa; *(f32x4*)(dst + c + 4) = xb;
;                     ss += (xa[0] * xa[0] + xa[1] * xa[1]) + (xa[2] * xa[2] + xa[3] * xa[3]) + (xb[0] * xb[0] + xb[1] * xb[1]) + (xb[2] * xb[2] + xb[3] * xb[3]);
;                     const f32x4 ya = xa * sv[bj][0], yb = xb * sv[bj][1];
;                     u32x4 w; w.x = pk2(ya[0], ya[1]); w.y = pk2(ya[2], ya[3]); w.z = pk2(yb[0], yb[1]); w.w = pk2(yb[2], yb[3]);
;                     *(u32x4*)(Hn + (size_t)R * DM + c) = w; }
;                 ss += __shfl_xor(ss, 16); ss += __shfl_xor(ss, 32);
;                 if (fq == 0) stat[(size_t)R * 16 + u.pn * 4 + wc] = ss;
.LBB0_1221:
	v_cndmask_b32_e64 v150, v150, v146, s[42:43]
	v_ashrrev_i32_e32 v151, 31, v150
	v_lshlrev_b64 v[150:151], 12, v[150:151]
	v_lshl_add_u64 v[150:151], s[68:69], 0, v[150:151]
	v_lshl_add_u64 v[158:159], v[150:151], 0, v[188:189]
	v_lshl_add_u64 v[226:227], v[158:159], 0, v[242:243]
	global_load_dwordx4 v[214:217], v[226:227], off offset:-4096 nt
	global_load_dwordx4 v[218:221], v[226:227], off nt
	v_lshlrev_b64 v[160:161], 11, v[146:147]
	v_lshl_add_u64 v[192:193], v[148:149], 0, v[188:189]
	v_lshl_add_u64 v[148:149], s[60:61], 0, v[160:161]
	v_lshl_add_u64 v[160:161], v[186:187], 1, v[148:149]
	s_waitcnt vmcnt(0)
	v_cndmask_b32_e64 v222, v218, v214, s[100:101]
	v_cndmask_b32_e64 v223, v219, v215, s[100:101]
	v_cndmask_b32_e64 v224, v220, v216, s[100:101]
	v_cndmask_b32_e64 v225, v221, v217, s[100:101]
	v_mov_b32_dpp v238, v222 quad_perm:[1,0,3,2] row_mask:0xf bank_mask:0xf
	v_mov_b32_dpp v239, v223 quad_perm:[1,0,3,2] row_mask:0xf bank_mask:0xf
	v_mov_b32_dpp v240, v224 quad_perm:[1,0,3,2] row_mask:0xf bank_mask:0xf
	v_mov_b32_dpp v241, v225 quad_perm:[1,0,3,2] row_mask:0xf bank_mask:0xf
	v_cndmask_b32_e64 v150, v214, v238, s[100:101]
	v_cndmask_b32_e64 v154, v238, v218, s[100:101]
	v_cndmask_b32_e64 v151, v215, v239, s[100:101]
	v_cndmask_b32_e64 v155, v239, v219, s[100:101]
	v_cndmask_b32_e64 v152, v216, v240, s[100:101]
	v_cndmask_b32_e64 v156, v240, v220, s[100:101]
	v_cndmask_b32_e64 v153, v217, v241, s[100:101]
	v_cndmask_b32_e64 v157, v241, v221, s[100:101]
	v_pk_fma_f32 v[144:145], v[144:145], v[96:97], v[152:153]
	v_pk_fma_f32 v[142:143], v[142:143], v[94:95], v[150:151]
	s_waitcnt vmcnt(0)
	v_pk_fma_f32 v[140:141], v[140:141], v[88:89], v[156:157]
	v_pk_fma_f32 v[138:139], v[138:139], v[86:87], v[154:155]
	v_pk_mul_f32 v[150:151], v[92:93], v[144:145]
	v_pk_mul_f32 v[148:149], v[90:91], v[142:143]
	v_pk_mul_f32 v[152:153], v[84:85], v[140:141]
	v_pk_mul_f32 v[154:155], v[82:83], v[138:139]
	v_cvt_pk_bf16_f32 v148, v148, v149
	v_cvt_pk_bf16_f32 v149, v150, v151
	v_cvt_pk_bf16_f32 v150, v154, v155
	v_cvt_pk_bf16_f32 v151, v152, v153
	v_cndmask_b32_e64 v222, v138, v142, s[100:101]
	v_cndmask_b32_e64 v223, v139, v143, s[100:101]
	v_cndmask_b32_e64 v224, v140, v144, s[100:101]
	v_cndmask_b32_e64 v225, v141, v145, s[100:101]
	v_mov_b32_dpp v238, v222 quad_perm:[1,0,3,2] row_mask:0xf bank_mask:0xf
	v_mov_b32_dpp v239, v223 quad_perm:[1,0,3,2] row_mask:0xf bank_mask:0xf
	v_mov_b32_dpp v240, v224 quad_perm:[1,0,3,2] row_mask:0xf bank_mask:0xf
	v_mov_b32_dpp v241, v225 quad_perm:[1,0,3,2] row_mask:0xf bank_mask:0xf
	v_cndmask_b32_e64 v214, v142, v238, s[100:101]
	v_cndmask_b32_e64 v218, v238, v138, s[100:101]
	v_cndmask_b32_e64 v215, v143, v239, s[100:101]
	v_cndmask_b32_e64 v219, v239, v139, s[100:101]
	v_cndmask_b32_e64 v216, v144, v240, s[100:101]
	v_cndmask_b32_e64 v220, v240, v140, s[100:101]
	v_cndmask_b32_e64 v217, v145, v241, s[100:101]
	v_cndmask_b32_e64 v221, v241, v141, s[100:101]
	v_lshl_add_u64 v[226:227], v[192:193], 0, v[242:243]
	global_store_dwordx4 v[226:227], v[214:217], off offset:-4096
	global_store_dwordx4 v[226:227], v[218:221], off
	global_store_dwordx4 v[160:161], v[148:151], off
	v_lshl_add_u64 v[226:227], v[158:159], 0, v[242:243]
	global_load_dwordx4 v[214:217], v[226:227], off offset:-3584 nt
	global_load_dwordx4 v[218:221], v[226:227], off offset:512 nt
	s_nop 0
	v_mul_f32_e32 v143, v143, v143
	v_mul_f32_e32 v145, v145, v145
	v_mul_f32_e32 v139, v139, v139
	v_fmac_f32_e32 v143, v142, v142
	v_fmac_f32_e32 v145, v144, v144
	v_mul_f32_e32 v141, v141, v141
	v_fmac_f32_e32 v139, v138, v138
	v_add_f32_e32 v138, v143, v145
	v_fmac_f32_e32 v141, v140, v140
	v_add_f32_e32 v138, v138, v139
	v_add_f32_e32 v138, v141, v138
	s_waitcnt vmcnt(0)
	v_cndmask_b32_e64 v222, v218, v214, s[100:101]
	v_cndmask_b32_e64 v223, v219, v215, s[100:101]
	v_cndmask_b32_e64 v224, v220, v216, s[100:101]
	v_cndmask_b32_e64 v225, v221, v217, s[100:101]
	v_mov_b32_dpp v238, v222 quad_perm:[1,0,3,2] row_mask:0xf bank_mask:0xf
	v_mov_b32_dpp v239, v223 quad_perm:[1,0,3,2] row_mask:0xf bank_mask:0xf
	v_mov_b32_dpp v240, v224 quad_perm:[1,0,3,2] row_mask:0xf bank_mask:0xf
	v_mov_b32_dpp v241, v225 quad_perm:[1,0,3,2] row_mask:0xf bank_mask:0xf
	v_cndmask_b32_e64 v148, v214, v238, s[100:101]
	v_cndmask_b32_e64 v152, v238, v218, s[100:101]
	v_cndmask_b32_e64 v149, v215, v239, s[100:101]
	v_cndmask_b32_e64 v153, v239, v219, s[100:101]
	v_cndmask_b32_e64 v150, v216, v240, s[100:101]
	v_cndmask_b32_e64 v154, v240, v220, s[100:101]
	v_cndmask_b32_e64 v151, v217, v241, s[100:101]
	v_cndmask_b32_e64 v155, v241, v221, s[100:101]
	v_pk_fma_f32 v[136:137], v[136:137], v[80:81], v[150:151]
	v_pk_fma_f32 v[134:135], v[134:135], v[78:79], v[148:149]
	s_waitcnt vmcnt(0)
	v_pk_fma_f32 v[130:131], v[130:131], v[74:75], v[152:153]
	v_mul_f32_e32 v139, v135, v135
	v_mul_f32_e32 v140, v137, v137
	v_pk_fma_f32 v[132:133], v[132:133], v[76:77], v[154:155]
	v_mul_f32_e32 v141, v131, v131
	v_fmac_f32_e32 v139, v134, v134
	v_fmac_f32_e32 v140, v136, v136
	v_mul_f32_e32 v142, v133, v133
	v_fmac_f32_e32 v141, v130, v130
	v_add_f32_e32 v139, v139, v140
	v_fmac_f32_e32 v142, v132, v132
	v_add_f32_e32 v139, v139, v141
	v_add_f32_e32 v139, v142, v139
	v_add_f32_e32 v142, v138, v139
	ds_bpermute_b32 v143, v200, v142
	v_cndmask_b32_e64 v222, v130, v134, s[100:101]
	v_cndmask_b32_e64 v223, v131, v135, s[100:101]
	v_cndmask_b32_e64 v224, v132, v136, s[100:101]
	v_cndmask_b32_e64 v225, v133, v137, s[100:101]
	v_mov_b32_dpp v238, v222 quad_perm:[1,0,3,2] row_mask:0xf bank_mask:0xf
	v_mov_b32_dpp v239, v223 quad_perm:[1,0,3,2] row_mask:0xf bank_mask:0xf
	v_mov_b32_dpp v240, v224 quad_perm:[1,0,3,2] row_mask:0xf bank_mask:0xf
	v_mov_b32_dpp v241, v225 quad_perm:[1,0,3,2] row_mask:0xf bank_mask:0xf
	v_cndmask_b32_e64 v214, v134, v238, s[100:101]
	v_cndmask_b32_e64 v218, v238, v130, s[100:101]
	v_cndmask_b32_e64 v215, v135, v239, s[100:101]
	v_cndmask_b32_e64 v219, v239, v131, s[100:101]
	v_cndmask_b32_e64 v216, v136, v240, s[100:101]
	v_cndmask_b32_e64 v220, v240, v132, s[100:101]
	v_cndmask_b32_e64 v217, v137, v241, s[100:101]
	v_cndmask_b32_e64 v221, v241, v133, s[100:101]
	v_lshl_add_u64 v[226:227], v[192:193], 0, v[242:243]
	global_store_dwordx4 v[226:227], v[214:217], off offset:-3584
	global_store_dwordx4 v[226:227], v[218:221], off offset:512
	v_pk_mul_f32 v[140:141], v[58:59], v[130:131]
	v_pk_mul_f32 v[136:137], v[64:65], v[136:137]
	v_pk_mul_f32 v[134:135], v[62:63], v[134:135]
	s_waitcnt lgkmcnt(0)
	v_add_f32_e32 v130, v142, v143
	ds_bpermute_b32 v131, v195, v130
	v_pk_mul_f32 v[138:139], v[60:61], v[132:133]
	v_cvt_pk_bf16_f32 v132, v134, v135
	v_cvt_pk_bf16_f32 v133, v136, v137
	v_cvt_pk_bf16_f32 v134, v140, v141
	v_cvt_pk_bf16_f32 v135, v138, v139
	global_store_dwordx4 v[160:161], v[132:135], off offset:256
	s_and_saveexec_b64 s[34:35], s[38:39]
	s_cbranch_execz .LBB0_1223
;     __device__ __forceinline__ void operator()(const f32x4 (&acc)[2][2][4][2], const pg8::Unit& u, int wr, int wc, int fr, int fq) const {
;     ...
;                 if (fq == 0) stat[(size_t)R * 16 + u.pn * 4 + wc] = ss;
	v_lshlrev_b64 v[132:133], 6, v[146:147]
	v_lshl_add_u64 v[132:133], s[62:63], 0, v[132:133]
	v_lshl_add_u64 v[132:133], s[24:25], 2, v[132:133]
	s_lshl_b32 s0, s56, 2
	v_lshl_add_u64 v[132:133], v[132:133], 0, s[0:1]
	s_waitcnt lgkmcnt(0)
	v_add_f32_e32 v130, v130, v131
	global_store_dword v[132:133], v130, off

; __device__ __forceinline__ unsigned pk2(float lo, float hi) { return pg8::cvt_pk_bf16(lo, hi); }
;     __device__ __forceinline__ void operator()(const f32x4 (&acc)[2][2][4][2], const pg8::Unit& u, int wr, int wc, int fr, int fq) const {
;     ...
;                 const int R = rowbase + u.pm * 256 + ai * 128 + wr * 64 + m * 16 + fr;
;                 const float* src = islat ? rin_l + (size_t)R * DM : rin_c + (size_t)(R - TL) * DM;
;                 float* dst = islat ? rout_l + (size_t)R * DM : rout_c + (size_t)(R - TL) * DM;
;                 float ss = 0.f;
; #pragma unroll
;                 for (int bj = 0; bj < 2; ++bj) { const int c = u.pn * 256 + bj * 128 + wc * 32 + 8 * fq;
;                     const f32x4 xa = *(const f32x4*)(src + c) + gv[bj][0] * acc[ai][bj][m][0];
;                     const f32x4 xb = *(const f32x4*)(src + c + 4) + gv[bj][1] * acc[ai][bj][m][1];
;                     *(f32x4*)(dst + c) = xa; *(f32x4*)(dst + c + 4) = xb;
;                     ss += (xa[0] * xa[0] + xa[1] * xa[1]) + (xa[2] * xa[2] + xa[3] * xa[3]) + (xb[0] * xb[0] + xb[1] * xb[1]) + (xb[2] * xb[2] + xb[3] * xb[3]);
;                     const f32x4 ya = xa * sv[bj][0], yb = xb * sv[bj][1];
;                     u32x4 w; w.x = pk2(ya[0], ya[1]); w.y = pk2(ya[2], ya[3]); w.z = pk2(yb[0], yb[1]); w.w = pk2(yb[2], yb[3]);
;                     *(u32x4*)(Hn + (size_t)R * DM + c) = w; }
;                 ss += __shfl_xor(ss, 16); ss += __shfl_xor(ss, 32);
;                 if (fq == 0) stat[(size_t)R * 16 + u.pn * 4 + wc] = ss;
.LBB0_1227:
	v_cndmask_b32_e64 v134, v134, v130, s[42:43]
	v_ashrrev_i32_e32 v135, 31, v134
	v_lshlrev_b64 v[134:135], 12, v[134:135]
	v_lshl_add_u64 v[134:135], s[68:69], 0, v[134:135]
	v_lshl_add_u64 v[142:143], v[134:135], 0, v[188:189]
	v_lshl_add_u64 v[226:227], v[142:143], 0, v[242:243]
	global_load_dwordx4 v[214:217], v[226:227], off offset:-4096 nt
	global_load_dwordx4 v[218:221], v[226:227], off nt
	v_lshlrev_b64 v[144:145], 11, v[130:131]
	v_lshl_add_u64 v[146:147], v[132:133], 0, v[188:189]
	v_lshl_add_u64 v[132:133], s[60:61], 0, v[144:145]
	v_lshl_add_u64 v[144:145], v[186:187], 1, v[132:133]
	s_waitcnt vmcnt(0)
	v_cndmask_b32_e64 v222, v218, v214, s[100:101]
	v_cndmask_b32_e64 v223, v219, v215, s[100:101]
	v_cndmask_b32_e64 v224, v220, v216, s[100:101]
	v_cndmask_b32_e64 v225, v221, v217, s[100:101]
	v_mov_b32_dpp v238, v222 quad_perm:[1,0,3,2] row_mask:0xf bank_mask:0xf
	v_mov_b32_dpp v239, v223 quad_perm:[1,0,3,2] row_mask:0xf bank_mask:0xf
	v_mov_b32_dpp v240, v224 quad_perm:[1,0,3,2] row_mask:0xf bank_mask:0xf
	v_mov_b32_dpp v241, v225 quad_perm:[1,0,3,2] row_mask:0xf bank_mask:0xf
	v_cndmask_b32_e64 v134, v214, v238, s[100:101]
	v_cndmask_b32_e64 v138, v238, v218, s[100:101]
	v_cndmask_b32_e64 v135, v215, v239, s[100:101]
	v_cndmask_b32_e64 v139, v239, v219, s[100:101]
	v_cndmask_b32_e64 v136, v216, v240, s[100:101]
	v_cndmask_b32_e64 v140, v240, v220, s[100:101]
	v_cndmask_b32_e64 v137, v217, v241, s[100:101]
	v_cndmask_b32_e64 v141, v241, v221, s[100:101]
	v_pk_fma_f32 v[128:129], v[128:129], v[96:97], v[136:137]
	v_pk_fma_f32 v[126:127], v[126:127], v[94:95], v[134:135]
	s_waitcnt vmcnt(0)
	v_pk_fma_f32 v[124:125], v[124:125], v[88:89], v[140:141]
	v_pk_fma_f32 v[122:123], v[122:123], v[86:87], v[138:139]
	v_pk_mul_f32 v[134:135], v[92:93], v[128:129]
	v_pk_mul_f32 v[132:133], v[90:91], v[126:127]
	v_pk_mul_f32 v[136:137], v[84:85], v[124:125]
	v_pk_mul_f32 v[138:139], v[82:83], v[122:123]
	v_cvt_pk_bf16_f32 v132, v132, v133
	v_cvt_pk_bf16_f32 v133, v134, v135
	v_cvt_pk_bf16_f32 v134, v138, v139
	v_cvt_pk_bf16_f32 v135, v136, v137
	v_cndmask_b32_e64 v222, v122, v126, s[100:101]
	v_cndmask_b32_e64 v223, v123, v127, s[100:101]
	v_cndmask_b32_e64 v224, v124, v128, s[100:101]
	v_cndmask_b32_e64 v225, v125, v129, s[100:101]
	v_mov_b32_dpp v238, v222 quad_perm:[1,0,3,2] row_mask:0xf bank_mask:0xf
	v_mov_b32_dpp v239, v223 quad_perm:[1,0,3,2] row_mask:0xf bank_mask:0xf
	v_mov_b32_dpp v240, v224 quad_perm:[1,0,3,2] row_mask:0xf bank_mask:0xf
	v_mov_b32_dpp v241, v225 quad_perm:[1,0,3,2] row_mask:0xf bank_mask:0xf
	v_cndmask_b32_e64 v214, v126, v238, s[100:101]
	v_cndmask_b32_e64 v218, v238, v122, s[100:101]
	v_cndmask_b32_e64 v215, v127, v239, s[100:101]
	v_cndmask_b32_e64 v219, v239, v123, s[100:101]
	v_cndmask_b32_e64 v216, v128, v240, s[100:101]
	v_cndmask_b32_e64 v220, v240, v124, s[100:101]
	v_cndmask_b32_e64 v217, v129, v241, s[100:101]
	v_cndmask_b32_e64 v221, v241, v125, s[100:101]
	v_lshl_add_u64 v[226:227], v[146:147], 0, v[242:243]
	global_store_dwordx4 v[226:227], v[214:217], off offset:-4096
	global_store_dwordx4 v[226:227], v[218:221], off
	global_store_dwordx4 v[144:145], v[132:135], off
	v_lshl_add_u64 v[226:227], v[142:143], 0, v[242:243]
	global_load_dwordx4 v[214:217], v[226:227], off offset:-3584 nt
	global_load_dwordx4 v[218:221], v[226:227], off offset:512 nt
	s_nop 0
	v_mul_f32_e32 v127, v127, v127
	v_mul_f32_e32 v129, v129, v129
	v_mul_f32_e32 v123, v123, v123
	v_fmac_f32_e32 v127, v126, v126
	v_fmac_f32_e32 v129, v128, v128
	v_mul_f32_e32 v125, v125, v125
	v_fmac_f32_e32 v123, v122, v122
	v_add_f32_e32 v122, v127, v129
	v_fmac_f32_e32 v125, v124, v124
	v_add_f32_e32 v122, v122, v123
	v_add_f32_e32 v122, v125, v122
	s_waitcnt vmcnt(0)
	v_cndmask_b32_e64 v222, v218, v214, s[100:101]
	v_cndmask_b32_e64 v223, v219, v215, s[100:101]
	v_cndmask_b32_e64 v224, v220, v216, s[100:101]
	v_cndmask_b32_e64 v225, v221, v217, s[100:101]
	v_mov_b32_dpp v238, v222 quad_perm:[1,0,3,2] row_mask:0xf bank_mask:0xf
	v_mov_b32_dpp v239, v223 quad_perm:[1,0,3,2] row_mask:0xf bank_mask:0xf
	v_mov_b32_dpp v240, v224 quad_perm:[1,0,3,2] row_mask:0xf bank_mask:0xf
	v_mov_b32_dpp v241, v225 quad_perm:[1,0,3,2] row_mask:0xf bank_mask:0xf
	v_cndmask_b32_e64 v132, v214, v238, s[100:101]
	v_cndmask_b32_e64 v136, v238, v218, s[100:101]
	v_cndmask_b32_e64 v133, v215, v239, s[100:101]
	v_cndmask_b32_e64 v137, v239, v219, s[100:101]
	v_cndmask_b32_e64 v134, v216, v240, s[100:101]
	v_cndmask_b32_e64 v138, v240, v220, s[100:101]
	v_cndmask_b32_e64 v135, v217, v241, s[100:101]
	v_cndmask_b32_e64 v139, v241, v221, s[100:101]
	v_pk_fma_f32 v[120:121], v[120:121], v[80:81], v[134:135]
	v_pk_fma_f32 v[118:119], v[118:119], v[78:79], v[132:133]
	s_waitcnt vmcnt(0)
	v_pk_fma_f32 v[114:115], v[114:115], v[74:75], v[136:137]
	v_mul_f32_e32 v123, v119, v119
	v_mul_f32_e32 v124, v121, v121
	v_pk_fma_f32 v[116:117], v[116:117], v[76:77], v[138:139]
	v_mul_f32_e32 v125, v115, v115
	v_fmac_f32_e32 v123, v118, v118
	v_fmac_f32_e32 v124, v120, v120
	v_mul_f32_e32 v126, v117, v117
	v_fmac_f32_e32 v125, v114, v114
	v_add_f32_e32 v123, v123, v124
	v_fmac_f32_e32 v126, v116, v116
	v_add_f32_e32 v123, v123, v125
	v_add_f32_e32 v123, v126, v123
	v_add_f32_e32 v126, v122, v123
	ds_bpermute_b32 v127, v200, v126
	v_cndmask_b32_e64 v222, v114, v118, s[100:101]
	v_cndmask_b32_e64 v223, v115, v119, s[100:101]
	v_cndmask_b32_e64 v224, v116, v120, s[100:101]
	v_cndmask_b32_e64 v225, v117, v121, s[100:101]
	v_mov_b32_dpp v238, v222 quad_perm:[1,0,3,2] row_mask:0xf bank_mask:0xf
	v_mov_b32_dpp v239, v223 quad_perm:[1,0,3,2] row_mask:0xf bank_mask:0xf
	v_mov_b32_dpp v240, v224 quad_perm:[1,0,3,2] row_mask:0xf bank_mask:0xf
	v_mov_b32_dpp v241, v225 quad_perm:[1,0,3,2] row_mask:0xf bank_mask:0xf
	v_cndmask_b32_e64 v214, v118, v238, s[100:101]
	v_cndmask_b32_e64 v218, v238, v114, s[100:101]
	v_cndmask_b32_e64 v215, v119, v239, s[100:101]
	v_cndmask_b32_e64 v219, v239, v115, s[100:101]
	v_cndmask_b32_e64 v216, v120, v240, s[100:101]
	v_cndmask_b32_e64 v220, v240, v116, s[100:101]
	v_cndmask_b32_e64 v217, v121, v241, s[100:101]
	v_cndmask_b32_e64 v221, v241, v117, s[100:101]
	v_lshl_add_u64 v[226:227], v[146:147], 0, v[242:243]
	global_store_dwordx4 v[226:227], v[214:217], off offset:-3584
	global_store_dwordx4 v[226:227], v[218:221], off offset:512
	v_pk_mul_f32 v[124:125], v[58:59], v[114:115]
	v_pk_mul_f32 v[120:121], v[64:65], v[120:121]
	v_pk_mul_f32 v[118:119], v[62:63], v[118:119]
	s_waitcnt lgkmcnt(0)
	v_add_f32_e32 v114, v126, v127
	ds_bpermute_b32 v115, v195, v114
	v_pk_mul_f32 v[122:123], v[60:61], v[116:117]
	v_cvt_pk_bf16_f32 v116, v118, v119
	v_cvt_pk_bf16_f32 v117, v120, v121
	v_cvt_pk_bf16_f32 v118, v124, v125
	v_cvt_pk_bf16_f32 v119, v122, v123
	global_store_dwordx4 v[144:145], v[116:119], off offset:256
	s_and_saveexec_b64 s[34:35], s[38:39]
	s_cbranch_execz .LBB0_1229
;     __device__ __forceinline__ void operator()(const f32x4 (&acc)[2][2][4][2], const pg8::Unit& u, int wr, int wc, int fr, int fq) const {
;     ...
;                 if (fq == 0) stat[(size_t)R * 16 + u.pn * 4 + wc] = ss;
	v_lshlrev_b64 v[116:117], 6, v[130:131]
	v_lshl_add_u64 v[116:117], s[62:63], 0, v[116:117]
	v_lshl_add_u64 v[116:117], s[24:25], 2, v[116:117]
	s_lshl_b32 s0, s56, 2
	v_lshl_add_u64 v[116:117], v[116:117], 0, s[0:1]
	s_waitcnt lgkmcnt(0)
	v_add_f32_e32 v114, v114, v115
	global_store_dword v[116:117], v114, off

; __device__ __forceinline__ unsigned pk2(float lo, float hi) { return pg8::cvt_pk_bf16(lo, hi); }
;     __device__ __forceinline__ void operator()(const f32x4 (&acc)[2][2][4][2], const pg8::Unit& u, int wr, int wc, int fr, int fq) const {
;     ...
;                 const int R = rowbase + u.pm * 256 + ai * 128 + wr * 64 + m * 16 + fr;
;                 const float* src = islat ? rin_l + (size_t)R * DM : rin_c + (size_t)(R - TL) * DM;
;                 float* dst = islat ? rout_l + (size_t)R * DM : rout_c + (size_t)(R - TL) * DM;
;                 float ss = 0.f;
; #pragma unroll
;                 for (int bj = 0; bj < 2; ++bj) { const int c = u.pn * 256 + bj * 128 + wc * 32 + 8 * fq;
;                     const f32x4 xa = *(const f32x4*)(src + c) + gv[bj][0] * acc[ai][bj][m][0];
;                     const f32x4 xb = *(const f32x4*)(src + c + 4) + gv[bj][1] * acc[ai][bj][m][1];
;                     *(f32x4*)(dst + c) = xa; *(f32x4*)(dst + c + 4) = xb;
;                     ss += (xa[0] * xa[0] + xa[1] * xa[1]) + (xa[2] * xa[2] + xa[3] * xa[3]) + (xb[0] * xb[0] + xb[1] * xb[1]) + (xb[2] * xb[2] + xb[3] * xb[3]);
;                     const f32x4 ya = xa * sv[bj][0], yb = xb * sv[bj][1];
;                     u32x4 w; w.x = pk2(ya[0], ya[1]); w.y = pk2(ya[2], ya[3]); w.z = pk2(yb[0], yb[1]); w.w = pk2(yb[2], yb[3]);
;                     *(u32x4*)(Hn + (size_t)R * DM + c) = w; }
;                 ss += __shfl_xor(ss, 16); ss += __shfl_xor(ss, 32);
;                 if (fq == 0) stat[(size_t)R * 16 + u.pn * 4 + wc] = ss;
.LBB0_1233:
	v_cndmask_b32_e64 v118, v118, v114, s[42:43]
	v_ashrrev_i32_e32 v119, 31, v118
	v_lshlrev_b64 v[118:119], 12, v[118:119]
	v_lshl_add_u64 v[118:119], s[68:69], 0, v[118:119]
	v_lshl_add_u64 v[126:127], v[118:119], 0, v[188:189]
	v_lshl_add_u64 v[226:227], v[126:127], 0, v[242:243]
	global_load_dwordx4 v[214:217], v[226:227], off offset:-4096 nt
	global_load_dwordx4 v[218:221], v[226:227], off nt
	v_lshlrev_b64 v[128:129], 11, v[114:115]
	v_lshl_add_u64 v[130:131], v[116:117], 0, v[188:189]
	v_lshl_add_u64 v[116:117], s[60:61], 0, v[128:129]
	v_lshl_add_u64 v[128:129], v[186:187], 1, v[116:117]
	s_waitcnt vmcnt(0)
	v_cndmask_b32_e64 v222, v218, v214, s[100:101]
	v_cndmask_b32_e64 v223, v219, v215, s[100:101]
	v_cndmask_b32_e64 v224, v220, v216, s[100:101]
	v_cndmask_b32_e64 v225, v221, v217, s[100:101]
	v_mov_b32_dpp v238, v222 quad_perm:[1,0,3,2] row_mask:0xf bank_mask:0xf
	v_mov_b32_dpp v239, v223 quad_perm:[1,0,3,2] row_mask:0xf bank_mask:0xf
	v_mov_b32_dpp v240, v224 quad_perm:[1,0,3,2] row_mask:0xf bank_mask:0xf
	v_mov_b32_dpp v241, v225 quad_perm:[1,0,3,2] row_mask:0xf bank_mask:0xf
	v_cndmask_b32_e64 v118, v214, v238, s[100:101]
	v_cndmask_b32_e64 v122, v238, v218, s[100:101]
	v_cndmask_b32_e64 v119, v215, v239, s[100:101]
	v_cndmask_b32_e64 v123, v239, v219, s[100:101]
	v_cndmask_b32_e64 v120, v216, v240, s[100:101]
	v_cndmask_b32_e64 v124, v240, v220, s[100:101]
	v_cndmask_b32_e64 v121, v217, v241, s[100:101]
	v_cndmask_b32_e64 v125, v241, v221, s[100:101]
	v_pk_fma_f32 v[112:113], v[112:113], v[96:97], v[120:121]
	v_pk_fma_f32 v[110:111], v[110:111], v[94:95], v[118:119]
	s_waitcnt vmcnt(0)
	v_pk_fma_f32 v[108:109], v[108:109], v[88:89], v[124:125]
	v_pk_fma_f32 v[106:107], v[106:107], v[86:87], v[122:123]
	v_pk_mul_f32 v[118:119], v[92:93], v[112:113]
	v_pk_mul_f32 v[116:117], v[90:91], v[110:111]
	v_pk_mul_f32 v[120:121], v[84:85], v[108:109]
	v_pk_mul_f32 v[122:123], v[82:83], v[106:107]
	v_cvt_pk_bf16_f32 v116, v116, v117
	v_cvt_pk_bf16_f32 v117, v118, v119
	v_cvt_pk_bf16_f32 v118, v122, v123
	v_cvt_pk_bf16_f32 v119, v120, v121
	v_cndmask_b32_e64 v222, v106, v110, s[100:101]
	v_cndmask_b32_e64 v223, v107, v111, s[100:101]
	v_cndmask_b32_e64 v224, v108, v112, s[100:101]
	v_cndmask_b32_e64 v225, v109, v113, s[100:101]
	v_mov_b32_dpp v238, v222 quad_perm:[1,0,3,2] row_mask:0xf bank_mask:0xf
	v_mov_b32_dpp v239, v223 quad_perm:[1,0,3,2] row_mask:0xf bank_mask:0xf
	v_mov_b32_dpp v240, v224 quad_perm:[1,0,3,2] row_mask:0xf bank_mask:0xf
	v_mov_b32_dpp v241, v225 quad_perm:[1,0,3,2] row_mask:0xf bank_mask:0xf
	v_cndmask_b32_e64 v214, v110, v238, s[100:101]
	v_cndmask_b32_e64 v218, v238, v106, s[100:101]
	v_cndmask_b32_e64 v215, v111, v239, s[100:101]
	v_cndmask_b32_e64 v219, v239, v107, s[100:101]
	v_cndmask_b32_e64 v216, v112, v240, s[100:101]
	v_cndmask_b32_e64 v220, v240, v108, s[100:101]
	v_cndmask_b32_e64 v217, v113, v241, s[100:101]
	v_cndmask_b32_e64 v221, v241, v109, s[100:101]
	v_lshl_add_u64 v[226:227], v[130:131], 0, v[242:243]
	global_store_dwordx4 v[226:227], v[214:217], off offset:-4096
	global_store_dwordx4 v[226:227], v[218:221], off
	global_store_dwordx4 v[128:129], v[116:119], off
	v_lshl_add_u64 v[226:227], v[126:127], 0, v[242:243]
	global_load_dwordx4 v[214:217], v[226:227], off offset:-3584 nt
	global_load_dwordx4 v[218:221], v[226:227], off offset:512 nt
	s_nop 0
	v_mul_f32_e32 v111, v111, v111
	v_mul_f32_e32 v113, v113, v113
	v_mul_f32_e32 v107, v107, v107
	v_fmac_f32_e32 v111, v110, v110
	v_fmac_f32_e32 v113, v112, v112
	v_mul_f32_e32 v109, v109, v109
	v_fmac_f32_e32 v107, v106, v106
	v_add_f32_e32 v106, v111, v113
	v_fmac_f32_e32 v109, v108, v108
	v_add_f32_e32 v106, v106, v107
	v_add_f32_e32 v106, v109, v106
	s_waitcnt vmcnt(0)
	v_cndmask_b32_e64 v222, v218, v214, s[100:101]
	v_cndmask_b32_e64 v223, v219, v215, s[100:101]
	v_cndmask_b32_e64 v224, v220, v216, s[100:101]
	v_cndmask_b32_e64 v225, v221, v217, s[100:101]
	v_mov_b32_dpp v238, v222 quad_perm:[1,0,3,2] row_mask:0xf bank_mask:0xf
	v_mov_b32_dpp v239, v223 quad_perm:[1,0,3,2] row_mask:0xf bank_mask:0xf
	v_mov_b32_dpp v240, v224 quad_perm:[1,0,3,2] row_mask:0xf bank_mask:0xf
	v_mov_b32_dpp v241, v225 quad_perm:[1,0,3,2] row_mask:0xf bank_mask:0xf
	v_cndmask_b32_e64 v116, v214, v238, s[100:101]
	v_cndmask_b32_e64 v120, v238, v218, s[100:101]
	v_cndmask_b32_e64 v117, v215, v239, s[100:101]
	v_cndmask_b32_e64 v121, v239, v219, s[100:101]
	v_cndmask_b32_e64 v118, v216, v240, s[100:101]
	v_cndmask_b32_e64 v122, v240, v220, s[100:101]
	v_cndmask_b32_e64 v119, v217, v241, s[100:101]
	v_cndmask_b32_e64 v123, v241, v221, s[100:101]
	v_pk_fma_f32 v[104:105], v[104:105], v[80:81], v[118:119]
	v_pk_fma_f32 v[102:103], v[102:103], v[78:79], v[116:117]
	s_waitcnt vmcnt(0)
	v_pk_fma_f32 v[98:99], v[98:99], v[74:75], v[120:121]
	v_mul_f32_e32 v107, v103, v103
	v_mul_f32_e32 v108, v105, v105
	v_pk_fma_f32 v[100:101], v[100:101], v[76:77], v[122:123]
	v_mul_f32_e32 v109, v99, v99
	v_fmac_f32_e32 v107, v102, v102
	v_fmac_f32_e32 v108, v104, v104
	v_mul_f32_e32 v110, v101, v101
	v_fmac_f32_e32 v109, v98, v98
	v_add_f32_e32 v107, v107, v108
	v_fmac_f32_e32 v110, v100, v100
	v_add_f32_e32 v107, v107, v109
	v_add_f32_e32 v107, v110, v107
	v_add_f32_e32 v110, v106, v107
	ds_bpermute_b32 v111, v200, v110
	v_cndmask_b32_e64 v222, v98, v102, s[100:101]
	v_cndmask_b32_e64 v223, v99, v103, s[100:101]
	v_cndmask_b32_e64 v224, v100, v104, s[100:101]
	v_cndmask_b32_e64 v225, v101, v105, s[100:101]
	v_mov_b32_dpp v238, v222 quad_perm:[1,0,3,2] row_mask:0xf bank_mask:0xf
	v_mov_b32_dpp v239, v223 quad_perm:[1,0,3,2] row_mask:0xf bank_mask:0xf
	v_mov_b32_dpp v240, v224 quad_perm:[1,0,3,2] row_mask:0xf bank_mask:0xf
	v_mov_b32_dpp v241, v225 quad_perm:[1,0,3,2] row_mask:0xf bank_mask:0xf
	v_cndmask_b32_e64 v214, v102, v238, s[100:101]
	v_cndmask_b32_e64 v218, v238, v98, s[100:101]
	v_cndmask_b32_e64 v215, v103, v239, s[100:101]
	v_cndmask_b32_e64 v219, v239, v99, s[100:101]
	v_cndmask_b32_e64 v216, v104, v240, s[100:101]
	v_cndmask_b32_e64 v220, v240, v100, s[100:101]
	v_cndmask_b32_e64 v217, v105, v241, s[100:101]
	v_cndmask_b32_e64 v221, v241, v101, s[100:101]
	v_lshl_add_u64 v[226:227], v[130:131], 0, v[242:243]
	global_store_dwordx4 v[226:227], v[214:217], off offset:-3584
	global_store_dwordx4 v[226:227], v[218:221], off offset:512
	v_pk_mul_f32 v[108:109], v[58:59], v[98:99]
	v_pk_mul_f32 v[104:105], v[64:65], v[104:105]
	v_pk_mul_f32 v[102:103], v[62:63], v[102:103]
	s_waitcnt lgkmcnt(0)
	v_add_f32_e32 v98, v110, v111
	ds_bpermute_b32 v99, v195, v98
	v_pk_mul_f32 v[106:107], v[60:61], v[100:101]
	v_cvt_pk_bf16_f32 v100, v102, v103
	v_cvt_pk_bf16_f32 v101, v104, v105
	v_cvt_pk_bf16_f32 v102, v108, v109
	v_cvt_pk_bf16_f32 v103, v106, v107
	global_store_dwordx4 v[128:129], v[100:103], off offset:256
	s_and_saveexec_b64 s[34:35], s[38:39]
	s_cbranch_execz .LBB0_1235
;     __device__ __forceinline__ void operator()(const f32x4 (&acc)[2][2][4][2], const pg8::Unit& u, int wr, int wc, int fr, int fq) const {
;     ...
;                 if (fq == 0) stat[(size_t)R * 16 + u.pn * 4 + wc] = ss;
	v_lshlrev_b64 v[100:101], 6, v[114:115]
	v_lshl_add_u64 v[100:101], s[62:63], 0, v[100:101]
	v_lshl_add_u64 v[100:101], s[24:25], 2, v[100:101]
	s_lshl_b32 s0, s56, 2
	v_lshl_add_u64 v[100:101], v[100:101], 0, s[0:1]
	s_waitcnt lgkmcnt(0)
	v_add_f32_e32 v98, v98, v99
	global_store_dword v[100:101], v98, off

; __device__ __forceinline__ unsigned pk2(float lo, float hi) { return pg8::cvt_pk_bf16(lo, hi); }
;     __device__ __forceinline__ void operator()(const f32x4 (&acc)[2][2][4][2], const pg8::Unit& u, int wr, int wc, int fr, int fq) const {
;     ...
;                 const int R = rowbase + u.pm * 256 + ai * 128 + wr * 64 + m * 16 + fr;
;                 const float* src = islat ? rin_l + (size_t)R * DM : rin_c + (size_t)(R - TL) * DM;
;                 float* dst = islat ? rout_l + (size_t)R * DM : rout_c + (size_t)(R - TL) * DM;
;                 float ss = 0.f;
; #pragma unroll
;                 for (int bj = 0; bj < 2; ++bj) { const int c = u.pn * 256 + bj * 128 + wc * 32 + 8 * fq;
;                     const f32x4 xa = *(const f32x4*)(src + c) + gv[bj][0] * acc[ai][bj][m][0];
;                     const f32x4 xb = *(const f32x4*)(src + c + 4) + gv[bj][1] * acc[ai][bj][m][1];
;                     *(f32x4*)(dst + c) = xa; *(f32x4*)(dst + c + 4) = xb;
;                     ss += (xa[0] * xa[0] + xa[1] * xa[1]) + (xa[2] * xa[2] + xa[3] * xa[3]) + (xb[0] * xb[0] + xb[1] * xb[1]) + (xb[2] * xb[2] + xb[3] * xb[3]);
;                     const f32x4 ya = xa * sv[bj][0], yb = xb * sv[bj][1];
;                     u32x4 w; w.x = pk2(ya[0], ya[1]); w.y = pk2(ya[2], ya[3]); w.z = pk2(yb[0], yb[1]); w.w = pk2(yb[2], yb[3]);
;                     *(u32x4*)(Hn + (size_t)R * DM + c) = w; }
;                 ss += __shfl_xor(ss, 16); ss += __shfl_xor(ss, 32);
;                 if (fq == 0) stat[(size_t)R * 16 + u.pn * 4 + wc] = ss;
.LBB0_1239:
	v_cndmask_b32_e64 v102, v102, v98, s[42:43]
	v_ashrrev_i32_e32 v103, 31, v102
	v_lshlrev_b64 v[102:103], 12, v[102:103]
	v_lshl_add_u64 v[102:103], s[68:69], 0, v[102:103]
	v_lshl_add_u64 v[110:111], v[102:103], 0, v[188:189]
	v_lshl_add_u64 v[226:227], v[110:111], 0, v[242:243]
	global_load_dwordx4 v[214:217], v[226:227], off offset:-4096 nt
	global_load_dwordx4 v[218:221], v[226:227], off nt
	v_lshlrev_b64 v[112:113], 11, v[98:99]
	v_lshl_add_u64 v[114:115], v[100:101], 0, v[188:189]
	v_lshl_add_u64 v[100:101], s[60:61], 0, v[112:113]
	v_lshl_add_u64 v[112:113], v[186:187], 1, v[100:101]
	s_waitcnt vmcnt(0)
	v_cndmask_b32_e64 v222, v218, v214, s[100:101]
	v_cndmask_b32_e64 v223, v219, v215, s[100:101]
	v_cndmask_b32_e64 v224, v220, v216, s[100:101]
	v_cndmask_b32_e64 v225, v221, v217, s[100:101]
	v_mov_b32_dpp v238, v222 quad_perm:[1,0,3,2] row_mask:0xf bank_mask:0xf
	v_mov_b32_dpp v239, v223 quad_perm:[1,0,3,2] row_mask:0xf bank_mask:0xf
	v_mov_b32_dpp v240, v224 quad_perm:[1,0,3,2] row_mask:0xf bank_mask:0xf
	v_mov_b32_dpp v241, v225 quad_perm:[1,0,3,2] row_mask:0xf bank_mask:0xf
	v_cndmask_b32_e64 v102, v214, v238, s[100:101]
	v_cndmask_b32_e64 v106, v238, v218, s[100:101]
	v_cndmask_b32_e64 v103, v215, v239, s[100:101]
	v_cndmask_b32_e64 v107, v239, v219, s[100:101]
	v_cndmask_b32_e64 v104, v216, v240, s[100:101]
	v_cndmask_b32_e64 v108, v240, v220, s[100:101]
	v_cndmask_b32_e64 v105, v217, v241, s[100:101]
	v_cndmask_b32_e64 v109, v241, v221, s[100:101]
	v_pk_fma_f32 v[72:73], v[72:73], v[96:97], v[104:105]
	v_pk_fma_f32 v[70:71], v[70:71], v[94:95], v[102:103]
	s_waitcnt vmcnt(0)
	v_pk_fma_f32 v[68:69], v[68:69], v[88:89], v[108:109]
	v_pk_fma_f32 v[66:67], v[66:67], v[86:87], v[106:107]
	v_pk_mul_f32 v[102:103], v[92:93], v[72:73]
	v_pk_mul_f32 v[100:101], v[90:91], v[70:71]
	v_pk_mul_f32 v[104:105], v[84:85], v[68:69]
	v_pk_mul_f32 v[106:107], v[82:83], v[66:67]
	v_cvt_pk_bf16_f32 v100, v100, v101
	v_cvt_pk_bf16_f32 v101, v102, v103
	v_cvt_pk_bf16_f32 v102, v106, v107
	v_cvt_pk_bf16_f32 v103, v104, v105
	v_cndmask_b32_e64 v222, v66, v70, s[100:101]
	v_cndmask_b32_e64 v223, v67, v71, s[100:101]
	v_cndmask_b32_e64 v224, v68, v72, s[100:101]
	v_cndmask_b32_e64 v225, v69, v73, s[100:101]
	v_mov_b32_dpp v238, v222 quad_perm:[1,0,3,2] row_mask:0xf bank_mask:0xf
	v_mov_b32_dpp v239, v223 quad_perm:[1,0,3,2] row_mask:0xf bank_mask:0xf
	v_mov_b32_dpp v240, v224 quad_perm:[1,0,3,2] row_mask:0xf bank_mask:0xf
	v_mov_b32_dpp v241, v225 quad_perm:[1,0,3,2] row_mask:0xf bank_mask:0xf
	v_cndmask_b32_e64 v214, v70, v238, s[100:101]
	v_cndmask_b32_e64 v218, v238, v66, s[100:101]
	v_cndmask_b32_e64 v215, v71, v239, s[100:101]
	v_cndmask_b32_e64 v219, v239, v67, s[100:101]
	v_cndmask_b32_e64 v216, v72, v240, s[100:101]
	v_cndmask_b32_e64 v220, v240, v68, s[100:101]
	v_cndmask_b32_e64 v217, v73, v241, s[100:101]
	v_cndmask_b32_e64 v221, v241, v69, s[100:101]
	v_lshl_add_u64 v[226:227], v[114:115], 0, v[242:243]
	global_store_dwordx4 v[226:227], v[214:217], off offset:-4096
	global_store_dwordx4 v[226:227], v[218:221], off
	global_store_dwordx4 v[112:113], v[100:103], off
	v_lshl_add_u64 v[226:227], v[110:111], 0, v[242:243]
	global_load_dwordx4 v[214:217], v[226:227], off offset:-3584 nt
	global_load_dwordx4 v[218:221], v[226:227], off offset:512 nt
	s_nop 0
	v_mul_f32_e32 v71, v71, v71
	v_mul_f32_e32 v73, v73, v73
	v_mul_f32_e32 v67, v67, v67
	v_fmac_f32_e32 v71, v70, v70
	v_fmac_f32_e32 v73, v72, v72
	v_mul_f32_e32 v69, v69, v69
	v_fmac_f32_e32 v67, v66, v66
	v_add_f32_e32 v66, v71, v73
	v_fmac_f32_e32 v69, v68, v68
	v_add_f32_e32 v66, v66, v67
	v_add_f32_e32 v66, v69, v66
	s_waitcnt vmcnt(0)
	v_cndmask_b32_e64 v222, v218, v214, s[100:101]
	v_cndmask_b32_e64 v223, v219, v215, s[100:101]
	v_cndmask_b32_e64 v224, v220, v216, s[100:101]
	v_cndmask_b32_e64 v225, v221, v217, s[100:101]
	v_mov_b32_dpp v238, v222 quad_perm:[1,0,3,2] row_mask:0xf bank_mask:0xf
	v_mov_b32_dpp v239, v223 quad_perm:[1,0,3,2] row_mask:0xf bank_mask:0xf
	v_mov_b32_dpp v240, v224 quad_perm:[1,0,3,2] row_mask:0xf bank_mask:0xf
	v_mov_b32_dpp v241, v225 quad_perm:[1,0,3,2] row_mask:0xf bank_mask:0xf
	v_cndmask_b32_e64 v100, v214, v238, s[100:101]
	v_cndmask_b32_e64 v104, v238, v218, s[100:101]
	v_cndmask_b32_e64 v101, v215, v239, s[100:101]
	v_cndmask_b32_e64 v105, v239, v219, s[100:101]
	v_cndmask_b32_e64 v102, v216, v240, s[100:101]
	v_cndmask_b32_e64 v106, v240, v220, s[100:101]
	v_cndmask_b32_e64 v103, v217, v241, s[100:101]
	v_cndmask_b32_e64 v107, v241, v221, s[100:101]
	v_pk_fma_f32 v[56:57], v[56:57], v[80:81], v[102:103]
	v_pk_fma_f32 v[54:55], v[54:55], v[78:79], v[100:101]
	s_waitcnt vmcnt(0)
	v_pk_fma_f32 v[50:51], v[50:51], v[74:75], v[104:105]
	v_mul_f32_e32 v67, v55, v55
	v_mul_f32_e32 v68, v57, v57
	v_pk_fma_f32 v[52:53], v[52:53], v[76:77], v[106:107]
	v_mul_f32_e32 v69, v51, v51
	v_fmac_f32_e32 v67, v54, v54
	v_fmac_f32_e32 v68, v56, v56
	v_mul_f32_e32 v70, v53, v53
	v_fmac_f32_e32 v69, v50, v50
	v_add_f32_e32 v67, v67, v68
	v_fmac_f32_e32 v70, v52, v52
	v_add_f32_e32 v67, v67, v69
	v_add_f32_e32 v67, v70, v67
	v_add_f32_e32 v70, v66, v67
	ds_bpermute_b32 v71, v200, v70
	v_cndmask_b32_e64 v222, v50, v54, s[100:101]
	v_cndmask_b32_e64 v223, v51, v55, s[100:101]
	v_cndmask_b32_e64 v224, v52, v56, s[100:101]
	v_cndmask_b32_e64 v225, v53, v57, s[100:101]
	v_mov_b32_dpp v238, v222 quad_perm:[1,0,3,2] row_mask:0xf bank_mask:0xf
	v_mov_b32_dpp v239, v223 quad_perm:[1,0,3,2] row_mask:0xf bank_mask:0xf
	v_mov_b32_dpp v240, v224 quad_perm:[1,0,3,2] row_mask:0xf bank_mask:0xf
	v_mov_b32_dpp v241, v225 quad_perm:[1,0,3,2] row_mask:0xf bank_mask:0xf
	v_cndmask_b32_e64 v214, v54, v238, s[100:101]
	v_cndmask_b32_e64 v218, v238, v50, s[100:101]
	v_cndmask_b32_e64 v215, v55, v239, s[100:101]
	v_cndmask_b32_e64 v219, v239, v51, s[100:101]
	v_cndmask_b32_e64 v216, v56, v240, s[100:101]
	v_cndmask_b32_e64 v220, v240, v52, s[100:101]
	v_cndmask_b32_e64 v217, v57, v241, s[100:101]
	v_cndmask_b32_e64 v221, v241, v53, s[100:101]
	v_lshl_add_u64 v[226:227], v[114:115], 0, v[242:243]
	global_store_dwordx4 v[226:227], v[214:217], off offset:-3584
	global_store_dwordx4 v[226:227], v[218:221], off offset:512
	v_pk_mul_f32 v[68:69], v[58:59], v[50:51]
	v_pk_mul_f32 v[56:57], v[64:65], v[56:57]
	v_pk_mul_f32 v[54:55], v[62:63], v[54:55]
	s_waitcnt lgkmcnt(0)
	v_add_f32_e32 v50, v70, v71
	ds_bpermute_b32 v51, v195, v50
	v_pk_mul_f32 v[66:67], v[60:61], v[52:53]
	v_cvt_pk_bf16_f32 v52, v54, v55
	v_cvt_pk_bf16_f32 v53, v56, v57
	v_cvt_pk_bf16_f32 v54, v68, v69
	v_cvt_pk_bf16_f32 v55, v66, v67
	global_store_dwordx4 v[112:113], v[52:55], off offset:256
	s_and_saveexec_b64 s[34:35], s[38:39]
	s_cbranch_execz .LBB0_1241
	v_lshlrev_b64 v[52:53], 6, v[98:99]
	v_lshl_add_u64 v[52:53], s[62:63], 0, v[52:53]
	v_lshl_add_u64 v[52:53], s[24:25], 2, v[52:53]
	s_lshl_b32 s0, s56, 2
	v_lshl_add_u64 v[52:53], v[52:53], 0, s[0:1]
	s_waitcnt lgkmcnt(0)
	v_add_f32_e32 v50, v50, v51
	global_store_dword v[52:53], v50, off

; __device__ __forceinline__ unsigned pk2(float lo, float hi) { return pg8::cvt_pk_bf16(lo, hi); }
;     __device__ __forceinline__ void operator()(const f32x4 (&acc)[2][2][4][2], const pg8::Unit& u, int wr, int wc, int fr, int fq) const {
;     ...
;                 const int R = rowbase + u.pm * 256 + ai * 128 + wr * 64 + m * 16 + fr;
;                 const float* src = islat ? rin_l + (size_t)R * DM : rin_c + (size_t)(R - TL) * DM;
;                 float* dst = islat ? rout_l + (size_t)R * DM : rout_c + (size_t)(R - TL) * DM;
;                 float ss = 0.f;
; #pragma unroll
;                 for (int bj = 0; bj < 2; ++bj) { const int c = u.pn * 256 + bj * 128 + wc * 32 + 8 * fq;
;                     const f32x4 xa = *(const f32x4*)(src + c) + gv[bj][0] * acc[ai][bj][m][0];
;                     const f32x4 xb = *(const f32x4*)(src + c + 4) + gv[bj][1] * acc[ai][bj][m][1];
;                     *(f32x4*)(dst + c) = xa; *(f32x4*)(dst + c + 4) = xb;
;                     ss += (xa[0] * xa[0] + xa[1] * xa[1]) + (xa[2] * xa[2] + xa[3] * xa[3]) + (xb[0] * xb[0] + xb[1] * xb[1]) + (xb[2] * xb[2] + xb[3] * xb[3]);
;                     const f32x4 ya = xa * sv[bj][0], yb = xb * sv[bj][1];
;                     u32x4 w; w.x = pk2(ya[0], ya[1]); w.y = pk2(ya[2], ya[3]); w.z = pk2(yb[0], yb[1]); w.w = pk2(yb[2], yb[3]);
;                     *(u32x4*)(Hn + (size_t)R * DM + c) = w; }
;                 ss += __shfl_xor(ss, 16); ss += __shfl_xor(ss, 32);
;                 if (fq == 0) stat[(size_t)R * 16 + u.pn * 4 + wc] = ss;
.LBB0_1245:
	v_cndmask_b32_e64 v54, v54, v50, s[42:43]
	v_ashrrev_i32_e32 v55, 31, v54
	v_lshlrev_b64 v[54:55], 12, v[54:55]
	v_lshl_add_u64 v[54:55], s[68:69], 0, v[54:55]
	v_lshl_add_u64 v[70:71], v[54:55], 0, v[188:189]
	v_lshl_add_u64 v[226:227], v[70:71], 0, v[242:243]
	global_load_dwordx4 v[214:217], v[226:227], off offset:-4096 nt
	global_load_dwordx4 v[218:221], v[226:227], off nt
	v_lshlrev_b64 v[72:73], 11, v[50:51]
	v_lshl_add_u64 v[98:99], v[52:53], 0, v[188:189]
	v_lshl_add_u64 v[52:53], s[60:61], 0, v[72:73]
	v_lshl_add_u64 v[72:73], v[186:187], 1, v[52:53]
	s_waitcnt vmcnt(0)
	v_cndmask_b32_e64 v222, v218, v214, s[100:101]
	v_cndmask_b32_e64 v223, v219, v215, s[100:101]
	v_cndmask_b32_e64 v224, v220, v216, s[100:101]
	v_cndmask_b32_e64 v225, v221, v217, s[100:101]
	v_mov_b32_dpp v238, v222 quad_perm:[1,0,3,2] row_mask:0xf bank_mask:0xf
	v_mov_b32_dpp v239, v223 quad_perm:[1,0,3,2] row_mask:0xf bank_mask:0xf
	v_mov_b32_dpp v240, v224 quad_perm:[1,0,3,2] row_mask:0xf bank_mask:0xf
	v_mov_b32_dpp v241, v225 quad_perm:[1,0,3,2] row_mask:0xf bank_mask:0xf
	v_cndmask_b32_e64 v54, v214, v238, s[100:101]
	v_cndmask_b32_e64 v66, v238, v218, s[100:101]
	v_cndmask_b32_e64 v55, v215, v239, s[100:101]
	v_cndmask_b32_e64 v67, v239, v219, s[100:101]
	v_cndmask_b32_e64 v56, v216, v240, s[100:101]
	v_cndmask_b32_e64 v68, v240, v220, s[100:101]
	v_cndmask_b32_e64 v57, v217, v241, s[100:101]
	v_cndmask_b32_e64 v69, v241, v221, s[100:101]
	v_pk_fma_f32 v[48:49], v[48:49], v[96:97], v[56:57]
	v_pk_fma_f32 v[46:47], v[46:47], v[94:95], v[54:55]
	s_waitcnt vmcnt(0)
	v_pk_fma_f32 v[44:45], v[44:45], v[88:89], v[68:69]
	v_pk_fma_f32 v[42:43], v[42:43], v[86:87], v[66:67]
	v_pk_mul_f32 v[54:55], v[92:93], v[48:49]
	v_pk_mul_f32 v[52:53], v[90:91], v[46:47]
	v_pk_mul_f32 v[56:57], v[84:85], v[44:45]
	v_pk_mul_f32 v[66:67], v[82:83], v[42:43]
	v_cvt_pk_bf16_f32 v52, v52, v53
	v_cvt_pk_bf16_f32 v53, v54, v55
	v_cvt_pk_bf16_f32 v54, v66, v67
	v_cvt_pk_bf16_f32 v55, v56, v57
	v_cndmask_b32_e64 v222, v42, v46, s[100:101]
	v_cndmask_b32_e64 v223, v43, v47, s[100:101]
	v_cndmask_b32_e64 v224, v44, v48, s[100:101]
	v_cndmask_b32_e64 v225, v45, v49, s[100:101]
	v_mov_b32_dpp v238, v222 quad_perm:[1,0,3,2] row_mask:0xf bank_mask:0xf
	v_mov_b32_dpp v239, v223 quad_perm:[1,0,3,2] row_mask:0xf bank_mask:0xf
	v_mov_b32_dpp v240, v224 quad_perm:[1,0,3,2] row_mask:0xf bank_mask:0xf
	v_mov_b32_dpp v241, v225 quad_perm:[1,0,3,2] row_mask:0xf bank_mask:0xf
	v_cndmask_b32_e64 v214, v46, v238, s[100:101]
	v_cndmask_b32_e64 v218, v238, v42, s[100:101]
	v_cndmask_b32_e64 v215, v47, v239, s[100:101]
	v_cndmask_b32_e64 v219, v239, v43, s[100:101]
	v_cndmask_b32_e64 v216, v48, v240, s[100:101]
	v_cndmask_b32_e64 v220, v240, v44, s[100:101]
	v_cndmask_b32_e64 v217, v49, v241, s[100:101]
	v_cndmask_b32_e64 v221, v241, v45, s[100:101]
	v_lshl_add_u64 v[226:227], v[98:99], 0, v[242:243]
	global_store_dwordx4 v[226:227], v[214:217], off offset:-4096
	global_store_dwordx4 v[226:227], v[218:221], off
	global_store_dwordx4 v[72:73], v[52:55], off
	v_lshl_add_u64 v[226:227], v[70:71], 0, v[242:243]
	global_load_dwordx4 v[214:217], v[226:227], off offset:-3584 nt
	global_load_dwordx4 v[218:221], v[226:227], off offset:512 nt
	s_nop 0
	v_mul_f32_e32 v47, v47, v47
	v_mul_f32_e32 v49, v49, v49
	v_mul_f32_e32 v43, v43, v43
	v_fmac_f32_e32 v47, v46, v46
	v_fmac_f32_e32 v49, v48, v48
	v_mul_f32_e32 v45, v45, v45
	v_fmac_f32_e32 v43, v42, v42
	v_add_f32_e32 v42, v47, v49
	v_fmac_f32_e32 v45, v44, v44
	v_add_f32_e32 v42, v42, v43
	v_add_f32_e32 v42, v45, v42
	s_waitcnt vmcnt(0)
	v_cndmask_b32_e64 v222, v218, v214, s[100:101]
	v_cndmask_b32_e64 v223, v219, v215, s[100:101]
	v_cndmask_b32_e64 v224, v220, v216, s[100:101]
	v_cndmask_b32_e64 v225, v221, v217, s[100:101]
	v_mov_b32_dpp v238, v222 quad_perm:[1,0,3,2] row_mask:0xf bank_mask:0xf
	v_mov_b32_dpp v239, v223 quad_perm:[1,0,3,2] row_mask:0xf bank_mask:0xf
	v_mov_b32_dpp v240, v224 quad_perm:[1,0,3,2] row_mask:0xf bank_mask:0xf
	v_mov_b32_dpp v241, v225 quad_perm:[1,0,3,2] row_mask:0xf bank_mask:0xf
	v_cndmask_b32_e64 v52, v214, v238, s[100:101]
	v_cndmask_b32_e64 v66, v238, v218, s[100:101]
	v_cndmask_b32_e64 v53, v215, v239, s[100:101]
	v_cndmask_b32_e64 v67, v239, v219, s[100:101]
	v_cndmask_b32_e64 v54, v216, v240, s[100:101]
	v_cndmask_b32_e64 v68, v240, v220, s[100:101]
	v_cndmask_b32_e64 v55, v217, v241, s[100:101]
	v_cndmask_b32_e64 v69, v241, v221, s[100:101]
	v_pk_fma_f32 v[40:41], v[40:41], v[80:81], v[54:55]
	v_pk_fma_f32 v[38:39], v[38:39], v[78:79], v[52:53]
	s_waitcnt vmcnt(0)
	v_pk_fma_f32 v[34:35], v[34:35], v[74:75], v[66:67]
	v_mul_f32_e32 v43, v39, v39
	v_mul_f32_e32 v44, v41, v41
	v_pk_fma_f32 v[36:37], v[36:37], v[76:77], v[68:69]
	v_mul_f32_e32 v45, v35, v35
	v_fmac_f32_e32 v43, v38, v38
	v_fmac_f32_e32 v44, v40, v40
	v_mul_f32_e32 v46, v37, v37
	v_fmac_f32_e32 v45, v34, v34
	v_add_f32_e32 v43, v43, v44
	v_fmac_f32_e32 v46, v36, v36
	v_add_f32_e32 v43, v43, v45
	v_add_f32_e32 v43, v46, v43
	v_add_f32_e32 v46, v42, v43
	ds_bpermute_b32 v47, v200, v46
	v_cndmask_b32_e64 v222, v34, v38, s[100:101]
	v_cndmask_b32_e64 v223, v35, v39, s[100:101]
	v_cndmask_b32_e64 v224, v36, v40, s[100:101]
	v_cndmask_b32_e64 v225, v37, v41, s[100:101]
	v_mov_b32_dpp v238, v222 quad_perm:[1,0,3,2] row_mask:0xf bank_mask:0xf
	v_mov_b32_dpp v239, v223 quad_perm:[1,0,3,2] row_mask:0xf bank_mask:0xf
	v_mov_b32_dpp v240, v224 quad_perm:[1,0,3,2] row_mask:0xf bank_mask:0xf
	v_mov_b32_dpp v241, v225 quad_perm:[1,0,3,2] row_mask:0xf bank_mask:0xf
	v_cndmask_b32_e64 v214, v38, v238, s[100:101]
	v_cndmask_b32_e64 v218, v238, v34, s[100:101]
	v_cndmask_b32_e64 v215, v39, v239, s[100:101]
	v_cndmask_b32_e64 v219, v239, v35, s[100:101]
	v_cndmask_b32_e64 v216, v40, v240, s[100:101]
	v_cndmask_b32_e64 v220, v240, v36, s[100:101]
	v_cndmask_b32_e64 v217, v41, v241, s[100:101]
	v_cndmask_b32_e64 v221, v241, v37, s[100:101]
	v_lshl_add_u64 v[226:227], v[98:99], 0, v[242:243]
	global_store_dwordx4 v[226:227], v[214:217], off offset:-3584
	global_store_dwordx4 v[226:227], v[218:221], off offset:512
	v_pk_mul_f32 v[44:45], v[58:59], v[34:35]
	v_pk_mul_f32 v[40:41], v[64:65], v[40:41]
	v_pk_mul_f32 v[38:39], v[62:63], v[38:39]
	s_waitcnt lgkmcnt(0)
	v_add_f32_e32 v34, v46, v47
	ds_bpermute_b32 v35, v195, v34
	v_pk_mul_f32 v[42:43], v[60:61], v[36:37]
	v_cvt_pk_bf16_f32 v36, v38, v39
	v_cvt_pk_bf16_f32 v37, v40, v41
	v_cvt_pk_bf16_f32 v38, v44, v45
	v_cvt_pk_bf16_f32 v39, v42, v43
	global_store_dwordx4 v[72:73], v[36:39], off offset:256
	s_and_saveexec_b64 s[34:35], s[38:39]
	s_cbranch_execz .LBB0_1247
	v_lshlrev_b64 v[36:37], 6, v[50:51]
	v_lshl_add_u64 v[36:37], s[62:63], 0, v[36:37]
	v_lshl_add_u64 v[36:37], s[24:25], 2, v[36:37]
	s_lshl_b32 s0, s56, 2
	v_lshl_add_u64 v[36:37], v[36:37], 0, s[0:1]
	s_waitcnt lgkmcnt(0)
	v_add_f32_e32 v34, v34, v35
	global_store_dword v[36:37], v34, off

; __device__ __forceinline__ unsigned pk2(float lo, float hi) { return pg8::cvt_pk_bf16(lo, hi); }
;     __device__ __forceinline__ void operator()(const f32x4 (&acc)[2][2][4][2], const pg8::Unit& u, int wr, int wc, int fr, int fq) const {
;     ...
;                 const int R = rowbase + u.pm * 256 + ai * 128 + wr * 64 + m * 16 + fr;
;                 const float* src = islat ? rin_l + (size_t)R * DM : rin_c + (size_t)(R - TL) * DM;
;                 float* dst = islat ? rout_l + (size_t)R * DM : rout_c + (size_t)(R - TL) * DM;
;                 float ss = 0.f;
; #pragma unroll
;                 for (int bj = 0; bj < 2; ++bj) { const int c = u.pn * 256 + bj * 128 + wc * 32 + 8 * fq;
;                     const f32x4 xa = *(const f32x4*)(src + c) + gv[bj][0] * acc[ai][bj][m][0];
;                     const f32x4 xb = *(const f32x4*)(src + c + 4) + gv[bj][1] * acc[ai][bj][m][1];
;                     *(f32x4*)(dst + c) = xa; *(f32x4*)(dst + c + 4) = xb;
;                     ss += (xa[0] * xa[0] + xa[1] * xa[1]) + (xa[2] * xa[2] + xa[3] * xa[3]) + (xb[0] * xb[0] + xb[1] * xb[1]) + (xb[2] * xb[2] + xb[3] * xb[3]);
;                     const f32x4 ya = xa * sv[bj][0], yb = xb * sv[bj][1];
;                     u32x4 w; w.x = pk2(ya[0], ya[1]); w.y = pk2(ya[2], ya[3]); w.z = pk2(yb[0], yb[1]); w.w = pk2(yb[2], yb[3]);
;                     *(u32x4*)(Hn + (size_t)R * DM + c) = w; }
;                 ss += __shfl_xor(ss, 16); ss += __shfl_xor(ss, 32);
;                 if (fq == 0) stat[(size_t)R * 16 + u.pn * 4 + wc] = ss;
.LBB0_1251:
	v_cndmask_b32_e64 v38, v38, v34, s[42:43]
	v_ashrrev_i32_e32 v39, 31, v38
	v_lshlrev_b64 v[38:39], 12, v[38:39]
	v_lshl_add_u64 v[38:39], s[68:69], 0, v[38:39]
	v_lshl_add_u64 v[46:47], v[38:39], 0, v[188:189]
	v_lshl_add_u64 v[226:227], v[46:47], 0, v[242:243]
	global_load_dwordx4 v[214:217], v[226:227], off offset:-4096 nt
	global_load_dwordx4 v[218:221], v[226:227], off nt
	v_lshlrev_b64 v[48:49], 11, v[34:35]
	v_lshl_add_u64 v[50:51], v[36:37], 0, v[188:189]
	v_lshl_add_u64 v[36:37], s[60:61], 0, v[48:49]
	v_lshl_add_u64 v[48:49], v[186:187], 1, v[36:37]
	s_waitcnt vmcnt(0)
	v_cndmask_b32_e64 v222, v218, v214, s[100:101]
	v_cndmask_b32_e64 v223, v219, v215, s[100:101]
	v_cndmask_b32_e64 v224, v220, v216, s[100:101]
	v_cndmask_b32_e64 v225, v221, v217, s[100:101]
	v_mov_b32_dpp v238, v222 quad_perm:[1,0,3,2] row_mask:0xf bank_mask:0xf
	v_mov_b32_dpp v239, v223 quad_perm:[1,0,3,2] row_mask:0xf bank_mask:0xf
	v_mov_b32_dpp v240, v224 quad_perm:[1,0,3,2] row_mask:0xf bank_mask:0xf
	v_mov_b32_dpp v241, v225 quad_perm:[1,0,3,2] row_mask:0xf bank_mask:0xf
	v_cndmask_b32_e64 v38, v214, v238, s[100:101]
	v_cndmask_b32_e64 v42, v238, v218, s[100:101]
	v_cndmask_b32_e64 v39, v215, v239, s[100:101]
	v_cndmask_b32_e64 v43, v239, v219, s[100:101]
	v_cndmask_b32_e64 v40, v216, v240, s[100:101]
	v_cndmask_b32_e64 v44, v240, v220, s[100:101]
	v_cndmask_b32_e64 v41, v217, v241, s[100:101]
	v_cndmask_b32_e64 v45, v241, v221, s[100:101]
	v_pk_fma_f32 v[32:33], v[32:33], v[96:97], v[40:41]
	v_pk_fma_f32 v[30:31], v[30:31], v[94:95], v[38:39]
	s_waitcnt vmcnt(0)
	v_pk_fma_f32 v[28:29], v[28:29], v[88:89], v[44:45]
	v_pk_fma_f32 v[26:27], v[26:27], v[86:87], v[42:43]
	v_pk_mul_f32 v[38:39], v[92:93], v[32:33]
	v_pk_mul_f32 v[36:37], v[90:91], v[30:31]
	v_pk_mul_f32 v[40:41], v[84:85], v[28:29]
	v_pk_mul_f32 v[42:43], v[82:83], v[26:27]
	v_cvt_pk_bf16_f32 v36, v36, v37
	v_cvt_pk_bf16_f32 v37, v38, v39
	v_cvt_pk_bf16_f32 v38, v42, v43
	v_cvt_pk_bf16_f32 v39, v40, v41
	v_cndmask_b32_e64 v222, v26, v30, s[100:101]
	v_cndmask_b32_e64 v223, v27, v31, s[100:101]
	v_cndmask_b32_e64 v224, v28, v32, s[100:101]
	v_cndmask_b32_e64 v225, v29, v33, s[100:101]
	v_mov_b32_dpp v238, v222 quad_perm:[1,0,3,2] row_mask:0xf bank_mask:0xf
	v_mov_b32_dpp v239, v223 quad_perm:[1,0,3,2] row_mask:0xf bank_mask:0xf
	v_mov_b32_dpp v240, v224 quad_perm:[1,0,3,2] row_mask:0xf bank_mask:0xf
	v_mov_b32_dpp v241, v225 quad_perm:[1,0,3,2] row_mask:0xf bank_mask:0xf
	v_cndmask_b32_e64 v214, v30, v238, s[100:101]
	v_cndmask_b32_e64 v218, v238, v26, s[100:101]
	v_cndmask_b32_e64 v215, v31, v239, s[100:101]
	v_cndmask_b32_e64 v219, v239, v27, s[100:101]
	v_cndmask_b32_e64 v216, v32, v240, s[100:101]
	v_cndmask_b32_e64 v220, v240, v28, s[100:101]
	v_cndmask_b32_e64 v217, v33, v241, s[100:101]
	v_cndmask_b32_e64 v221, v241, v29, s[100:101]
	v_lshl_add_u64 v[226:227], v[50:51], 0, v[242:243]
	global_store_dwordx4 v[226:227], v[214:217], off offset:-4096
	global_store_dwordx4 v[226:227], v[218:221], off
	global_store_dwordx4 v[48:49], v[36:39], off
	v_lshl_add_u64 v[226:227], v[46:47], 0, v[242:243]
	global_load_dwordx4 v[214:217], v[226:227], off offset:-3584 nt
	global_load_dwordx4 v[218:221], v[226:227], off offset:512 nt
	s_nop 0
	v_mul_f32_e32 v31, v31, v31
	v_mul_f32_e32 v33, v33, v33
	v_mul_f32_e32 v27, v27, v27
	v_fmac_f32_e32 v31, v30, v30
	v_fmac_f32_e32 v33, v32, v32
	v_mul_f32_e32 v29, v29, v29
	v_fmac_f32_e32 v27, v26, v26
	v_add_f32_e32 v26, v31, v33
	v_fmac_f32_e32 v29, v28, v28
	v_add_f32_e32 v26, v26, v27
	v_add_f32_e32 v26, v29, v26
	s_waitcnt vmcnt(0)
	v_cndmask_b32_e64 v222, v218, v214, s[100:101]
	v_cndmask_b32_e64 v223, v219, v215, s[100:101]
	v_cndmask_b32_e64 v224, v220, v216, s[100:101]
	v_cndmask_b32_e64 v225, v221, v217, s[100:101]
	v_mov_b32_dpp v238, v222 quad_perm:[1,0,3,2] row_mask:0xf bank_mask:0xf
	v_mov_b32_dpp v239, v223 quad_perm:[1,0,3,2] row_mask:0xf bank_mask:0xf
	v_mov_b32_dpp v240, v224 quad_perm:[1,0,3,2] row_mask:0xf bank_mask:0xf
	v_mov_b32_dpp v241, v225 quad_perm:[1,0,3,2] row_mask:0xf bank_mask:0xf
	v_cndmask_b32_e64 v36, v214, v238, s[100:101]
	v_cndmask_b32_e64 v40, v238, v218, s[100:101]
	v_cndmask_b32_e64 v37, v215, v239, s[100:101]
	v_cndmask_b32_e64 v41, v239, v219, s[100:101]
	v_cndmask_b32_e64 v38, v216, v240, s[100:101]
	v_cndmask_b32_e64 v42, v240, v220, s[100:101]
	v_cndmask_b32_e64 v39, v217, v241, s[100:101]
	v_cndmask_b32_e64 v43, v241, v221, s[100:101]
	v_pk_fma_f32 v[24:25], v[24:25], v[80:81], v[38:39]
	v_pk_fma_f32 v[22:23], v[22:23], v[78:79], v[36:37]
	s_waitcnt vmcnt(0)
	v_pk_fma_f32 v[18:19], v[18:19], v[74:75], v[40:41]
	v_mul_f32_e32 v27, v23, v23
	v_mul_f32_e32 v28, v25, v25
	v_pk_fma_f32 v[20:21], v[20:21], v[76:77], v[42:43]
	v_mul_f32_e32 v29, v19, v19
	v_fmac_f32_e32 v27, v22, v22
	v_fmac_f32_e32 v28, v24, v24
	v_mul_f32_e32 v30, v21, v21
	v_fmac_f32_e32 v29, v18, v18
	v_add_f32_e32 v27, v27, v28
	v_fmac_f32_e32 v30, v20, v20
	v_add_f32_e32 v27, v27, v29
	v_add_f32_e32 v27, v30, v27
	v_add_f32_e32 v30, v26, v27
	ds_bpermute_b32 v31, v200, v30
	v_cndmask_b32_e64 v222, v18, v22, s[100:101]
	v_cndmask_b32_e64 v223, v19, v23, s[100:101]
	v_cndmask_b32_e64 v224, v20, v24, s[100:101]
	v_cndmask_b32_e64 v225, v21, v25, s[100:101]
	v_mov_b32_dpp v238, v222 quad_perm:[1,0,3,2] row_mask:0xf bank_mask:0xf
	v_mov_b32_dpp v239, v223 quad_perm:[1,0,3,2] row_mask:0xf bank_mask:0xf
	v_mov_b32_dpp v240, v224 quad_perm:[1,0,3,2] row_mask:0xf bank_mask:0xf
	v_mov_b32_dpp v241, v225 quad_perm:[1,0,3,2] row_mask:0xf bank_mask:0xf
	v_cndmask_b32_e64 v214, v22, v238, s[100:101]
	v_cndmask_b32_e64 v218, v238, v18, s[100:101]
	v_cndmask_b32_e64 v215, v23, v239, s[100:101]
	v_cndmask_b32_e64 v219, v239, v19, s[100:101]
	v_cndmask_b32_e64 v216, v24, v240, s[100:101]
	v_cndmask_b32_e64 v220, v240, v20, s[100:101]
	v_cndmask_b32_e64 v217, v25, v241, s[100:101]
	v_cndmask_b32_e64 v221, v241, v21, s[100:101]
	v_lshl_add_u64 v[226:227], v[50:51], 0, v[242:243]
	global_store_dwordx4 v[226:227], v[214:217], off offset:-3584
	global_store_dwordx4 v[226:227], v[218:221], off offset:512
	v_pk_mul_f32 v[28:29], v[58:59], v[18:19]
	v_pk_mul_f32 v[24:25], v[64:65], v[24:25]
	v_pk_mul_f32 v[22:23], v[62:63], v[22:23]
	s_waitcnt lgkmcnt(0)
	v_add_f32_e32 v18, v30, v31
	ds_bpermute_b32 v19, v195, v18
	v_pk_mul_f32 v[26:27], v[60:61], v[20:21]
	v_cvt_pk_bf16_f32 v20, v22, v23
	v_cvt_pk_bf16_f32 v21, v24, v25
	v_cvt_pk_bf16_f32 v22, v28, v29
	v_cvt_pk_bf16_f32 v23, v26, v27
	global_store_dwordx4 v[48:49], v[20:23], off offset:256
	s_and_saveexec_b64 s[34:35], s[38:39]
	s_cbranch_execz .LBB0_1253
	v_lshlrev_b64 v[20:21], 6, v[34:35]
	v_lshl_add_u64 v[20:21], s[62:63], 0, v[20:21]
	v_lshl_add_u64 v[20:21], s[24:25], 2, v[20:21]
	s_lshl_b32 s0, s56, 2
	v_lshl_add_u64 v[20:21], v[20:21], 0, s[0:1]
	s_waitcnt lgkmcnt(0)
	v_add_f32_e32 v18, v18, v19
	global_store_dword v[20:21], v18, off

; __device__ __forceinline__ unsigned pk2(float lo, float hi) { return pg8::cvt_pk_bf16(lo, hi); }
;     __device__ __forceinline__ void operator()(const f32x4 (&acc)[2][2][4][2], const pg8::Unit& u, int wr, int wc, int fr, int fq) const {
;     ...
;                 const int R = rowbase + u.pm * 256 + ai * 128 + wr * 64 + m * 16 + fr;
;                 const float* src = islat ? rin_l + (size_t)R * DM : rin_c + (size_t)(R - TL) * DM;
;                 float* dst = islat ? rout_l + (size_t)R * DM : rout_c + (size_t)(R - TL) * DM;
;                 float ss = 0.f;
; #pragma unroll
;                 for (int bj = 0; bj < 2; ++bj) { const int c = u.pn * 256 + bj * 128 + wc * 32 + 8 * fq;
;                     const f32x4 xa = *(const f32x4*)(src + c) + gv[bj][0] * acc[ai][bj][m][0];
;                     const f32x4 xb = *(const f32x4*)(src + c + 4) + gv[bj][1] * acc[ai][bj][m][1];
;                     *(f32x4*)(dst + c) = xa; *(f32x4*)(dst + c + 4) = xb;
;                     ss += (xa[0] * xa[0] + xa[1] * xa[1]) + (xa[2] * xa[2] + xa[3] * xa[3]) + (xb[0] * xb[0] + xb[1] * xb[1]) + (xb[2] * xb[2] + xb[3] * xb[3]);
;                     const f32x4 ya = xa * sv[bj][0], yb = xb * sv[bj][1];
;                     u32x4 w; w.x = pk2(ya[0], ya[1]); w.y = pk2(ya[2], ya[3]); w.z = pk2(yb[0], yb[1]); w.w = pk2(yb[2], yb[3]);
;                     *(u32x4*)(Hn + (size_t)R * DM + c) = w; }
;                 ss += __shfl_xor(ss, 16); ss += __shfl_xor(ss, 32);
;                 if (fq == 0) stat[(size_t)R * 16 + u.pn * 4 + wc] = ss;
.LBB0_1257:
	v_cndmask_b32_e64 v22, v22, v18, s[42:43]
	v_ashrrev_i32_e32 v23, 31, v22
	v_lshlrev_b64 v[22:23], 12, v[22:23]
	v_lshl_add_u64 v[22:23], s[68:69], 0, v[22:23]
	v_lshl_add_u64 v[30:31], v[22:23], 0, v[188:189]
	v_lshl_add_u64 v[226:227], v[30:31], 0, v[242:243]
	global_load_dwordx4 v[214:217], v[226:227], off offset:-4096 nt
	global_load_dwordx4 v[218:221], v[226:227], off nt
	v_lshlrev_b64 v[32:33], 11, v[18:19]
	v_lshl_add_u64 v[34:35], v[20:21], 0, v[188:189]
	v_lshl_add_u64 v[20:21], s[60:61], 0, v[32:33]
	v_lshl_add_u64 v[32:33], v[186:187], 1, v[20:21]
	s_waitcnt vmcnt(0)
	v_cndmask_b32_e64 v222, v218, v214, s[100:101]
	v_cndmask_b32_e64 v223, v219, v215, s[100:101]
	v_cndmask_b32_e64 v224, v220, v216, s[100:101]
	v_cndmask_b32_e64 v225, v221, v217, s[100:101]
	v_mov_b32_dpp v238, v222 quad_perm:[1,0,3,2] row_mask:0xf bank_mask:0xf
	v_mov_b32_dpp v239, v223 quad_perm:[1,0,3,2] row_mask:0xf bank_mask:0xf
	v_mov_b32_dpp v240, v224 quad_perm:[1,0,3,2] row_mask:0xf bank_mask:0xf
	v_mov_b32_dpp v241, v225 quad_perm:[1,0,3,2] row_mask:0xf bank_mask:0xf
	v_cndmask_b32_e64 v22, v214, v238, s[100:101]
	v_cndmask_b32_e64 v26, v238, v218, s[100:101]
	v_cndmask_b32_e64 v23, v215, v239, s[100:101]
	v_cndmask_b32_e64 v27, v239, v219, s[100:101]
	v_cndmask_b32_e64 v24, v216, v240, s[100:101]
	v_cndmask_b32_e64 v28, v240, v220, s[100:101]
	v_cndmask_b32_e64 v25, v217, v241, s[100:101]
	v_cndmask_b32_e64 v29, v241, v221, s[100:101]
	v_pk_fma_f32 v[16:17], v[16:17], v[96:97], v[24:25]
	v_pk_fma_f32 v[14:15], v[14:15], v[94:95], v[22:23]
	s_waitcnt vmcnt(0)
	v_pk_fma_f32 v[12:13], v[12:13], v[88:89], v[28:29]
	v_pk_fma_f32 v[10:11], v[10:11], v[86:87], v[26:27]
	v_pk_mul_f32 v[22:23], v[92:93], v[16:17]
	v_pk_mul_f32 v[20:21], v[90:91], v[14:15]
	v_pk_mul_f32 v[24:25], v[84:85], v[12:13]
	v_pk_mul_f32 v[26:27], v[82:83], v[10:11]
	v_cvt_pk_bf16_f32 v20, v20, v21
	v_cvt_pk_bf16_f32 v21, v22, v23
	v_cvt_pk_bf16_f32 v22, v26, v27
	v_cvt_pk_bf16_f32 v23, v24, v25
	v_cndmask_b32_e64 v222, v10, v14, s[100:101]
	v_cndmask_b32_e64 v223, v11, v15, s[100:101]
	v_cndmask_b32_e64 v224, v12, v16, s[100:101]
	v_cndmask_b32_e64 v225, v13, v17, s[100:101]
	v_mov_b32_dpp v238, v222 quad_perm:[1,0,3,2] row_mask:0xf bank_mask:0xf
	v_mov_b32_dpp v239, v223 quad_perm:[1,0,3,2] row_mask:0xf bank_mask:0xf
	v_mov_b32_dpp v240, v224 quad_perm:[1,0,3,2] row_mask:0xf bank_mask:0xf
	v_mov_b32_dpp v241, v225 quad_perm:[1,0,3,2] row_mask:0xf bank_mask:0xf
	v_cndmask_b32_e64 v214, v14, v238, s[100:101]
	v_cndmask_b32_e64 v218, v238, v10, s[100:101]
	v_cndmask_b32_e64 v215, v15, v239, s[100:101]
	v_cndmask_b32_e64 v219, v239, v11, s[100:101]
	v_cndmask_b32_e64 v216, v16, v240, s[100:101]
	v_cndmask_b32_e64 v220, v240, v12, s[100:101]
	v_cndmask_b32_e64 v217, v17, v241, s[100:101]
	v_cndmask_b32_e64 v221, v241, v13, s[100:101]
	v_lshl_add_u64 v[226:227], v[34:35], 0, v[242:243]
	global_store_dwordx4 v[226:227], v[214:217], off offset:-4096
	global_store_dwordx4 v[226:227], v[218:221], off
	global_store_dwordx4 v[32:33], v[20:23], off
	v_lshl_add_u64 v[226:227], v[30:31], 0, v[242:243]
	global_load_dwordx4 v[214:217], v[226:227], off offset:-3584 nt
	global_load_dwordx4 v[218:221], v[226:227], off offset:512 nt
	s_nop 0
	v_mul_f32_e32 v15, v15, v15
	v_mul_f32_e32 v17, v17, v17
	v_mul_f32_e32 v11, v11, v11
	v_fmac_f32_e32 v15, v14, v14
	v_fmac_f32_e32 v17, v16, v16
	v_mul_f32_e32 v13, v13, v13
	v_fmac_f32_e32 v11, v10, v10
	v_add_f32_e32 v10, v15, v17
	v_fmac_f32_e32 v13, v12, v12
	v_add_f32_e32 v10, v10, v11
	v_add_f32_e32 v10, v13, v10
	s_waitcnt vmcnt(0)
	v_cndmask_b32_e64 v222, v218, v214, s[100:101]
	v_cndmask_b32_e64 v223, v219, v215, s[100:101]
	v_cndmask_b32_e64 v224, v220, v216, s[100:101]
	v_cndmask_b32_e64 v225, v221, v217, s[100:101]
	v_mov_b32_dpp v238, v222 quad_perm:[1,0,3,2] row_mask:0xf bank_mask:0xf
	v_mov_b32_dpp v239, v223 quad_perm:[1,0,3,2] row_mask:0xf bank_mask:0xf
	v_mov_b32_dpp v240, v224 quad_perm:[1,0,3,2] row_mask:0xf bank_mask:0xf
	v_mov_b32_dpp v241, v225 quad_perm:[1,0,3,2] row_mask:0xf bank_mask:0xf
	v_cndmask_b32_e64 v20, v214, v238, s[100:101]
	v_cndmask_b32_e64 v24, v238, v218, s[100:101]
	v_cndmask_b32_e64 v21, v215, v239, s[100:101]
	v_cndmask_b32_e64 v25, v239, v219, s[100:101]
	v_cndmask_b32_e64 v22, v216, v240, s[100:101]
	v_cndmask_b32_e64 v26, v240, v220, s[100:101]
	v_cndmask_b32_e64 v23, v217, v241, s[100:101]
	v_cndmask_b32_e64 v27, v241, v221, s[100:101]
	v_pk_fma_f32 v[8:9], v[8:9], v[80:81], v[22:23]
	v_pk_fma_f32 v[6:7], v[6:7], v[78:79], v[20:21]
	s_waitcnt vmcnt(0)
	v_pk_fma_f32 v[2:3], v[2:3], v[74:75], v[24:25]
	v_mul_f32_e32 v11, v7, v7
	v_mul_f32_e32 v12, v9, v9
	v_pk_fma_f32 v[4:5], v[4:5], v[76:77], v[26:27]
	v_mul_f32_e32 v13, v3, v3
	v_fmac_f32_e32 v11, v6, v6
	v_fmac_f32_e32 v12, v8, v8
	v_mul_f32_e32 v14, v5, v5
	v_fmac_f32_e32 v13, v2, v2
	v_add_f32_e32 v11, v11, v12
	v_fmac_f32_e32 v14, v4, v4
	v_add_f32_e32 v11, v11, v13
	v_add_f32_e32 v11, v14, v11
	v_add_f32_e32 v14, v10, v11
	ds_bpermute_b32 v15, v200, v14
	v_cndmask_b32_e64 v222, v2, v6, s[100:101]
	v_cndmask_b32_e64 v223, v3, v7, s[100:101]
	v_cndmask_b32_e64 v224, v4, v8, s[100:101]
	v_cndmask_b32_e64 v225, v5, v9, s[100:101]
	v_mov_b32_dpp v238, v222 quad_perm:[1,0,3,2] row_mask:0xf bank_mask:0xf
	v_mov_b32_dpp v239, v223 quad_perm:[1,0,3,2] row_mask:0xf bank_mask:0xf
	v_mov_b32_dpp v240, v224 quad_perm:[1,0,3,2] row_mask:0xf bank_mask:0xf
	v_mov_b32_dpp v241, v225 quad_perm:[1,0,3,2] row_mask:0xf bank_mask:0xf
	v_cndmask_b32_e64 v214, v6, v238, s[100:101]
	v_cndmask_b32_e64 v218, v238, v2, s[100:101]
	v_cndmask_b32_e64 v215, v7, v239, s[100:101]
	v_cndmask_b32_e64 v219, v239, v3, s[100:101]
	v_cndmask_b32_e64 v216, v8, v240, s[100:101]
	v_cndmask_b32_e64 v220, v240, v4, s[100:101]
	v_cndmask_b32_e64 v217, v9, v241, s[100:101]
	v_cndmask_b32_e64 v221, v241, v5, s[100:101]
	v_lshl_add_u64 v[226:227], v[34:35], 0, v[242:243]
	global_store_dwordx4 v[226:227], v[214:217], off offset:-3584
	global_store_dwordx4 v[226:227], v[218:221], off offset:512
	v_pk_mul_f32 v[12:13], v[58:59], v[2:3]
	v_pk_mul_f32 v[8:9], v[64:65], v[8:9]
	v_pk_mul_f32 v[6:7], v[62:63], v[6:7]
	s_waitcnt lgkmcnt(0)
	v_add_f32_e32 v2, v14, v15
	ds_bpermute_b32 v3, v195, v2
	v_pk_mul_f32 v[10:11], v[60:61], v[4:5]
	v_cvt_pk_bf16_f32 v4, v6, v7
	v_cvt_pk_bf16_f32 v5, v8, v9
	v_cvt_pk_bf16_f32 v6, v12, v13
	v_cvt_pk_bf16_f32 v7, v10, v11
	global_store_dwordx4 v[32:33], v[4:7], off offset:256
	s_and_saveexec_b64 s[34:35], s[38:39]
	s_cbranch_execz .LBB0_1259
	v_lshlrev_b64 v[4:5], 6, v[18:19]
	v_lshl_add_u64 v[4:5], s[62:63], 0, v[4:5]
	v_lshl_add_u64 v[4:5], s[24:25], 2, v[4:5]
	s_lshl_b32 s0, s56, 2
	v_lshl_add_u64 v[4:5], v[4:5], 0, s[0:1]
	s_waitcnt lgkmcnt(0)
	v_add_f32_e32 v2, v2, v3
	global_store_dword v[4:5], v2, off
